# GEMM K-loops re-emitted: software-pipelined LDS fragment reads, LDS-DMA loads spread between MFMAs, one barrier per K-step
# speedup vs baseline: 1.0316x; 1.0316x over previous
.LBB0_74:
	s_lshr_b32 s0, s5, 1
	s_and_b32 s0, s0, 0x1ffff80
	v_or_b32_e32 v0, s0, v154
	s_and_b32 s0, s5, 0xc0
	s_mov_b32 s5, s15
	s_lshl_b64 s[4:5], s[4:5], 16
	v_lshlrev_b32_e32 v128, 7, v0
	v_or_b32_e32 v0, s0, v154
	s_add_u32 s6, s4, s74
	v_lshlrev_b32_e32 v139, 7, v0
	v_lshl_add_u64 v[0:1], s[66:67], 0, v[130:131]
	s_addc_u32 s7, s5, s75
	s_waitcnt vmcnt(0)
	v_lshl_add_u64 v[142:143], v[0:1], 0, s[6:7]
	s_add_u32 s4, s4, s76
	v_lshl_add_u64 v[0:1], s[66:67], 0, v[134:135]
	s_addc_u32 s5, s5, s77
	v_lshl_add_u64 v[146:147], v[0:1], 0, s[6:7]
	v_mov_b32_e32 v0, 0
	v_lshl_add_u64 v[144:145], v[132:133], 0, s[4:5]
	v_lshl_add_u64 v[148:149], v[136:137], 0, s[4:5]
	s_mov_b64 s[4:5], 0
	s_mov_b32 s12, 0
	v_mov_b32_e32 v1, v0
	v_mov_b32_e32 v2, v0
	v_mov_b32_e32 v3, v0
	v_mov_b32_e32 v4, v0
	v_mov_b32_e32 v5, v0
	v_mov_b32_e32 v6, v0
	v_mov_b32_e32 v7, v0
	v_mov_b32_e32 v8, v0
	v_mov_b32_e32 v9, v0
	v_mov_b32_e32 v10, v0
	v_mov_b32_e32 v11, v0
	v_mov_b32_e32 v12, v0
	v_mov_b32_e32 v13, v0
	v_mov_b32_e32 v14, v0
	v_mov_b32_e32 v15, v0
	v_mov_b32_e32 v16, v0
	v_mov_b32_e32 v17, v0
	v_mov_b32_e32 v18, v0
	v_mov_b32_e32 v19, v0
	v_mov_b32_e32 v20, v0
	v_mov_b32_e32 v21, v0
	v_mov_b32_e32 v22, v0
	v_mov_b32_e32 v23, v0
	v_mov_b32_e32 v24, v0
	v_mov_b32_e32 v25, v0
	v_mov_b32_e32 v26, v0
	v_mov_b32_e32 v27, v0
	v_mov_b32_e32 v28, v0
	v_mov_b32_e32 v29, v0
	v_mov_b32_e32 v30, v0
	v_mov_b32_e32 v31, v0
	v_mov_b32_e32 v32, v0
	v_mov_b32_e32 v33, v0
	v_mov_b32_e32 v34, v0
	v_mov_b32_e32 v35, v0
	v_mov_b32_e32 v36, v0
	v_mov_b32_e32 v37, v0
	v_mov_b32_e32 v38, v0
	v_mov_b32_e32 v39, v0
	v_mov_b32_e32 v40, v0
	v_mov_b32_e32 v41, v0
	v_mov_b32_e32 v42, v0
	v_mov_b32_e32 v43, v0
	v_mov_b32_e32 v44, v0
	v_mov_b32_e32 v45, v0
	v_mov_b32_e32 v46, v0
	v_mov_b32_e32 v47, v0
	v_mov_b32_e32 v48, v0
	v_mov_b32_e32 v49, v0
	v_mov_b32_e32 v50, v0
	v_mov_b32_e32 v51, v0
	v_mov_b32_e32 v52, v0
	v_mov_b32_e32 v53, v0
	v_mov_b32_e32 v54, v0
	v_mov_b32_e32 v55, v0
	v_mov_b32_e32 v56, v0
	v_mov_b32_e32 v57, v0
	v_mov_b32_e32 v58, v0
	v_mov_b32_e32 v59, v0
	v_mov_b32_e32 v60, v0
	v_mov_b32_e32 v61, v0
	v_mov_b32_e32 v62, v0
	v_mov_b32_e32 v63, v0
	v_mov_b32_e32 v64, v0
	v_mov_b32_e32 v65, v0
	v_mov_b32_e32 v66, v0
	v_mov_b32_e32 v67, v0
	v_mov_b32_e32 v68, v0
	v_mov_b32_e32 v69, v0
	v_mov_b32_e32 v70, v0
	v_mov_b32_e32 v71, v0
	v_mov_b32_e32 v72, v0
	v_mov_b32_e32 v73, v0
	v_mov_b32_e32 v74, v0
	v_mov_b32_e32 v75, v0
	v_mov_b32_e32 v76, v0
	v_mov_b32_e32 v77, v0
	v_mov_b32_e32 v78, v0
	v_mov_b32_e32 v79, v0
	v_mov_b32_e32 v80, v0
	v_mov_b32_e32 v81, v0
	v_mov_b32_e32 v82, v0
	v_mov_b32_e32 v83, v0
	v_mov_b32_e32 v84, v0
	v_mov_b32_e32 v85, v0
	v_mov_b32_e32 v86, v0
	v_mov_b32_e32 v87, v0
	v_mov_b32_e32 v88, v0
	v_mov_b32_e32 v89, v0
	v_mov_b32_e32 v90, v0
	v_mov_b32_e32 v91, v0
	v_mov_b32_e32 v92, v0
	v_mov_b32_e32 v93, v0
	v_mov_b32_e32 v94, v0
	v_mov_b32_e32 v95, v0
	v_mov_b32_e32 v96, v0
	v_mov_b32_e32 v97, v0
	v_mov_b32_e32 v98, v0
	v_mov_b32_e32 v99, v0
	v_mov_b32_e32 v100, v0
	v_mov_b32_e32 v101, v0
	v_mov_b32_e32 v102, v0
	v_mov_b32_e32 v103, v0
	v_mov_b32_e32 v104, v0
	v_mov_b32_e32 v105, v0
	v_mov_b32_e32 v106, v0
	v_mov_b32_e32 v107, v0
	v_mov_b32_e32 v108, v0
	v_mov_b32_e32 v109, v0
	v_mov_b32_e32 v110, v0
	v_mov_b32_e32 v111, v0
	v_mov_b32_e32 v112, v0
	v_mov_b32_e32 v113, v0
	v_mov_b32_e32 v114, v0
	v_mov_b32_e32 v115, v0
	v_mov_b32_e32 v116, v0
	v_mov_b32_e32 v117, v0
	v_mov_b32_e32 v118, v0
	v_mov_b32_e32 v119, v0
	v_mov_b32_e32 v120, v0
	v_mov_b32_e32 v121, v0
	v_mov_b32_e32 v122, v0
	v_mov_b32_e32 v123, v0
	v_mov_b32_e32 v124, v0
	v_mov_b32_e32 v125, v0
	v_mov_b32_e32 v126, v0
	v_mov_b32_e32 v127, v0
	s_waitcnt vmcnt(0) lgkmcnt(0)
	s_barrier
	v_bfe_u32 v250, v178, 3, 3
	v_and_b32_e32 v251, 7, v178
	v_lshrrev_b32_e32 v252, 1, v250
	v_xor_b32_e32 v251, v251, v252
	v_lshlrev_b32_e32 v251, 4, v251
	v_lshl_or_b32 v250, v250, 11, v251
	v_xor_b32_e32 v251, 64, v250
	v_add_u32_e32 v251, 0x4000, v251
	v_add_u32_e32 v252, 0x8000, v250
	v_add_u32_e32 v253, 0x8000, v251
	v_lshl_add_u64 v[242:243], v[142:143], 0, s[4:5]
	v_lshl_add_u64 v[242:243], v[242:243], 0, s[38:39]
	v_lshl_add_u64 v[244:245], v[144:145], 0, s[4:5]
	v_lshl_add_u64 v[244:245], v[244:245], 0, s[40:41]
	v_add_u32_e32 v254, v128, v155
	v_add_u32_e32 v255, v139, v155
	v_readfirstlane_b32 s98, v242
	v_readfirstlane_b32 s99, v243
	v_readfirstlane_b32 s100, v244
	v_readfirstlane_b32 s101, v245
	ds_read_b128 v[206:209], v254
	ds_read_b128 v[210:213], v254 offset:2048
	ds_read_b128 v[150:153], v255 offset:32768
	ds_read_b128 v[194:197], v255 offset:34816
	ds_read_b128 v[198:201], v255 offset:36864
	ds_read_b128 v[202:205], v255 offset:38912
	s_nop 4
	s_lshl_b32 m0, s4, 9
	s_and_b32 m0, m0, 0x10000
	s_xor_b32 m0, m0, 0x10000
	s_add_i32 m0, m0, s8
	s_nop 0
	global_load_lds_dwordx4 v250, s[98:99]
	s_add_i32 m0, m0, 0x8000
	s_nop 0
	global_load_lds_dwordx4 v250, s[100:101]
	s_add_i32 m0, m0, 0xffff8400
	s_nop 0
	global_load_lds_dwordx4 v251, s[98:99]
	s_add_i32 m0, m0, 0x8000
	s_nop 0
	global_load_lds_dwordx4 v251, s[100:101]
.LBB0_75:
	ds_read_b128 v[242:245], v254 offset:4096
	ds_read_b128 v[246:249], v254 offset:6144
	s_lshl_b32 m0, s4, 9
	s_and_b32 m0, m0, 0x10000
	s_xor_b32 m0, m0, 0x10000
	s_add_i32 m0, m0, s8
	s_add_i32 m0, m0, 0x800
	s_waitcnt lgkmcnt(5)
	v_mfma_f32_16x16x32_bf16 v[124:127], v[150:153], v[206:209], v[124:127]
	global_load_lds_dwordx4 v252, s[98:99]
	s_add_i32 m0, m0, 0x8000
	v_mfma_f32_16x16x32_bf16 v[108:111], v[150:153], v[210:213], v[108:111]
	s_waitcnt lgkmcnt(4)
	v_mfma_f32_16x16x32_bf16 v[120:123], v[194:197], v[206:209], v[120:123]
	global_load_lds_dwordx4 v252, s[100:101]
	s_add_i32 m0, m0, 0xffff8400
	v_mfma_f32_16x16x32_bf16 v[104:107], v[194:197], v[210:213], v[104:107]
	s_waitcnt lgkmcnt(3)
	v_mfma_f32_16x16x32_bf16 v[116:119], v[198:201], v[206:209], v[116:119]
	global_load_lds_dwordx4 v253, s[98:99]
	s_add_i32 m0, m0, 0x8000
	v_mfma_f32_16x16x32_bf16 v[100:103], v[198:201], v[210:213], v[100:103]
	s_waitcnt lgkmcnt(2)
	v_mfma_f32_16x16x32_bf16 v[112:115], v[202:205], v[206:209], v[112:115]
	global_load_lds_dwordx4 v253, s[100:101]
	v_mfma_f32_16x16x32_bf16 v[96:99], v[202:205], v[210:213], v[96:99]
	s_add_u32 s98, s98, 0x80
	s_addc_u32 s99, s99, 0
	s_add_u32 s100, s100, 0x80
	s_addc_u32 s101, s101, 0
	ds_read_b128 v[206:209], v254 offset:8192
	ds_read_b128 v[210:213], v254 offset:10240
	s_waitcnt lgkmcnt(2)
	v_mfma_f32_16x16x32_bf16 v[92:95], v[150:153], v[242:245], v[92:95]
	s_add_i32 s7, s12, 0x10000
	v_mfma_f32_16x16x32_bf16 v[76:79], v[150:153], v[246:249], v[76:79]
	s_and_b32 s0, s7, 0x10000
	v_mfma_f32_16x16x32_bf16 v[88:91], v[194:197], v[242:245], v[88:91]
	s_add_i32 s6, s0, 0
	v_mfma_f32_16x16x32_bf16 v[72:75], v[194:197], v[246:249], v[72:75]
	s_add_i32 s0, s6, s8
	v_mfma_f32_16x16x32_bf16 v[84:87], v[198:201], v[242:245], v[84:87]
	s_add_i32 s0, s6, s11
	v_mfma_f32_16x16x32_bf16 v[68:71], v[198:201], v[246:249], v[68:71]
	s_add_i32 s0, s6, s10
	v_mfma_f32_16x16x32_bf16 v[80:83], v[202:205], v[242:245], v[80:83]
	s_add_i32 s0, s6, s9
	v_mfma_f32_16x16x32_bf16 v[64:67], v[202:205], v[246:249], v[64:67]
	s_and_b32 s0, s12, 0x10000
	s_add_i32 s0, s0, 0
	s_add_u32 s4, s4, 0x80
	s_addc_u32 s5, s5, 0
	s_cmpk_eq_i32 s4, 0x780
	s_mov_b32 s12, s7
	ds_read_b128 v[242:245], v254 offset:12288
	ds_read_b128 v[246:249], v254 offset:14336
	s_waitcnt lgkmcnt(2)
	v_mfma_f32_16x16x32_bf16 v[60:63], v[150:153], v[206:209], v[60:63]
	v_mfma_f32_16x16x32_bf16 v[44:47], v[150:153], v[210:213], v[44:47]
	v_mfma_f32_16x16x32_bf16 v[56:59], v[194:197], v[206:209], v[56:59]
	v_mfma_f32_16x16x32_bf16 v[40:43], v[194:197], v[210:213], v[40:43]
	v_mfma_f32_16x16x32_bf16 v[52:55], v[198:201], v[206:209], v[52:55]
	v_mfma_f32_16x16x32_bf16 v[36:39], v[198:201], v[210:213], v[36:39]
	v_mfma_f32_16x16x32_bf16 v[48:51], v[202:205], v[206:209], v[48:51]
	v_mfma_f32_16x16x32_bf16 v[32:35], v[202:205], v[210:213], v[32:35]
	v_xor_b32_e32 v254, 64, v254
	v_xor_b32_e32 v255, 64, v255
	ds_read_b128 v[206:209], v254
	ds_read_b128 v[210:213], v254 offset:2048
	s_waitcnt lgkmcnt(2)
	v_mfma_f32_16x16x32_bf16 v[28:31], v[150:153], v[242:245], v[28:31]
	v_mfma_f32_16x16x32_bf16 v[12:15], v[150:153], v[246:249], v[12:15]
	ds_read_b128 v[150:153], v255 offset:32768
	v_mfma_f32_16x16x32_bf16 v[24:27], v[194:197], v[242:245], v[24:27]
	v_mfma_f32_16x16x32_bf16 v[8:11], v[194:197], v[246:249], v[8:11]
	ds_read_b128 v[194:197], v255 offset:34816
	v_mfma_f32_16x16x32_bf16 v[20:23], v[198:201], v[242:245], v[20:23]
	v_mfma_f32_16x16x32_bf16 v[4:7], v[198:201], v[246:249], v[4:7]
	ds_read_b128 v[198:201], v255 offset:36864
	v_mfma_f32_16x16x32_bf16 v[16:19], v[202:205], v[242:245], v[16:19]
	v_mfma_f32_16x16x32_bf16 v[0:3], v[202:205], v[246:249], v[0:3]
	ds_read_b128 v[202:205], v255 offset:38912
	ds_read_b128 v[242:245], v254 offset:4096
	ds_read_b128 v[246:249], v254 offset:6144
	s_waitcnt lgkmcnt(5)
	v_mfma_f32_16x16x32_bf16 v[124:127], v[150:153], v[206:209], v[124:127]
	v_mfma_f32_16x16x32_bf16 v[108:111], v[150:153], v[210:213], v[108:111]
	s_waitcnt lgkmcnt(4)
	v_mfma_f32_16x16x32_bf16 v[120:123], v[194:197], v[206:209], v[120:123]
	v_mfma_f32_16x16x32_bf16 v[104:107], v[194:197], v[210:213], v[104:107]
	s_waitcnt lgkmcnt(3)
	v_mfma_f32_16x16x32_bf16 v[116:119], v[198:201], v[206:209], v[116:119]
	v_mfma_f32_16x16x32_bf16 v[100:103], v[198:201], v[210:213], v[100:103]
	s_waitcnt lgkmcnt(2)
	v_mfma_f32_16x16x32_bf16 v[112:115], v[202:205], v[206:209], v[112:115]
	v_mfma_f32_16x16x32_bf16 v[96:99], v[202:205], v[210:213], v[96:99]
	ds_read_b128 v[206:209], v254 offset:8192
	ds_read_b128 v[210:213], v254 offset:10240
	s_waitcnt lgkmcnt(2)
	v_mfma_f32_16x16x32_bf16 v[92:95], v[150:153], v[242:245], v[92:95]
	v_mfma_f32_16x16x32_bf16 v[76:79], v[150:153], v[246:249], v[76:79]
	v_mfma_f32_16x16x32_bf16 v[88:91], v[194:197], v[242:245], v[88:91]
	v_mfma_f32_16x16x32_bf16 v[72:75], v[194:197], v[246:249], v[72:75]
	v_mfma_f32_16x16x32_bf16 v[84:87], v[198:201], v[242:245], v[84:87]
	v_mfma_f32_16x16x32_bf16 v[68:71], v[198:201], v[246:249], v[68:71]
	v_mfma_f32_16x16x32_bf16 v[80:83], v[202:205], v[242:245], v[80:83]
	v_mfma_f32_16x16x32_bf16 v[64:67], v[202:205], v[246:249], v[64:67]
	ds_read_b128 v[242:245], v254 offset:12288
	ds_read_b128 v[246:249], v254 offset:14336
	s_waitcnt lgkmcnt(2)
	v_mfma_f32_16x16x32_bf16 v[60:63], v[150:153], v[206:209], v[60:63]
	v_mfma_f32_16x16x32_bf16 v[44:47], v[150:153], v[210:213], v[44:47]
	v_mfma_f32_16x16x32_bf16 v[56:59], v[194:197], v[206:209], v[56:59]
	v_mfma_f32_16x16x32_bf16 v[40:43], v[194:197], v[210:213], v[40:43]
	v_mfma_f32_16x16x32_bf16 v[52:55], v[198:201], v[206:209], v[52:55]
	v_mfma_f32_16x16x32_bf16 v[36:39], v[198:201], v[210:213], v[36:39]
	v_mfma_f32_16x16x32_bf16 v[48:51], v[202:205], v[206:209], v[48:51]
	v_mfma_f32_16x16x32_bf16 v[32:35], v[202:205], v[210:213], v[32:35]
	s_waitcnt vmcnt(0) lgkmcnt(0)
	s_barrier
	s_cmpk_eq_i32 s4, 0x780
	s_cbranch_scc1 .Lgx_75
	v_xor_b32_e32 v254, 0x10040, v254
	v_xor_b32_e32 v255, 0x10040, v255
	ds_read_b128 v[206:209], v254
	ds_read_b128 v[210:213], v254 offset:2048
	s_lshl_b32 m0, s4, 9
	s_and_b32 m0, m0, 0x10000
	s_xor_b32 m0, m0, 0x10000
	s_add_i32 m0, m0, s8
	v_mfma_f32_16x16x32_bf16 v[28:31], v[150:153], v[242:245], v[28:31]
	global_load_lds_dwordx4 v250, s[98:99]
	s_add_i32 m0, m0, 0x8000
	v_mfma_f32_16x16x32_bf16 v[12:15], v[150:153], v[246:249], v[12:15]
	ds_read_b128 v[150:153], v255 offset:32768
	v_mfma_f32_16x16x32_bf16 v[24:27], v[194:197], v[242:245], v[24:27]
	global_load_lds_dwordx4 v250, s[100:101]
	s_add_i32 m0, m0, 0xffff8400
	v_mfma_f32_16x16x32_bf16 v[8:11], v[194:197], v[246:249], v[8:11]
	ds_read_b128 v[194:197], v255 offset:34816
	v_mfma_f32_16x16x32_bf16 v[20:23], v[198:201], v[242:245], v[20:23]
	global_load_lds_dwordx4 v251, s[98:99]
	s_add_i32 m0, m0, 0x8000
	v_mfma_f32_16x16x32_bf16 v[4:7], v[198:201], v[246:249], v[4:7]
	ds_read_b128 v[198:201], v255 offset:36864
	v_mfma_f32_16x16x32_bf16 v[16:19], v[202:205], v[242:245], v[16:19]
	global_load_lds_dwordx4 v251, s[100:101]
	v_mfma_f32_16x16x32_bf16 v[0:3], v[202:205], v[246:249], v[0:3]
	ds_read_b128 v[202:205], v255 offset:38912
	s_branch .LBB0_75
.Lgx_75:
	v_mfma_f32_16x16x32_bf16 v[28:31], v[150:153], v[242:245], v[28:31]
	v_mfma_f32_16x16x32_bf16 v[12:15], v[150:153], v[246:249], v[12:15]
	v_mfma_f32_16x16x32_bf16 v[24:27], v[194:197], v[242:245], v[24:27]
	v_mfma_f32_16x16x32_bf16 v[8:11], v[194:197], v[246:249], v[8:11]
	v_mfma_f32_16x16x32_bf16 v[20:23], v[198:201], v[242:245], v[20:23]
	v_mfma_f32_16x16x32_bf16 v[4:7], v[198:201], v[246:249], v[4:7]
	v_mfma_f32_16x16x32_bf16 v[16:19], v[202:205], v[242:245], v[16:19]
	v_mfma_f32_16x16x32_bf16 v[0:3], v[202:205], v[246:249], v[0:3]
	v_add_u32_e32 v139, s6, v139
	v_add_u32_e32 v141, v139, v155
	ds_read_b128 v[142:145], v141 offset:32768
	ds_read_b128 v[150:153], v141 offset:34816
	ds_read_b128 v[194:197], v141 offset:36864
	ds_read_b128 v[198:201], v141 offset:38912
	v_add_u32_e32 v128, s6, v128
	v_add_u32_e32 v193, v128, v155
	ds_read_b128 v[146:149], v193
	v_add_u32_e32 v139, v139, v156
	v_add_u32_e32 v128, v128, v156
	s_waitcnt lgkmcnt(0)
	v_mfma_f32_16x16x32_bf16 v[124:127], v[142:145], v[146:149], v[124:127]
	s_and_b64 vcc, exec, s[60:61]
	v_mfma_f32_16x16x32_bf16 v[120:123], v[150:153], v[146:149], v[120:123]
	v_mfma_f32_16x16x32_bf16 v[116:119], v[194:197], v[146:149], v[116:119]
	v_mfma_f32_16x16x32_bf16 v[112:115], v[198:201], v[146:149], v[112:115]
	ds_read_b128 v[146:149], v193 offset:2048
	s_waitcnt lgkmcnt(0)
	v_mfma_f32_16x16x32_bf16 v[108:111], v[142:145], v[146:149], v[108:111]
	v_mfma_f32_16x16x32_bf16 v[104:107], v[150:153], v[146:149], v[104:107]
	v_mfma_f32_16x16x32_bf16 v[100:103], v[194:197], v[146:149], v[100:103]
	v_mfma_f32_16x16x32_bf16 v[96:99], v[198:201], v[146:149], v[96:99]
	ds_read_b128 v[146:149], v193 offset:4096
	s_waitcnt lgkmcnt(0)
	v_mfma_f32_16x16x32_bf16 v[92:95], v[142:145], v[146:149], v[92:95]
	v_mfma_f32_16x16x32_bf16 v[88:91], v[150:153], v[146:149], v[88:91]
	v_mfma_f32_16x16x32_bf16 v[84:87], v[194:197], v[146:149], v[84:87]
	v_mfma_f32_16x16x32_bf16 v[80:83], v[198:201], v[146:149], v[80:83]
	ds_read_b128 v[146:149], v193 offset:6144
	s_waitcnt lgkmcnt(0)
	v_mfma_f32_16x16x32_bf16 v[76:79], v[142:145], v[146:149], v[76:79]
	v_mfma_f32_16x16x32_bf16 v[72:75], v[150:153], v[146:149], v[72:75]
	v_mfma_f32_16x16x32_bf16 v[68:71], v[194:197], v[146:149], v[68:71]
	v_mfma_f32_16x16x32_bf16 v[64:67], v[198:201], v[146:149], v[64:67]
	ds_read_b128 v[146:149], v193 offset:8192
	s_waitcnt lgkmcnt(0)
	v_mfma_f32_16x16x32_bf16 v[60:63], v[142:145], v[146:149], v[60:63]
	v_mfma_f32_16x16x32_bf16 v[56:59], v[150:153], v[146:149], v[56:59]
	v_mfma_f32_16x16x32_bf16 v[52:55], v[194:197], v[146:149], v[52:55]
	v_mfma_f32_16x16x32_bf16 v[48:51], v[198:201], v[146:149], v[48:51]
	ds_read_b128 v[146:149], v193 offset:10240
	s_waitcnt lgkmcnt(0)
	v_mfma_f32_16x16x32_bf16 v[44:47], v[142:145], v[146:149], v[44:47]
	v_mfma_f32_16x16x32_bf16 v[40:43], v[150:153], v[146:149], v[40:43]
	v_mfma_f32_16x16x32_bf16 v[36:39], v[194:197], v[146:149], v[36:39]
	v_mfma_f32_16x16x32_bf16 v[32:35], v[198:201], v[146:149], v[32:35]
	ds_read_b128 v[146:149], v193 offset:12288
	s_waitcnt lgkmcnt(0)
	v_mfma_f32_16x16x32_bf16 v[28:31], v[142:145], v[146:149], v[28:31]
	v_mfma_f32_16x16x32_bf16 v[24:27], v[150:153], v[146:149], v[24:27]
	v_mfma_f32_16x16x32_bf16 v[20:23], v[194:197], v[146:149], v[20:23]
	v_mfma_f32_16x16x32_bf16 v[16:19], v[198:201], v[146:149], v[16:19]
	ds_read_b128 v[146:149], v193 offset:14336
	s_waitcnt lgkmcnt(0)
	v_mfma_f32_16x16x32_bf16 v[12:15], v[142:145], v[146:149], v[12:15]
	ds_read_b128 v[142:145], v139 offset:32768
	v_mfma_f32_16x16x32_bf16 v[8:11], v[150:153], v[146:149], v[8:11]
	ds_read_b128 v[150:153], v139 offset:34816
	v_mfma_f32_16x16x32_bf16 v[4:7], v[194:197], v[146:149], v[4:7]
	ds_read_b128 v[194:197], v139 offset:36864
	v_mfma_f32_16x16x32_bf16 v[0:3], v[198:201], v[146:149], v[0:3]
	ds_read_b128 v[198:201], v139 offset:38912
	ds_read_b128 v[146:149], v128
	s_waitcnt lgkmcnt(0)
	v_mfma_f32_16x16x32_bf16 v[124:127], v[142:145], v[146:149], v[124:127]
	v_mfma_f32_16x16x32_bf16 v[120:123], v[150:153], v[146:149], v[120:123]
	v_mfma_f32_16x16x32_bf16 v[116:119], v[194:197], v[146:149], v[116:119]
	v_mfma_f32_16x16x32_bf16 v[112:115], v[198:201], v[146:149], v[112:115]
	ds_read_b128 v[146:149], v128 offset:2048
	s_waitcnt lgkmcnt(0)
	v_mfma_f32_16x16x32_bf16 v[108:111], v[142:145], v[146:149], v[108:111]
	v_mfma_f32_16x16x32_bf16 v[104:107], v[150:153], v[146:149], v[104:107]
	v_mfma_f32_16x16x32_bf16 v[100:103], v[194:197], v[146:149], v[100:103]
	v_mfma_f32_16x16x32_bf16 v[96:99], v[198:201], v[146:149], v[96:99]
	ds_read_b128 v[146:149], v128 offset:4096
	s_waitcnt lgkmcnt(0)
	v_mfma_f32_16x16x32_bf16 v[92:95], v[142:145], v[146:149], v[92:95]
	v_mfma_f32_16x16x32_bf16 v[88:91], v[150:153], v[146:149], v[88:91]
	v_mfma_f32_16x16x32_bf16 v[84:87], v[194:197], v[146:149], v[84:87]
	v_mfma_f32_16x16x32_bf16 v[80:83], v[198:201], v[146:149], v[80:83]
	ds_read_b128 v[146:149], v128 offset:6144
	s_waitcnt lgkmcnt(0)
	v_mfma_f32_16x16x32_bf16 v[76:79], v[142:145], v[146:149], v[76:79]
	v_mfma_f32_16x16x32_bf16 v[72:75], v[150:153], v[146:149], v[72:75]
	v_mfma_f32_16x16x32_bf16 v[68:71], v[194:197], v[146:149], v[68:71]
	v_mfma_f32_16x16x32_bf16 v[64:67], v[198:201], v[146:149], v[64:67]
	ds_read_b128 v[146:149], v128 offset:8192
	s_waitcnt lgkmcnt(0)
	v_mfma_f32_16x16x32_bf16 v[60:63], v[142:145], v[146:149], v[60:63]
	v_mfma_f32_16x16x32_bf16 v[56:59], v[150:153], v[146:149], v[56:59]
	v_mfma_f32_16x16x32_bf16 v[52:55], v[194:197], v[146:149], v[52:55]
	v_mfma_f32_16x16x32_bf16 v[48:51], v[198:201], v[146:149], v[48:51]
	ds_read_b128 v[146:149], v128 offset:10240
	s_waitcnt lgkmcnt(0)
	v_mfma_f32_16x16x32_bf16 v[44:47], v[142:145], v[146:149], v[44:47]
	v_mfma_f32_16x16x32_bf16 v[40:43], v[150:153], v[146:149], v[40:43]
	v_mfma_f32_16x16x32_bf16 v[36:39], v[194:197], v[146:149], v[36:39]
	v_mfma_f32_16x16x32_bf16 v[32:35], v[198:201], v[146:149], v[32:35]
	ds_read_b128 v[146:149], v128 offset:12288
	s_waitcnt lgkmcnt(0)
	v_mfma_f32_16x16x32_bf16 v[28:31], v[142:145], v[146:149], v[28:31]
	v_mfma_f32_16x16x32_bf16 v[24:27], v[150:153], v[146:149], v[24:27]
	v_mfma_f32_16x16x32_bf16 v[20:23], v[194:197], v[146:149], v[20:23]
	v_mfma_f32_16x16x32_bf16 v[16:19], v[198:201], v[146:149], v[16:19]
	ds_read_b128 v[146:149], v128 offset:14336
	s_waitcnt vmcnt(0)
	s_waitcnt lgkmcnt(0)
	v_mfma_f32_16x16x32_bf16 v[12:15], v[142:145], v[146:149], v[12:15]
	s_barrier
	v_mfma_f32_16x16x32_bf16 v[8:11], v[150:153], v[146:149], v[8:11]
	v_mfma_f32_16x16x32_bf16 v[4:7], v[194:197], v[146:149], v[4:7]
	v_mfma_f32_16x16x32_bf16 v[0:3], v[198:201], v[146:149], v[0:3]
	s_cbranch_vccz .LBB0_78
	s_lshl_b64 s[2:3], s[2:3], 1
	s_add_u32 s4, s62, s2
	s_addc_u32 s5, s63, s3
	s_add_u32 s2, s64, s2
	s_addc_u32 s3, s65, s3
	s_add_i32 s0, s8, 0
	v_mov_b32_e32 v139, v129
	s_mov_b32 m0, s0
	v_mov_b32_e32 v141, v129
	v_lshl_add_u64 v[142:143], s[4:5], 0, v[138:139]
	global_load_lds_dwordx4 v138, s[4:5]
	s_add_i32 m0, s0, 0x8000
	v_lshl_add_u64 v[146:147], s[4:5], 0, v[140:141]
	s_mov_b64 s[4:5], 0x4000
	s_add_i32 s0, s11, 0
	global_load_lds_dwordx4 v138, s[2:3]
	v_lshl_add_u64 v[148:149], v[146:147], 0, s[4:5]
	s_mov_b32 m0, s0
	v_lshl_add_u64 v[144:145], s[2:3], 0, v[138:139]
	global_load_lds_dwordx4 v[148:149], off
	v_lshl_add_u64 v[148:149], s[2:3], 0, v[140:141]
	v_lshl_add_u64 v[150:151], v[148:149], 0, s[4:5]
	s_add_i32 m0, s0, 0x8000
	s_mov_b64 s[2:3], 0x8000
	s_add_i32 s0, s10, 0
	global_load_lds_dwordx4 v[150:151], off
	v_lshl_add_u64 v[142:143], v[142:143], 0, s[2:3]
	s_mov_b32 m0, s0
	s_nop 0
	global_load_lds_dwordx4 v[142:143], off
	v_lshl_add_u64 v[142:143], v[144:145], 0, s[2:3]
	s_add_i32 m0, s0, 0x8000
	s_mov_b64 s[2:3], 0xc000
	s_add_i32 s0, s9, 0
	global_load_lds_dwordx4 v[142:143], off
	v_lshl_add_u64 v[142:143], v[146:147], 0, s[2:3]
	s_mov_b32 m0, s0
	s_nop 0
	global_load_lds_dwordx4 v[142:143], off
	v_lshl_add_u64 v[142:143], v[148:149], 0, s[2:3]
	s_add_i32 m0, s0, 0x8000
	s_nop 0
	global_load_lds_dwordx4 v[142:143], off

.LBB0_531:
	s_lshr_b32 s0, s5, 1
	s_and_b32 s0, s0, 0x1ffff80
	v_or_b32_e32 v0, s0, v154
	s_and_b32 s0, s5, 0xc0
	s_mov_b32 s5, s15
	s_lshl_b64 s[4:5], s[4:5], 16
	v_lshlrev_b32_e32 v139, 7, v0
	v_or_b32_e32 v0, s0, v154
	s_add_u32 s12, s4, s74
	v_lshlrev_b32_e32 v128, 7, v0
	v_lshl_add_u64 v[0:1], s[66:67], 0, v[130:131]
	s_addc_u32 s13, s5, s75
	s_waitcnt vmcnt(0)
	v_lshl_add_u64 v[142:143], v[0:1], 0, s[12:13]
	s_add_u32 s6, s4, s76
	v_lshl_add_u64 v[0:1], s[66:67], 0, v[134:135]
	s_addc_u32 s7, s5, s77
	v_lshl_add_u64 v[144:145], v[0:1], 0, s[12:13]
	v_mov_b32_e32 v0, 0
	s_mov_b32 s12, 0
	s_mov_b64 s[4:5], 0
	v_mov_b32_e32 v1, v0
	v_mov_b32_e32 v2, v0
	v_mov_b32_e32 v3, v0
	v_mov_b32_e32 v4, v0
	v_mov_b32_e32 v5, v0
	v_mov_b32_e32 v6, v0
	v_mov_b32_e32 v7, v0
	v_mov_b32_e32 v8, v0
	v_mov_b32_e32 v9, v0
	v_mov_b32_e32 v10, v0
	v_mov_b32_e32 v11, v0
	v_mov_b32_e32 v12, v0
	v_mov_b32_e32 v13, v0
	v_mov_b32_e32 v14, v0
	v_mov_b32_e32 v15, v0
	v_mov_b32_e32 v16, v0
	v_mov_b32_e32 v17, v0
	v_mov_b32_e32 v18, v0
	v_mov_b32_e32 v19, v0
	v_mov_b32_e32 v20, v0
	v_mov_b32_e32 v21, v0
	v_mov_b32_e32 v22, v0
	v_mov_b32_e32 v23, v0
	v_mov_b32_e32 v24, v0
	v_mov_b32_e32 v25, v0
	v_mov_b32_e32 v26, v0
	v_mov_b32_e32 v27, v0
	v_mov_b32_e32 v28, v0
	v_mov_b32_e32 v29, v0
	v_mov_b32_e32 v30, v0
	v_mov_b32_e32 v31, v0
	v_mov_b32_e32 v32, v0
	v_mov_b32_e32 v33, v0
	v_mov_b32_e32 v34, v0
	v_mov_b32_e32 v35, v0
	v_mov_b32_e32 v36, v0
	v_mov_b32_e32 v37, v0
	v_mov_b32_e32 v38, v0
	v_mov_b32_e32 v39, v0
	v_mov_b32_e32 v40, v0
	v_mov_b32_e32 v41, v0
	v_mov_b32_e32 v42, v0
	v_mov_b32_e32 v43, v0
	v_mov_b32_e32 v44, v0
	v_mov_b32_e32 v45, v0
	v_mov_b32_e32 v46, v0
	v_mov_b32_e32 v47, v0
	v_mov_b32_e32 v48, v0
	v_mov_b32_e32 v49, v0
	v_mov_b32_e32 v50, v0
	v_mov_b32_e32 v51, v0
	v_mov_b32_e32 v52, v0
	v_mov_b32_e32 v53, v0
	v_mov_b32_e32 v54, v0
	v_mov_b32_e32 v55, v0
	v_mov_b32_e32 v56, v0
	v_mov_b32_e32 v57, v0
	v_mov_b32_e32 v58, v0
	v_mov_b32_e32 v59, v0
	v_mov_b32_e32 v60, v0
	v_mov_b32_e32 v61, v0
	v_mov_b32_e32 v62, v0
	v_mov_b32_e32 v63, v0
	v_mov_b32_e32 v64, v0
	v_mov_b32_e32 v65, v0
	v_mov_b32_e32 v66, v0
	v_mov_b32_e32 v67, v0
	v_mov_b32_e32 v68, v0
	v_mov_b32_e32 v69, v0
	v_mov_b32_e32 v70, v0
	v_mov_b32_e32 v71, v0
	v_mov_b32_e32 v72, v0
	v_mov_b32_e32 v73, v0
	v_mov_b32_e32 v74, v0
	v_mov_b32_e32 v75, v0
	v_mov_b32_e32 v76, v0
	v_mov_b32_e32 v77, v0
	v_mov_b32_e32 v78, v0
	v_mov_b32_e32 v79, v0
	v_mov_b32_e32 v80, v0
	v_mov_b32_e32 v81, v0
	v_mov_b32_e32 v82, v0
	v_mov_b32_e32 v83, v0
	v_mov_b32_e32 v84, v0
	v_mov_b32_e32 v85, v0
	v_mov_b32_e32 v86, v0
	v_mov_b32_e32 v87, v0
	v_mov_b32_e32 v88, v0
	v_mov_b32_e32 v89, v0
	v_mov_b32_e32 v90, v0
	v_mov_b32_e32 v91, v0
	v_mov_b32_e32 v92, v0
	v_mov_b32_e32 v93, v0
	v_mov_b32_e32 v94, v0
	v_mov_b32_e32 v95, v0
	v_mov_b32_e32 v96, v0
	v_mov_b32_e32 v97, v0
	v_mov_b32_e32 v98, v0
	v_mov_b32_e32 v99, v0
	v_mov_b32_e32 v100, v0
	v_mov_b32_e32 v101, v0
	v_mov_b32_e32 v102, v0
	v_mov_b32_e32 v103, v0
	v_mov_b32_e32 v104, v0
	v_mov_b32_e32 v105, v0
	v_mov_b32_e32 v106, v0
	v_mov_b32_e32 v107, v0
	v_mov_b32_e32 v108, v0
	v_mov_b32_e32 v109, v0
	v_mov_b32_e32 v110, v0
	v_mov_b32_e32 v111, v0
	v_mov_b32_e32 v112, v0
	v_mov_b32_e32 v113, v0
	v_mov_b32_e32 v114, v0
	v_mov_b32_e32 v115, v0
	v_mov_b32_e32 v116, v0
	v_mov_b32_e32 v117, v0
	v_mov_b32_e32 v118, v0
	v_mov_b32_e32 v119, v0
	v_mov_b32_e32 v120, v0
	v_mov_b32_e32 v121, v0
	v_mov_b32_e32 v122, v0
	v_mov_b32_e32 v123, v0
	v_mov_b32_e32 v124, v0
	v_mov_b32_e32 v125, v0
	v_mov_b32_e32 v126, v0
	v_mov_b32_e32 v127, v0
	v_lshl_add_u64 v[146:147], v[132:133], 0, s[6:7]
	v_lshl_add_u64 v[148:149], v[136:137], 0, s[6:7]
	s_waitcnt vmcnt(0) lgkmcnt(0)
	s_barrier
	v_bfe_u32 v250, v178, 3, 3
	v_and_b32_e32 v251, 7, v178
	v_lshrrev_b32_e32 v252, 1, v250
	v_xor_b32_e32 v251, v251, v252
	v_lshlrev_b32_e32 v251, 4, v251
	v_lshl_or_b32 v250, v250, 11, v251
	v_xor_b32_e32 v251, 64, v250
	v_add_u32_e32 v251, 0x4000, v251
	v_add_u32_e32 v252, 0x8000, v250
	v_add_u32_e32 v253, 0x8000, v251
	v_lshl_add_u64 v[242:243], v[142:143], 0, s[4:5]
	v_lshl_add_u64 v[242:243], v[242:243], 0, s[38:39]
	v_lshl_add_u64 v[244:245], v[146:147], 0, s[4:5]
	v_lshl_add_u64 v[244:245], v[244:245], 0, s[40:41]
	v_add_u32_e32 v254, v139, v155
	v_add_u32_e32 v255, v128, v155
	v_readfirstlane_b32 s98, v242
	v_readfirstlane_b32 s99, v243
	v_readfirstlane_b32 s100, v244
	v_readfirstlane_b32 s101, v245
	ds_read_b128 v[206:209], v254
	ds_read_b128 v[210:213], v254 offset:2048
	ds_read_b128 v[150:153], v255 offset:32768
	ds_read_b128 v[194:197], v255 offset:34816
	ds_read_b128 v[198:201], v255 offset:36864
	ds_read_b128 v[202:205], v255 offset:38912
	s_nop 4
	s_lshl_b32 m0, s4, 9
	s_and_b32 m0, m0, 0x10000
	s_xor_b32 m0, m0, 0x10000
	s_add_i32 m0, m0, s8
	s_nop 0
	global_load_lds_dwordx4 v250, s[98:99]
	s_add_i32 m0, m0, 0x8000
	s_nop 0
	global_load_lds_dwordx4 v250, s[100:101]
	s_add_i32 m0, m0, 0xffff8400
	s_nop 0
	global_load_lds_dwordx4 v251, s[98:99]
	s_add_i32 m0, m0, 0x8000
	s_nop 0
	global_load_lds_dwordx4 v251, s[100:101]
.LBB0_532:
	ds_read_b128 v[242:245], v254 offset:4096
	ds_read_b128 v[246:249], v254 offset:6144
	s_lshl_b32 m0, s4, 9
	s_and_b32 m0, m0, 0x10000
	s_xor_b32 m0, m0, 0x10000
	s_add_i32 m0, m0, s8
	s_add_i32 m0, m0, 0x800
	s_waitcnt lgkmcnt(5)
	v_mfma_f32_16x16x32_bf16 v[124:127], v[206:209], v[150:153], v[124:127]
	global_load_lds_dwordx4 v252, s[98:99]
	s_add_i32 m0, m0, 0x8000
	v_mfma_f32_16x16x32_bf16 v[108:111], v[210:213], v[150:153], v[108:111]
	s_waitcnt lgkmcnt(4)
	v_mfma_f32_16x16x32_bf16 v[120:123], v[206:209], v[194:197], v[120:123]
	global_load_lds_dwordx4 v252, s[100:101]
	s_add_i32 m0, m0, 0xffff8400
	v_mfma_f32_16x16x32_bf16 v[104:107], v[210:213], v[194:197], v[104:107]
	s_waitcnt lgkmcnt(3)
	v_mfma_f32_16x16x32_bf16 v[116:119], v[206:209], v[198:201], v[116:119]
	global_load_lds_dwordx4 v253, s[98:99]
	s_add_i32 m0, m0, 0x8000
	v_mfma_f32_16x16x32_bf16 v[100:103], v[210:213], v[198:201], v[100:103]
	s_waitcnt lgkmcnt(2)
	v_mfma_f32_16x16x32_bf16 v[112:115], v[206:209], v[202:205], v[112:115]
	global_load_lds_dwordx4 v253, s[100:101]
	v_mfma_f32_16x16x32_bf16 v[96:99], v[210:213], v[202:205], v[96:99]
	s_add_u32 s98, s98, 0x80
	s_addc_u32 s99, s99, 0
	s_add_u32 s100, s100, 0x80
	s_addc_u32 s101, s101, 0
	ds_read_b128 v[206:209], v254 offset:8192
	ds_read_b128 v[210:213], v254 offset:10240
	s_waitcnt lgkmcnt(2)
	v_mfma_f32_16x16x32_bf16 v[92:95], v[242:245], v[150:153], v[92:95]
	s_add_i32 s6, s12, 0x10000
	v_mfma_f32_16x16x32_bf16 v[76:79], v[246:249], v[150:153], v[76:79]
	s_and_b32 s0, s6, 0x10000
	v_mfma_f32_16x16x32_bf16 v[88:91], v[242:245], v[194:197], v[88:91]
	s_add_i32 s0, s0, 0
	v_mfma_f32_16x16x32_bf16 v[72:75], v[246:249], v[194:197], v[72:75]
	s_add_i32 s1, s0, s8
	v_mfma_f32_16x16x32_bf16 v[84:87], v[242:245], v[198:201], v[84:87]
	s_add_i32 s1, s0, s11
	v_mfma_f32_16x16x32_bf16 v[68:71], v[246:249], v[198:201], v[68:71]
	s_add_i32 s1, s0, s10
	v_mfma_f32_16x16x32_bf16 v[80:83], v[242:245], v[202:205], v[80:83]
	s_add_i32 s0, s0, s9
	v_mfma_f32_16x16x32_bf16 v[64:67], v[246:249], v[202:205], v[64:67]
	s_and_b32 s0, s12, 0x10000
	s_add_i32 s0, s0, 0
	s_add_u32 s4, s4, 0x80
	s_addc_u32 s5, s5, 0
	s_cmpk_eq_i32 s4, 0x780
	s_mov_b32 s12, s6
	ds_read_b128 v[242:245], v254 offset:12288
	ds_read_b128 v[246:249], v254 offset:14336
	s_waitcnt lgkmcnt(2)
	v_mfma_f32_16x16x32_bf16 v[60:63], v[206:209], v[150:153], v[60:63]
	v_mfma_f32_16x16x32_bf16 v[44:47], v[210:213], v[150:153], v[44:47]
	v_mfma_f32_16x16x32_bf16 v[56:59], v[206:209], v[194:197], v[56:59]
	v_mfma_f32_16x16x32_bf16 v[40:43], v[210:213], v[194:197], v[40:43]
	v_mfma_f32_16x16x32_bf16 v[52:55], v[206:209], v[198:201], v[52:55]
	v_mfma_f32_16x16x32_bf16 v[36:39], v[210:213], v[198:201], v[36:39]
	v_mfma_f32_16x16x32_bf16 v[48:51], v[206:209], v[202:205], v[48:51]
	v_mfma_f32_16x16x32_bf16 v[32:35], v[210:213], v[202:205], v[32:35]
	v_xor_b32_e32 v254, 64, v254
	v_xor_b32_e32 v255, 64, v255
	ds_read_b128 v[206:209], v254
	ds_read_b128 v[210:213], v254 offset:2048
	s_waitcnt lgkmcnt(2)
	v_mfma_f32_16x16x32_bf16 v[28:31], v[242:245], v[150:153], v[28:31]
	v_mfma_f32_16x16x32_bf16 v[12:15], v[246:249], v[150:153], v[12:15]
	ds_read_b128 v[150:153], v255 offset:32768
	v_mfma_f32_16x16x32_bf16 v[24:27], v[242:245], v[194:197], v[24:27]
	v_mfma_f32_16x16x32_bf16 v[8:11], v[246:249], v[194:197], v[8:11]
	ds_read_b128 v[194:197], v255 offset:34816
	v_mfma_f32_16x16x32_bf16 v[20:23], v[242:245], v[198:201], v[20:23]
	v_mfma_f32_16x16x32_bf16 v[4:7], v[246:249], v[198:201], v[4:7]
	ds_read_b128 v[198:201], v255 offset:36864
	v_mfma_f32_16x16x32_bf16 v[16:19], v[242:245], v[202:205], v[16:19]
	v_mfma_f32_16x16x32_bf16 v[0:3], v[246:249], v[202:205], v[0:3]
	ds_read_b128 v[202:205], v255 offset:38912
	ds_read_b128 v[242:245], v254 offset:4096
	ds_read_b128 v[246:249], v254 offset:6144
	s_waitcnt lgkmcnt(5)
	v_mfma_f32_16x16x32_bf16 v[124:127], v[206:209], v[150:153], v[124:127]
	v_mfma_f32_16x16x32_bf16 v[108:111], v[210:213], v[150:153], v[108:111]
	s_waitcnt lgkmcnt(4)
	v_mfma_f32_16x16x32_bf16 v[120:123], v[206:209], v[194:197], v[120:123]
	v_mfma_f32_16x16x32_bf16 v[104:107], v[210:213], v[194:197], v[104:107]
	s_waitcnt lgkmcnt(3)
	v_mfma_f32_16x16x32_bf16 v[116:119], v[206:209], v[198:201], v[116:119]
	v_mfma_f32_16x16x32_bf16 v[100:103], v[210:213], v[198:201], v[100:103]
	s_waitcnt lgkmcnt(2)
	v_mfma_f32_16x16x32_bf16 v[112:115], v[206:209], v[202:205], v[112:115]
	v_mfma_f32_16x16x32_bf16 v[96:99], v[210:213], v[202:205], v[96:99]
	ds_read_b128 v[206:209], v254 offset:8192
	ds_read_b128 v[210:213], v254 offset:10240
	s_waitcnt lgkmcnt(2)
	v_mfma_f32_16x16x32_bf16 v[92:95], v[242:245], v[150:153], v[92:95]
	v_mfma_f32_16x16x32_bf16 v[76:79], v[246:249], v[150:153], v[76:79]
	v_mfma_f32_16x16x32_bf16 v[88:91], v[242:245], v[194:197], v[88:91]
	v_mfma_f32_16x16x32_bf16 v[72:75], v[246:249], v[194:197], v[72:75]
	v_mfma_f32_16x16x32_bf16 v[84:87], v[242:245], v[198:201], v[84:87]
	v_mfma_f32_16x16x32_bf16 v[68:71], v[246:249], v[198:201], v[68:71]
	v_mfma_f32_16x16x32_bf16 v[80:83], v[242:245], v[202:205], v[80:83]
	v_mfma_f32_16x16x32_bf16 v[64:67], v[246:249], v[202:205], v[64:67]
	ds_read_b128 v[242:245], v254 offset:12288
	ds_read_b128 v[246:249], v254 offset:14336
	s_waitcnt lgkmcnt(2)
	v_mfma_f32_16x16x32_bf16 v[60:63], v[206:209], v[150:153], v[60:63]
	v_mfma_f32_16x16x32_bf16 v[44:47], v[210:213], v[150:153], v[44:47]
	v_mfma_f32_16x16x32_bf16 v[56:59], v[206:209], v[194:197], v[56:59]
	v_mfma_f32_16x16x32_bf16 v[40:43], v[210:213], v[194:197], v[40:43]
	v_mfma_f32_16x16x32_bf16 v[52:55], v[206:209], v[198:201], v[52:55]
	v_mfma_f32_16x16x32_bf16 v[36:39], v[210:213], v[198:201], v[36:39]
	v_mfma_f32_16x16x32_bf16 v[48:51], v[206:209], v[202:205], v[48:51]
	v_mfma_f32_16x16x32_bf16 v[32:35], v[210:213], v[202:205], v[32:35]
	s_waitcnt vmcnt(0) lgkmcnt(0)
	s_barrier
	s_cmpk_eq_i32 s4, 0x780
	s_cbranch_scc1 .Lgx_532
	v_xor_b32_e32 v254, 0x10040, v254
	v_xor_b32_e32 v255, 0x10040, v255
	ds_read_b128 v[206:209], v254
	ds_read_b128 v[210:213], v254 offset:2048
	s_lshl_b32 m0, s4, 9
	s_and_b32 m0, m0, 0x10000
	s_xor_b32 m0, m0, 0x10000
	s_add_i32 m0, m0, s8
	v_mfma_f32_16x16x32_bf16 v[28:31], v[242:245], v[150:153], v[28:31]
	global_load_lds_dwordx4 v250, s[98:99]
	s_add_i32 m0, m0, 0x8000
	v_mfma_f32_16x16x32_bf16 v[12:15], v[246:249], v[150:153], v[12:15]
	ds_read_b128 v[150:153], v255 offset:32768
	v_mfma_f32_16x16x32_bf16 v[24:27], v[242:245], v[194:197], v[24:27]
	global_load_lds_dwordx4 v250, s[100:101]
	s_add_i32 m0, m0, 0xffff8400
	v_mfma_f32_16x16x32_bf16 v[8:11], v[246:249], v[194:197], v[8:11]
	ds_read_b128 v[194:197], v255 offset:34816
	v_mfma_f32_16x16x32_bf16 v[20:23], v[242:245], v[198:201], v[20:23]
	global_load_lds_dwordx4 v251, s[98:99]
	s_add_i32 m0, m0, 0x8000
	v_mfma_f32_16x16x32_bf16 v[4:7], v[246:249], v[198:201], v[4:7]
	ds_read_b128 v[198:201], v255 offset:36864
	v_mfma_f32_16x16x32_bf16 v[16:19], v[242:245], v[202:205], v[16:19]
	global_load_lds_dwordx4 v251, s[100:101]
	v_mfma_f32_16x16x32_bf16 v[0:3], v[246:249], v[202:205], v[0:3]
	ds_read_b128 v[202:205], v255 offset:38912
	s_branch .LBB0_532
.Lgx_532:
	v_mfma_f32_16x16x32_bf16 v[28:31], v[242:245], v[150:153], v[28:31]
	v_mfma_f32_16x16x32_bf16 v[12:15], v[246:249], v[150:153], v[12:15]
	v_mfma_f32_16x16x32_bf16 v[24:27], v[242:245], v[194:197], v[24:27]
	v_mfma_f32_16x16x32_bf16 v[8:11], v[246:249], v[194:197], v[8:11]
	v_mfma_f32_16x16x32_bf16 v[20:23], v[242:245], v[198:201], v[20:23]
	v_mfma_f32_16x16x32_bf16 v[4:7], v[246:249], v[198:201], v[4:7]
	v_mfma_f32_16x16x32_bf16 v[16:19], v[242:245], v[202:205], v[16:19]
	v_mfma_f32_16x16x32_bf16 v[0:3], v[246:249], v[202:205], v[0:3]
	s_add_i32 s0, 0, 0x10000
	v_add_u32_e32 v139, s0, v139
	v_add_u32_e32 v141, v139, v155
	ds_read_b128 v[142:145], v141
	v_add_u32_e32 v128, s0, v128
	v_add_u32_e32 v193, v128, v155
	ds_read_b128 v[146:149], v193 offset:32768
	ds_read_b128 v[150:153], v193 offset:34816
	ds_read_b128 v[194:197], v193 offset:36864
	ds_read_b128 v[198:201], v193 offset:38912
	v_add_u32_e32 v139, v139, v156
	v_add_u32_e32 v128, v128, v156
	s_waitcnt lgkmcnt(3)
	v_mfma_f32_16x16x32_bf16 v[124:127], v[142:145], v[146:149], v[124:127]
	s_and_b64 vcc, exec, s[60:61]
	s_waitcnt lgkmcnt(2)
	v_mfma_f32_16x16x32_bf16 v[120:123], v[142:145], v[150:153], v[120:123]
	s_waitcnt lgkmcnt(1)
	v_mfma_f32_16x16x32_bf16 v[116:119], v[142:145], v[194:197], v[116:119]
	s_waitcnt lgkmcnt(0)
	v_mfma_f32_16x16x32_bf16 v[112:115], v[142:145], v[198:201], v[112:115]
	ds_read_b128 v[142:145], v141 offset:2048
	s_waitcnt lgkmcnt(0)
	v_mfma_f32_16x16x32_bf16 v[108:111], v[142:145], v[146:149], v[108:111]
	v_mfma_f32_16x16x32_bf16 v[104:107], v[142:145], v[150:153], v[104:107]
	v_mfma_f32_16x16x32_bf16 v[100:103], v[142:145], v[194:197], v[100:103]
	v_mfma_f32_16x16x32_bf16 v[96:99], v[142:145], v[198:201], v[96:99]
	ds_read_b128 v[142:145], v141 offset:4096
	s_waitcnt lgkmcnt(0)
	v_mfma_f32_16x16x32_bf16 v[92:95], v[142:145], v[146:149], v[92:95]
	v_mfma_f32_16x16x32_bf16 v[88:91], v[142:145], v[150:153], v[88:91]
	v_mfma_f32_16x16x32_bf16 v[84:87], v[142:145], v[194:197], v[84:87]
	v_mfma_f32_16x16x32_bf16 v[80:83], v[142:145], v[198:201], v[80:83]
	ds_read_b128 v[142:145], v141 offset:6144
	s_waitcnt lgkmcnt(0)
	v_mfma_f32_16x16x32_bf16 v[76:79], v[142:145], v[146:149], v[76:79]
	v_mfma_f32_16x16x32_bf16 v[72:75], v[142:145], v[150:153], v[72:75]
	v_mfma_f32_16x16x32_bf16 v[68:71], v[142:145], v[194:197], v[68:71]
	v_mfma_f32_16x16x32_bf16 v[64:67], v[142:145], v[198:201], v[64:67]
	ds_read_b128 v[142:145], v141 offset:8192
	s_waitcnt lgkmcnt(0)
	v_mfma_f32_16x16x32_bf16 v[60:63], v[142:145], v[146:149], v[60:63]
	v_mfma_f32_16x16x32_bf16 v[56:59], v[142:145], v[150:153], v[56:59]
	v_mfma_f32_16x16x32_bf16 v[52:55], v[142:145], v[194:197], v[52:55]
	v_mfma_f32_16x16x32_bf16 v[48:51], v[142:145], v[198:201], v[48:51]
	ds_read_b128 v[142:145], v141 offset:10240
	s_waitcnt lgkmcnt(0)
	v_mfma_f32_16x16x32_bf16 v[44:47], v[142:145], v[146:149], v[44:47]
	v_mfma_f32_16x16x32_bf16 v[40:43], v[142:145], v[150:153], v[40:43]
	v_mfma_f32_16x16x32_bf16 v[36:39], v[142:145], v[194:197], v[36:39]
	v_mfma_f32_16x16x32_bf16 v[32:35], v[142:145], v[198:201], v[32:35]
	ds_read_b128 v[142:145], v141 offset:12288
	s_waitcnt lgkmcnt(0)
	v_mfma_f32_16x16x32_bf16 v[28:31], v[142:145], v[146:149], v[28:31]
	v_mfma_f32_16x16x32_bf16 v[24:27], v[142:145], v[150:153], v[24:27]
	v_mfma_f32_16x16x32_bf16 v[20:23], v[142:145], v[194:197], v[20:23]
	v_mfma_f32_16x16x32_bf16 v[16:19], v[142:145], v[198:201], v[16:19]
	ds_read_b128 v[142:145], v141 offset:14336
	s_waitcnt lgkmcnt(0)
	v_mfma_f32_16x16x32_bf16 v[12:15], v[142:145], v[146:149], v[12:15]
	ds_read_b128 v[146:149], v139
	v_mfma_f32_16x16x32_bf16 v[8:11], v[142:145], v[150:153], v[8:11]
	ds_read_b128 v[150:153], v128 offset:34816
	v_mfma_f32_16x16x32_bf16 v[4:7], v[142:145], v[194:197], v[4:7]
	ds_read_b128 v[194:197], v128 offset:36864
	v_mfma_f32_16x16x32_bf16 v[0:3], v[142:145], v[198:201], v[0:3]
	ds_read_b128 v[142:145], v128 offset:32768
	ds_read_b128 v[198:201], v128 offset:38912
	s_waitcnt lgkmcnt(1)
	v_mfma_f32_16x16x32_bf16 v[124:127], v[146:149], v[142:145], v[124:127]
	v_mfma_f32_16x16x32_bf16 v[120:123], v[146:149], v[150:153], v[120:123]
	v_mfma_f32_16x16x32_bf16 v[116:119], v[146:149], v[194:197], v[116:119]
	s_waitcnt lgkmcnt(0)
	v_mfma_f32_16x16x32_bf16 v[112:115], v[146:149], v[198:201], v[112:115]
	ds_read_b128 v[146:149], v139 offset:2048
	s_waitcnt lgkmcnt(0)
	v_mfma_f32_16x16x32_bf16 v[108:111], v[146:149], v[142:145], v[108:111]
	v_mfma_f32_16x16x32_bf16 v[104:107], v[146:149], v[150:153], v[104:107]
	v_mfma_f32_16x16x32_bf16 v[100:103], v[146:149], v[194:197], v[100:103]
	v_mfma_f32_16x16x32_bf16 v[96:99], v[146:149], v[198:201], v[96:99]
	ds_read_b128 v[146:149], v139 offset:4096
	s_waitcnt lgkmcnt(0)
	v_mfma_f32_16x16x32_bf16 v[92:95], v[146:149], v[142:145], v[92:95]
	v_mfma_f32_16x16x32_bf16 v[88:91], v[146:149], v[150:153], v[88:91]
	v_mfma_f32_16x16x32_bf16 v[84:87], v[146:149], v[194:197], v[84:87]
	v_mfma_f32_16x16x32_bf16 v[80:83], v[146:149], v[198:201], v[80:83]
	ds_read_b128 v[146:149], v139 offset:6144
	s_waitcnt lgkmcnt(0)
	v_mfma_f32_16x16x32_bf16 v[76:79], v[146:149], v[142:145], v[76:79]
	v_mfma_f32_16x16x32_bf16 v[72:75], v[146:149], v[150:153], v[72:75]
	v_mfma_f32_16x16x32_bf16 v[68:71], v[146:149], v[194:197], v[68:71]
	v_mfma_f32_16x16x32_bf16 v[64:67], v[146:149], v[198:201], v[64:67]
	ds_read_b128 v[146:149], v139 offset:8192
	s_waitcnt lgkmcnt(0)
	v_mfma_f32_16x16x32_bf16 v[60:63], v[146:149], v[142:145], v[60:63]
	v_mfma_f32_16x16x32_bf16 v[56:59], v[146:149], v[150:153], v[56:59]
	v_mfma_f32_16x16x32_bf16 v[52:55], v[146:149], v[194:197], v[52:55]
	v_mfma_f32_16x16x32_bf16 v[48:51], v[146:149], v[198:201], v[48:51]
	ds_read_b128 v[146:149], v139 offset:10240
	s_waitcnt lgkmcnt(0)
	v_mfma_f32_16x16x32_bf16 v[44:47], v[146:149], v[142:145], v[44:47]
	v_mfma_f32_16x16x32_bf16 v[40:43], v[146:149], v[150:153], v[40:43]
	v_mfma_f32_16x16x32_bf16 v[36:39], v[146:149], v[194:197], v[36:39]
	v_mfma_f32_16x16x32_bf16 v[32:35], v[146:149], v[198:201], v[32:35]
	ds_read_b128 v[146:149], v139 offset:12288
	s_waitcnt lgkmcnt(0)
	v_mfma_f32_16x16x32_bf16 v[28:31], v[146:149], v[142:145], v[28:31]
	v_mfma_f32_16x16x32_bf16 v[24:27], v[146:149], v[150:153], v[24:27]
	v_mfma_f32_16x16x32_bf16 v[20:23], v[146:149], v[194:197], v[20:23]
	v_mfma_f32_16x16x32_bf16 v[16:19], v[146:149], v[198:201], v[16:19]
	ds_read_b128 v[146:149], v139 offset:14336
	s_waitcnt vmcnt(0)
	s_waitcnt lgkmcnt(0)
	v_mfma_f32_16x16x32_bf16 v[12:15], v[146:149], v[142:145], v[12:15]
	s_barrier
	v_mfma_f32_16x16x32_bf16 v[8:11], v[146:149], v[150:153], v[8:11]
	v_mfma_f32_16x16x32_bf16 v[4:7], v[146:149], v[194:197], v[4:7]
	v_mfma_f32_16x16x32_bf16 v[0:3], v[146:149], v[198:201], v[0:3]
	s_cbranch_vccz .LBB0_535
	s_lshl_b64 s[2:3], s[2:3], 1
	s_add_u32 s4, s62, s2
	s_addc_u32 s5, s63, s3
	s_add_u32 s2, s64, s2
	s_addc_u32 s3, s65, s3
	s_add_i32 s0, s8, 0
	v_mov_b32_e32 v139, v129
	s_mov_b32 m0, s0
	v_mov_b32_e32 v141, v129
	v_lshl_add_u64 v[142:143], s[4:5], 0, v[138:139]
	global_load_lds_dwordx4 v138, s[4:5]
	s_add_i32 m0, s0, 0x8000
	v_lshl_add_u64 v[146:147], s[4:5], 0, v[140:141]
	s_mov_b64 s[4:5], 0x4000
	s_add_i32 s0, s11, 0
	global_load_lds_dwordx4 v138, s[2:3]
	v_lshl_add_u64 v[148:149], v[146:147], 0, s[4:5]
	s_mov_b32 m0, s0
	v_lshl_add_u64 v[144:145], s[2:3], 0, v[138:139]
	global_load_lds_dwordx4 v[148:149], off
	v_lshl_add_u64 v[148:149], s[2:3], 0, v[140:141]
	v_lshl_add_u64 v[150:151], v[148:149], 0, s[4:5]
	s_add_i32 m0, s0, 0x8000
	s_mov_b64 s[2:3], 0x8000
	s_add_i32 s0, s10, 0
	global_load_lds_dwordx4 v[150:151], off
	v_lshl_add_u64 v[142:143], v[142:143], 0, s[2:3]
	s_mov_b32 m0, s0
	s_nop 0
	global_load_lds_dwordx4 v[142:143], off
	v_lshl_add_u64 v[142:143], v[144:145], 0, s[2:3]
	s_add_i32 m0, s0, 0x8000
	s_mov_b64 s[2:3], 0xc000
	s_add_i32 s0, s9, 0
	global_load_lds_dwordx4 v[142:143], off
	v_lshl_add_u64 v[142:143], v[146:147], 0, s[2:3]
	s_mov_b32 m0, s0
	s_nop 0
	global_load_lds_dwordx4 v[142:143], off
	v_lshl_add_u64 v[142:143], v[148:149], 0, s[2:3]
	s_add_i32 m0, s0, 0x8000
	s_nop 0
	global_load_lds_dwordx4 v[142:143], off

.LBB0_735:
	s_lshr_b32 s38, s37, 1
	s_and_b32 s38, s38, 0x1ffff80
	v_or_b32_e32 v0, s38, v148
	s_and_b32 s37, s37, 0xc0
	v_lshlrev_b32_e32 v139, 7, v0
	v_or_b32_e32 v0, s37, v148
	s_mov_b32 s37, s3
	s_lshl_b64 s[36:37], s[36:37], 16
	s_add_u32 s30, s36, s30
	v_lshlrev_b32_e32 v153, 7, v0
	v_lshl_add_u64 v[0:1], s[28:29], 0, v[130:131]
	s_addc_u32 s31, s37, s31
	s_waitcnt vmcnt(0)
	v_lshl_add_u64 v[140:141], v[0:1], 0, s[30:31]
	s_add_u32 s34, s36, s34
	v_lshl_add_u64 v[0:1], s[28:29], 0, v[134:135]
	s_addc_u32 s35, s37, s35
	v_lshl_add_u64 v[144:145], v[0:1], 0, s[30:31]
	v_mov_b32_e32 v0, 0
	v_lshl_add_u64 v[142:143], v[132:133], 0, s[34:35]
	v_lshl_add_u64 v[146:147], v[136:137], 0, s[34:35]
	s_mov_b64 s[28:29], 0
	s_mov_b32 s34, 0
	v_mov_b32_e32 v1, v0
	v_mov_b32_e32 v2, v0
	v_mov_b32_e32 v3, v0
	v_mov_b32_e32 v4, v0
	v_mov_b32_e32 v5, v0
	v_mov_b32_e32 v6, v0
	v_mov_b32_e32 v7, v0
	v_mov_b32_e32 v8, v0
	v_mov_b32_e32 v9, v0
	v_mov_b32_e32 v10, v0
	v_mov_b32_e32 v11, v0
	v_mov_b32_e32 v12, v0
	v_mov_b32_e32 v13, v0
	v_mov_b32_e32 v14, v0
	v_mov_b32_e32 v15, v0
	v_mov_b32_e32 v16, v0
	v_mov_b32_e32 v17, v0
	v_mov_b32_e32 v18, v0
	v_mov_b32_e32 v19, v0
	v_mov_b32_e32 v20, v0
	v_mov_b32_e32 v21, v0
	v_mov_b32_e32 v22, v0
	v_mov_b32_e32 v23, v0
	v_mov_b32_e32 v24, v0
	v_mov_b32_e32 v25, v0
	v_mov_b32_e32 v26, v0
	v_mov_b32_e32 v27, v0
	v_mov_b32_e32 v28, v0
	v_mov_b32_e32 v29, v0
	v_mov_b32_e32 v30, v0
	v_mov_b32_e32 v31, v0
	v_mov_b32_e32 v32, v0
	v_mov_b32_e32 v33, v0
	v_mov_b32_e32 v34, v0
	v_mov_b32_e32 v35, v0
	v_mov_b32_e32 v36, v0
	v_mov_b32_e32 v37, v0
	v_mov_b32_e32 v38, v0
	v_mov_b32_e32 v39, v0
	v_mov_b32_e32 v40, v0
	v_mov_b32_e32 v41, v0
	v_mov_b32_e32 v42, v0
	v_mov_b32_e32 v43, v0
	v_mov_b32_e32 v44, v0
	v_mov_b32_e32 v45, v0
	v_mov_b32_e32 v46, v0
	v_mov_b32_e32 v47, v0
	v_mov_b32_e32 v48, v0
	v_mov_b32_e32 v49, v0
	v_mov_b32_e32 v50, v0
	v_mov_b32_e32 v51, v0
	v_mov_b32_e32 v52, v0
	v_mov_b32_e32 v53, v0
	v_mov_b32_e32 v54, v0
	v_mov_b32_e32 v55, v0
	v_mov_b32_e32 v56, v0
	v_mov_b32_e32 v57, v0
	v_mov_b32_e32 v58, v0
	v_mov_b32_e32 v59, v0
	v_mov_b32_e32 v60, v0
	v_mov_b32_e32 v61, v0
	v_mov_b32_e32 v62, v0
	v_mov_b32_e32 v63, v0
	v_mov_b32_e32 v64, v0
	v_mov_b32_e32 v65, v0
	v_mov_b32_e32 v66, v0
	v_mov_b32_e32 v67, v0
	v_mov_b32_e32 v68, v0
	v_mov_b32_e32 v69, v0
	v_mov_b32_e32 v70, v0
	v_mov_b32_e32 v71, v0
	v_mov_b32_e32 v72, v0
	v_mov_b32_e32 v73, v0
	v_mov_b32_e32 v74, v0
	v_mov_b32_e32 v75, v0
	v_mov_b32_e32 v76, v0
	v_mov_b32_e32 v77, v0
	v_mov_b32_e32 v78, v0
	v_mov_b32_e32 v79, v0
	v_mov_b32_e32 v80, v0
	v_mov_b32_e32 v81, v0
	v_mov_b32_e32 v82, v0
	v_mov_b32_e32 v83, v0
	v_mov_b32_e32 v84, v0
	v_mov_b32_e32 v85, v0
	v_mov_b32_e32 v86, v0
	v_mov_b32_e32 v87, v0
	v_mov_b32_e32 v88, v0
	v_mov_b32_e32 v89, v0
	v_mov_b32_e32 v90, v0
	v_mov_b32_e32 v91, v0
	v_mov_b32_e32 v92, v0
	v_mov_b32_e32 v93, v0
	v_mov_b32_e32 v94, v0
	v_mov_b32_e32 v95, v0
	v_mov_b32_e32 v96, v0
	v_mov_b32_e32 v97, v0
	v_mov_b32_e32 v98, v0
	v_mov_b32_e32 v99, v0
	v_mov_b32_e32 v100, v0
	v_mov_b32_e32 v101, v0
	v_mov_b32_e32 v102, v0
	v_mov_b32_e32 v103, v0
	v_mov_b32_e32 v104, v0
	v_mov_b32_e32 v105, v0
	v_mov_b32_e32 v106, v0
	v_mov_b32_e32 v107, v0
	v_mov_b32_e32 v108, v0
	v_mov_b32_e32 v109, v0
	v_mov_b32_e32 v110, v0
	v_mov_b32_e32 v111, v0
	v_mov_b32_e32 v112, v0
	v_mov_b32_e32 v113, v0
	v_mov_b32_e32 v114, v0
	v_mov_b32_e32 v115, v0
	v_mov_b32_e32 v116, v0
	v_mov_b32_e32 v117, v0
	v_mov_b32_e32 v118, v0
	v_mov_b32_e32 v119, v0
	v_mov_b32_e32 v120, v0
	v_mov_b32_e32 v121, v0
	v_mov_b32_e32 v122, v0
	v_mov_b32_e32 v123, v0
	v_mov_b32_e32 v124, v0
	v_mov_b32_e32 v125, v0
	v_mov_b32_e32 v126, v0
	v_mov_b32_e32 v127, v0
	s_waitcnt vmcnt(0) lgkmcnt(0)
	s_barrier
	v_bfe_u32 v250, v178, 3, 3
	v_and_b32_e32 v251, 7, v178
	v_lshrrev_b32_e32 v252, 1, v250
	v_xor_b32_e32 v251, v251, v252
	v_lshlrev_b32_e32 v251, 4, v251
	v_lshl_or_b32 v250, v250, 11, v251
	v_xor_b32_e32 v251, 64, v250
	v_add_u32_e32 v251, 0x4000, v251
	v_add_u32_e32 v252, 0x8000, v250
	v_add_u32_e32 v253, 0x8000, v251
	v_lshl_add_u64 v[242:243], v[140:141], 0, s[28:29]
	s_mov_b64 s[36:37], 0x80
	v_lshl_add_u64 v[242:243], v[242:243], 0, s[36:37]
	v_lshl_add_u64 v[244:245], v[142:143], 0, s[28:29]
	s_mov_b64 s[36:37], 0x12c00080
	v_lshl_add_u64 v[244:245], v[244:245], 0, s[36:37]
	v_add_u32_e32 v254, v139, v149
	v_add_u32_e32 v255, v153, v149
	v_readfirstlane_b32 s98, v242
	v_readfirstlane_b32 s99, v243
	v_readfirstlane_b32 s100, v244
	v_readfirstlane_b32 s101, v245
	ds_read_b128 v[170:173], v254
	ds_read_b128 v[174:177], v254 offset:2048
	ds_read_b128 v[154:157], v255 offset:32768
	ds_read_b128 v[158:161], v255 offset:34816
	ds_read_b128 v[162:165], v255 offset:36864
	ds_read_b128 v[166:169], v255 offset:38912
	s_nop 4
	s_lshl_b32 m0, s28, 9
	s_and_b32 m0, m0, 0x10000
	s_xor_b32 m0, m0, 0x10000
	s_add_i32 m0, m0, s2
	s_nop 0
	global_load_lds_dwordx4 v250, s[98:99]
	s_add_i32 m0, m0, 0x8000
	s_nop 0
	global_load_lds_dwordx4 v250, s[100:101]
	s_add_i32 m0, m0, 0xffff8400
	s_nop 0
	global_load_lds_dwordx4 v251, s[98:99]
	s_add_i32 m0, m0, 0x8000
	s_nop 0
	global_load_lds_dwordx4 v251, s[100:101]
.LBB0_736:
	ds_read_b128 v[242:245], v254 offset:4096
	ds_read_b128 v[246:249], v254 offset:6144
	s_lshl_b32 m0, s28, 9
	s_and_b32 m0, m0, 0x10000
	s_xor_b32 m0, m0, 0x10000
	s_add_i32 m0, m0, s2
	s_add_i32 m0, m0, 0x800
	s_waitcnt lgkmcnt(5)
	v_mfma_f32_16x16x32_bf16 v[124:127], v[154:157], v[170:173], v[124:127]
	global_load_lds_dwordx4 v252, s[98:99]
	s_add_i32 m0, m0, 0x8000
	v_mfma_f32_16x16x32_bf16 v[108:111], v[154:157], v[174:177], v[108:111]
	s_waitcnt lgkmcnt(4)
	v_mfma_f32_16x16x32_bf16 v[120:123], v[158:161], v[170:173], v[120:123]
	global_load_lds_dwordx4 v252, s[100:101]
	s_add_i32 m0, m0, 0xffff8400
	v_mfma_f32_16x16x32_bf16 v[104:107], v[158:161], v[174:177], v[104:107]
	s_waitcnt lgkmcnt(3)
	v_mfma_f32_16x16x32_bf16 v[116:119], v[162:165], v[170:173], v[116:119]
	global_load_lds_dwordx4 v253, s[98:99]
	s_add_i32 m0, m0, 0x8000
	v_mfma_f32_16x16x32_bf16 v[100:103], v[162:165], v[174:177], v[100:103]
	s_waitcnt lgkmcnt(2)
	v_mfma_f32_16x16x32_bf16 v[112:115], v[166:169], v[170:173], v[112:115]
	global_load_lds_dwordx4 v253, s[100:101]
	v_mfma_f32_16x16x32_bf16 v[96:99], v[166:169], v[174:177], v[96:99]
	s_add_u32 s98, s98, 0x80
	s_addc_u32 s99, s99, 0
	s_add_u32 s100, s100, 0x80
	s_addc_u32 s101, s101, 0
	ds_read_b128 v[170:173], v254 offset:8192
	ds_read_b128 v[174:177], v254 offset:10240
	s_waitcnt lgkmcnt(2)
	v_mfma_f32_16x16x32_bf16 v[92:95], v[154:157], v[242:245], v[92:95]
	s_add_i32 s31, s34, 0x10000
	v_mfma_f32_16x16x32_bf16 v[76:79], v[154:157], v[246:249], v[76:79]
	s_and_b32 s30, s31, 0x10000
	v_mfma_f32_16x16x32_bf16 v[88:91], v[158:161], v[242:245], v[88:91]
	s_add_i32 s30, s30, 0
	v_mfma_f32_16x16x32_bf16 v[72:75], v[158:161], v[246:249], v[72:75]
	s_mov_b64 s[36:37], 0x80
	v_mfma_f32_16x16x32_bf16 v[84:87], v[162:165], v[242:245], v[84:87]
	s_add_i32 s35, s30, s2
	v_mfma_f32_16x16x32_bf16 v[68:71], v[162:165], v[246:249], v[68:71]
	s_mov_b64 s[36:37], 0x12c00080
	v_mfma_f32_16x16x32_bf16 v[80:83], v[166:169], v[242:245], v[80:83]
	s_mov_b64 s[36:37], 0x4080
	v_mfma_f32_16x16x32_bf16 v[64:67], v[166:169], v[246:249], v[64:67]
	s_add_i32 s35, s30, s53
	s_mov_b64 s[36:37], 0x12c04080
	s_mov_b64 s[36:37], 0x8080
	s_add_i32 s35, s30, s52
	s_and_b32 s34, s34, 0x10000
	s_add_i32 s35, s30, s19
	s_add_i32 s34, s34, 0
	s_add_u32 s28, s28, 0x80
	s_addc_u32 s29, s29, 0
	s_cmpk_eq_i32 s28, 0x780
	s_mov_b32 s34, s31
	ds_read_b128 v[242:245], v254 offset:12288
	ds_read_b128 v[246:249], v254 offset:14336
	s_waitcnt lgkmcnt(2)
	v_mfma_f32_16x16x32_bf16 v[60:63], v[154:157], v[170:173], v[60:63]
	v_mfma_f32_16x16x32_bf16 v[44:47], v[154:157], v[174:177], v[44:47]
	v_mfma_f32_16x16x32_bf16 v[56:59], v[158:161], v[170:173], v[56:59]
	v_mfma_f32_16x16x32_bf16 v[40:43], v[158:161], v[174:177], v[40:43]
	v_mfma_f32_16x16x32_bf16 v[52:55], v[162:165], v[170:173], v[52:55]
	v_mfma_f32_16x16x32_bf16 v[36:39], v[162:165], v[174:177], v[36:39]
	v_mfma_f32_16x16x32_bf16 v[48:51], v[166:169], v[170:173], v[48:51]
	v_mfma_f32_16x16x32_bf16 v[32:35], v[166:169], v[174:177], v[32:35]
	v_xor_b32_e32 v254, 64, v254
	v_xor_b32_e32 v255, 64, v255
	ds_read_b128 v[170:173], v254
	ds_read_b128 v[174:177], v254 offset:2048
	s_waitcnt lgkmcnt(2)
	v_mfma_f32_16x16x32_bf16 v[28:31], v[154:157], v[242:245], v[28:31]
	v_mfma_f32_16x16x32_bf16 v[12:15], v[154:157], v[246:249], v[12:15]
	ds_read_b128 v[154:157], v255 offset:32768
	v_mfma_f32_16x16x32_bf16 v[24:27], v[158:161], v[242:245], v[24:27]
	v_mfma_f32_16x16x32_bf16 v[8:11], v[158:161], v[246:249], v[8:11]
	ds_read_b128 v[158:161], v255 offset:34816
	v_mfma_f32_16x16x32_bf16 v[20:23], v[162:165], v[242:245], v[20:23]
	v_mfma_f32_16x16x32_bf16 v[4:7], v[162:165], v[246:249], v[4:7]
	ds_read_b128 v[162:165], v255 offset:36864
	v_mfma_f32_16x16x32_bf16 v[16:19], v[166:169], v[242:245], v[16:19]
	v_mfma_f32_16x16x32_bf16 v[0:3], v[166:169], v[246:249], v[0:3]
	ds_read_b128 v[166:169], v255 offset:38912
	ds_read_b128 v[242:245], v254 offset:4096
	ds_read_b128 v[246:249], v254 offset:6144
	s_waitcnt lgkmcnt(5)
	v_mfma_f32_16x16x32_bf16 v[124:127], v[154:157], v[170:173], v[124:127]
	v_mfma_f32_16x16x32_bf16 v[108:111], v[154:157], v[174:177], v[108:111]
	s_waitcnt lgkmcnt(4)
	v_mfma_f32_16x16x32_bf16 v[120:123], v[158:161], v[170:173], v[120:123]
	v_mfma_f32_16x16x32_bf16 v[104:107], v[158:161], v[174:177], v[104:107]
	s_waitcnt lgkmcnt(3)
	v_mfma_f32_16x16x32_bf16 v[116:119], v[162:165], v[170:173], v[116:119]
	v_mfma_f32_16x16x32_bf16 v[100:103], v[162:165], v[174:177], v[100:103]
	s_waitcnt lgkmcnt(2)
	v_mfma_f32_16x16x32_bf16 v[112:115], v[166:169], v[170:173], v[112:115]
	v_mfma_f32_16x16x32_bf16 v[96:99], v[166:169], v[174:177], v[96:99]
	ds_read_b128 v[170:173], v254 offset:8192
	ds_read_b128 v[174:177], v254 offset:10240
	s_waitcnt lgkmcnt(2)
	v_mfma_f32_16x16x32_bf16 v[92:95], v[154:157], v[242:245], v[92:95]
	v_mfma_f32_16x16x32_bf16 v[76:79], v[154:157], v[246:249], v[76:79]
	v_mfma_f32_16x16x32_bf16 v[88:91], v[158:161], v[242:245], v[88:91]
	v_mfma_f32_16x16x32_bf16 v[72:75], v[158:161], v[246:249], v[72:75]
	v_mfma_f32_16x16x32_bf16 v[84:87], v[162:165], v[242:245], v[84:87]
	v_mfma_f32_16x16x32_bf16 v[68:71], v[162:165], v[246:249], v[68:71]
	v_mfma_f32_16x16x32_bf16 v[80:83], v[166:169], v[242:245], v[80:83]
	v_mfma_f32_16x16x32_bf16 v[64:67], v[166:169], v[246:249], v[64:67]
	ds_read_b128 v[242:245], v254 offset:12288
	ds_read_b128 v[246:249], v254 offset:14336
	s_waitcnt lgkmcnt(2)
	v_mfma_f32_16x16x32_bf16 v[60:63], v[154:157], v[170:173], v[60:63]
	v_mfma_f32_16x16x32_bf16 v[44:47], v[154:157], v[174:177], v[44:47]
	v_mfma_f32_16x16x32_bf16 v[56:59], v[158:161], v[170:173], v[56:59]
	v_mfma_f32_16x16x32_bf16 v[40:43], v[158:161], v[174:177], v[40:43]
	v_mfma_f32_16x16x32_bf16 v[52:55], v[162:165], v[170:173], v[52:55]
	v_mfma_f32_16x16x32_bf16 v[36:39], v[162:165], v[174:177], v[36:39]
	v_mfma_f32_16x16x32_bf16 v[48:51], v[166:169], v[170:173], v[48:51]
	v_mfma_f32_16x16x32_bf16 v[32:35], v[166:169], v[174:177], v[32:35]
	s_waitcnt vmcnt(0) lgkmcnt(0)
	s_barrier
	s_cmpk_eq_i32 s28, 0x780
	s_cbranch_scc1 .Lgx_736
	v_xor_b32_e32 v254, 0x10040, v254
	v_xor_b32_e32 v255, 0x10040, v255
	ds_read_b128 v[170:173], v254
	ds_read_b128 v[174:177], v254 offset:2048
	s_lshl_b32 m0, s28, 9
	s_and_b32 m0, m0, 0x10000
	s_xor_b32 m0, m0, 0x10000
	s_add_i32 m0, m0, s2
	v_mfma_f32_16x16x32_bf16 v[28:31], v[154:157], v[242:245], v[28:31]
	global_load_lds_dwordx4 v250, s[98:99]
	s_add_i32 m0, m0, 0x8000
	v_mfma_f32_16x16x32_bf16 v[12:15], v[154:157], v[246:249], v[12:15]
	ds_read_b128 v[154:157], v255 offset:32768
	v_mfma_f32_16x16x32_bf16 v[24:27], v[158:161], v[242:245], v[24:27]
	global_load_lds_dwordx4 v250, s[100:101]
	s_add_i32 m0, m0, 0xffff8400
	v_mfma_f32_16x16x32_bf16 v[8:11], v[158:161], v[246:249], v[8:11]
	ds_read_b128 v[158:161], v255 offset:34816
	v_mfma_f32_16x16x32_bf16 v[20:23], v[162:165], v[242:245], v[20:23]
	global_load_lds_dwordx4 v251, s[98:99]
	s_add_i32 m0, m0, 0x8000
	v_mfma_f32_16x16x32_bf16 v[4:7], v[162:165], v[246:249], v[4:7]
	ds_read_b128 v[162:165], v255 offset:36864
	v_mfma_f32_16x16x32_bf16 v[16:19], v[166:169], v[242:245], v[16:19]
	global_load_lds_dwordx4 v251, s[100:101]
	v_mfma_f32_16x16x32_bf16 v[0:3], v[166:169], v[246:249], v[0:3]
	ds_read_b128 v[166:169], v255 offset:38912
	s_branch .LBB0_736
.Lgx_736:
	v_mfma_f32_16x16x32_bf16 v[28:31], v[154:157], v[242:245], v[28:31]
	v_mfma_f32_16x16x32_bf16 v[12:15], v[154:157], v[246:249], v[12:15]
	v_mfma_f32_16x16x32_bf16 v[24:27], v[158:161], v[242:245], v[24:27]
	v_mfma_f32_16x16x32_bf16 v[8:11], v[158:161], v[246:249], v[8:11]
	v_mfma_f32_16x16x32_bf16 v[20:23], v[162:165], v[242:245], v[20:23]
	v_mfma_f32_16x16x32_bf16 v[4:7], v[162:165], v[246:249], v[4:7]
	v_mfma_f32_16x16x32_bf16 v[16:19], v[166:169], v[242:245], v[16:19]
	v_mfma_f32_16x16x32_bf16 v[0:3], v[166:169], v[246:249], v[0:3]
	v_add_u32_e32 v153, s30, v153
	v_add_u32_e32 v166, v153, v149
	v_add_u32_e32 v139, s30, v139
	ds_read_b128 v[140:143], v166 offset:32768
	v_add_u32_e32 v170, v139, v149
	ds_read_b128 v[144:147], v166 offset:34816
	ds_read_b128 v[154:157], v170
	ds_read_b128 v[158:161], v170 offset:2048
	ds_read_b128 v[162:165], v166 offset:36864
	ds_read_b128 v[166:169], v166 offset:38912
	s_waitcnt lgkmcnt(3)
	v_mfma_f32_16x16x32_bf16 v[120:123], v[144:147], v[154:157], v[120:123]
	v_add_u32_e32 v153, v153, v150
	v_add_u32_e32 v139, v139, v150
	s_and_b64 vcc, exec, s[20:21]
	v_mfma_f32_16x16x32_bf16 v[124:127], v[140:143], v[154:157], v[124:127]
	s_waitcnt lgkmcnt(1)
	v_mfma_f32_16x16x32_bf16 v[116:119], v[162:165], v[154:157], v[116:119]
	s_waitcnt lgkmcnt(0)
	v_mfma_f32_16x16x32_bf16 v[112:115], v[166:169], v[154:157], v[112:115]
	v_mfma_f32_16x16x32_bf16 v[108:111], v[140:143], v[158:161], v[108:111]
	v_mfma_f32_16x16x32_bf16 v[104:107], v[144:147], v[158:161], v[104:107]
	v_mfma_f32_16x16x32_bf16 v[100:103], v[162:165], v[158:161], v[100:103]
	v_mfma_f32_16x16x32_bf16 v[96:99], v[166:169], v[158:161], v[96:99]
	ds_read_b128 v[154:157], v170 offset:4096
	ds_read_b128 v[158:161], v170 offset:6144
	s_waitcnt lgkmcnt(1)
	v_mfma_f32_16x16x32_bf16 v[92:95], v[140:143], v[154:157], v[92:95]
	v_mfma_f32_16x16x32_bf16 v[88:91], v[144:147], v[154:157], v[88:91]
	v_mfma_f32_16x16x32_bf16 v[84:87], v[162:165], v[154:157], v[84:87]
	v_mfma_f32_16x16x32_bf16 v[80:83], v[166:169], v[154:157], v[80:83]
	s_waitcnt lgkmcnt(0)
	v_mfma_f32_16x16x32_bf16 v[76:79], v[140:143], v[158:161], v[76:79]
	v_mfma_f32_16x16x32_bf16 v[72:75], v[144:147], v[158:161], v[72:75]
	v_mfma_f32_16x16x32_bf16 v[68:71], v[162:165], v[158:161], v[68:71]
	v_mfma_f32_16x16x32_bf16 v[64:67], v[166:169], v[158:161], v[64:67]
	ds_read_b128 v[154:157], v170 offset:8192
	ds_read_b128 v[158:161], v170 offset:10240
	s_waitcnt lgkmcnt(1)
	v_mfma_f32_16x16x32_bf16 v[60:63], v[140:143], v[154:157], v[60:63]
	v_mfma_f32_16x16x32_bf16 v[56:59], v[144:147], v[154:157], v[56:59]
	v_mfma_f32_16x16x32_bf16 v[52:55], v[162:165], v[154:157], v[52:55]
	v_mfma_f32_16x16x32_bf16 v[48:51], v[166:169], v[154:157], v[48:51]
	s_waitcnt lgkmcnt(0)
	v_mfma_f32_16x16x32_bf16 v[44:47], v[140:143], v[158:161], v[44:47]
	v_mfma_f32_16x16x32_bf16 v[40:43], v[144:147], v[158:161], v[40:43]
	v_mfma_f32_16x16x32_bf16 v[36:39], v[162:165], v[158:161], v[36:39]
	v_mfma_f32_16x16x32_bf16 v[32:35], v[166:169], v[158:161], v[32:35]
	ds_read_b128 v[154:157], v170 offset:12288
	ds_read_b128 v[158:161], v170 offset:14336
	s_waitcnt lgkmcnt(1)
	v_mfma_f32_16x16x32_bf16 v[28:31], v[140:143], v[154:157], v[28:31]
	v_mfma_f32_16x16x32_bf16 v[24:27], v[144:147], v[154:157], v[24:27]
	v_mfma_f32_16x16x32_bf16 v[20:23], v[162:165], v[154:157], v[20:23]
	v_mfma_f32_16x16x32_bf16 v[16:19], v[166:169], v[154:157], v[16:19]
	s_waitcnt lgkmcnt(0)
	v_mfma_f32_16x16x32_bf16 v[12:15], v[140:143], v[158:161], v[12:15]
	v_mfma_f32_16x16x32_bf16 v[8:11], v[144:147], v[158:161], v[8:11]
	ds_read_b128 v[144:147], v153 offset:34816
	v_mfma_f32_16x16x32_bf16 v[140:143], v[162:165], v[158:161], v[4:7]
	s_nop 2
	ds_read_b128 v[4:7], v153 offset:32768
	v_mfma_f32_16x16x32_bf16 v[0:3], v[166:169], v[158:161], v[0:3]
	ds_read_b128 v[154:157], v139
	ds_read_b128 v[158:161], v139 offset:2048
	ds_read_b128 v[162:165], v153 offset:36864
	ds_read_b128 v[166:169], v153 offset:38912
	s_waitcnt lgkmcnt(3)
	v_mfma_f32_16x16x32_bf16 v[124:127], v[4:7], v[154:157], v[124:127]
	v_mfma_f32_16x16x32_bf16 v[120:123], v[144:147], v[154:157], v[120:123]
	s_waitcnt lgkmcnt(1)
	v_mfma_f32_16x16x32_bf16 v[116:119], v[162:165], v[154:157], v[116:119]
	s_waitcnt lgkmcnt(0)
	v_mfma_f32_16x16x32_bf16 v[112:115], v[166:169], v[154:157], v[112:115]
	v_mfma_f32_16x16x32_bf16 v[108:111], v[4:7], v[158:161], v[108:111]
	v_mfma_f32_16x16x32_bf16 v[104:107], v[144:147], v[158:161], v[104:107]
	v_mfma_f32_16x16x32_bf16 v[100:103], v[162:165], v[158:161], v[100:103]
	v_mfma_f32_16x16x32_bf16 v[96:99], v[166:169], v[158:161], v[96:99]
	ds_read_b128 v[154:157], v139 offset:4096
	ds_read_b128 v[158:161], v139 offset:6144
	s_waitcnt lgkmcnt(1)
	v_mfma_f32_16x16x32_bf16 v[92:95], v[4:7], v[154:157], v[92:95]
	v_mfma_f32_16x16x32_bf16 v[88:91], v[144:147], v[154:157], v[88:91]
	v_mfma_f32_16x16x32_bf16 v[84:87], v[162:165], v[154:157], v[84:87]
	v_mfma_f32_16x16x32_bf16 v[80:83], v[166:169], v[154:157], v[80:83]
	s_waitcnt lgkmcnt(0)
	v_mfma_f32_16x16x32_bf16 v[76:79], v[4:7], v[158:161], v[76:79]
	v_mfma_f32_16x16x32_bf16 v[72:75], v[144:147], v[158:161], v[72:75]
	v_mfma_f32_16x16x32_bf16 v[68:71], v[162:165], v[158:161], v[68:71]
	v_mfma_f32_16x16x32_bf16 v[64:67], v[166:169], v[158:161], v[64:67]
	ds_read_b128 v[154:157], v139 offset:8192
	ds_read_b128 v[158:161], v139 offset:10240
	s_waitcnt lgkmcnt(1)
	v_mfma_f32_16x16x32_bf16 v[60:63], v[4:7], v[154:157], v[60:63]
	v_mfma_f32_16x16x32_bf16 v[56:59], v[144:147], v[154:157], v[56:59]
	v_mfma_f32_16x16x32_bf16 v[52:55], v[162:165], v[154:157], v[52:55]
	v_mfma_f32_16x16x32_bf16 v[48:51], v[166:169], v[154:157], v[48:51]
	s_waitcnt lgkmcnt(0)
	v_mfma_f32_16x16x32_bf16 v[44:47], v[4:7], v[158:161], v[44:47]
	v_mfma_f32_16x16x32_bf16 v[40:43], v[144:147], v[158:161], v[40:43]
	v_mfma_f32_16x16x32_bf16 v[36:39], v[162:165], v[158:161], v[36:39]
	v_mfma_f32_16x16x32_bf16 v[32:35], v[166:169], v[158:161], v[32:35]
	ds_read_b128 v[154:157], v139 offset:12288
	ds_read_b128 v[158:161], v139 offset:14336
	s_waitcnt vmcnt(0)
	s_waitcnt lgkmcnt(0)
	v_mfma_f32_16x16x32_bf16 v[28:31], v[4:7], v[154:157], v[28:31]
	s_barrier
	v_mfma_f32_16x16x32_bf16 v[24:27], v[144:147], v[154:157], v[24:27]
	v_mfma_f32_16x16x32_bf16 v[20:23], v[162:165], v[154:157], v[20:23]
	v_mfma_f32_16x16x32_bf16 v[16:19], v[166:169], v[154:157], v[16:19]
	v_mfma_f32_16x16x32_bf16 v[12:15], v[4:7], v[158:161], v[12:15]
	v_mfma_f32_16x16x32_bf16 v[4:7], v[144:147], v[158:161], v[8:11]
	v_mfma_f32_16x16x32_bf16 v[8:11], v[162:165], v[158:161], v[140:143]
	v_mfma_f32_16x16x32_bf16 v[0:3], v[166:169], v[158:161], v[0:3]
	s_cbranch_vccz .LBB0_728
	s_add_u32 s24, s44, s24
	s_addc_u32 s25, s45, s25
	s_lshl_b64 s[20:21], s[26:27], 1
	s_add_u32 s22, s22, s20
	s_addc_u32 s23, s23, s21
	s_add_u32 s20, s24, s20
	s_addc_u32 s21, s25, s21
	s_add_i32 s2, s2, 0
	s_mov_b32 m0, s2
	v_mov_b32_e32 v139, v129
	global_load_lds_dwordx4 v128, s[22:23]
	s_add_i32 m0, s2, 0x8000
	v_lshl_add_u64 v[144:145], s[22:23], 0, v[138:139]
	s_add_i32 s2, s53, 0
	global_load_lds_dwordx4 v128, s[20:21]
	v_lshl_add_u64 v[146:147], v[144:145], 0, s[4:5]
	s_mov_b32 m0, s2
	v_lshl_add_u64 v[140:141], s[22:23], 0, v[128:129]
	global_load_lds_dwordx4 v[146:147], off
	v_lshl_add_u64 v[146:147], s[20:21], 0, v[138:139]
	v_lshl_add_u64 v[154:155], v[146:147], 0, s[4:5]
	s_add_i32 m0, s2, 0x8000
	s_add_i32 s2, s52, 0
	v_lshl_add_u64 v[142:143], s[20:21], 0, v[128:129]
	global_load_lds_dwordx4 v[154:155], off
	v_lshl_add_u64 v[140:141], v[140:141], 0, s[6:7]
	s_mov_b32 m0, s2
	s_nop 0
	global_load_lds_dwordx4 v[140:141], off
	v_lshl_add_u64 v[140:141], v[142:143], 0, s[6:7]
	s_add_i32 m0, s2, 0x8000
	s_add_i32 s2, s19, 0
	global_load_lds_dwordx4 v[140:141], off
	v_lshl_add_u64 v[140:141], v[144:145], 0, s[8:9]
	s_mov_b32 m0, s2
	s_nop 0
	global_load_lds_dwordx4 v[140:141], off
	v_lshl_add_u64 v[140:141], v[146:147], 0, s[8:9]
	s_add_i32 m0, s2, 0x8000
	s_nop 0
	global_load_lds_dwordx4 v[140:141], off
	s_branch .LBB0_728

.LBB0_791:
	s_lshr_b32 s46, s45, 1
	s_and_b32 s46, s46, 0x1ffff80
	v_or_b32_e32 v0, s46, v148
	s_and_b32 s45, s45, 0xc0
	v_lshlrev_b32_e32 v139, 7, v0
	v_or_b32_e32 v0, s45, v148
	s_mov_b32 s45, s11
	s_lshl_b64 s[44:45], s[44:45], 16
	s_add_u32 s40, s44, s40
	s_addc_u32 s41, s45, s41
	s_waitcnt vmcnt(0)
	v_lshlrev_b32_e32 v153, 7, v0
	v_lshl_add_u64 v[0:1], s[38:39], 0, v[130:131]
	s_add_u32 s42, s44, s42
	v_lshl_add_u64 v[140:141], v[0:1], 0, s[40:41]
	s_addc_u32 s43, s45, s43
	v_lshl_add_u64 v[0:1], s[38:39], 0, v[134:135]
	v_mov_b32_e32 v88, 0
	v_lshl_add_u64 v[142:143], v[132:133], 0, s[42:43]
	v_lshl_add_u64 v[144:145], v[0:1], 0, s[40:41]
	v_lshl_add_u64 v[146:147], v[136:137], 0, s[42:43]
	s_mov_b64 s[38:39], 0
	s_mov_b32 s40, 0
	v_mov_b32_e32 v89, v88
	v_mov_b32_e32 v90, v88
	v_mov_b32_e32 v91, v88
	v_mov_b32_e32 v104, v88
	v_mov_b32_e32 v105, v88
	v_mov_b32_e32 v106, v88
	v_mov_b32_e32 v107, v88
	v_mov_b32_e32 v0, v88
	v_mov_b32_e32 v1, v88
	v_mov_b32_e32 v2, v88
	v_mov_b32_e32 v3, v88
	v_mov_b32_e32 v4, v88
	v_mov_b32_e32 v5, v88
	v_mov_b32_e32 v6, v88
	v_mov_b32_e32 v7, v88
	v_mov_b32_e32 v8, v88
	v_mov_b32_e32 v9, v88
	v_mov_b32_e32 v10, v88
	v_mov_b32_e32 v11, v88
	v_mov_b32_e32 v12, v88
	v_mov_b32_e32 v13, v88
	v_mov_b32_e32 v14, v88
	v_mov_b32_e32 v15, v88
	v_mov_b32_e32 v16, v88
	v_mov_b32_e32 v17, v88
	v_mov_b32_e32 v18, v88
	v_mov_b32_e32 v19, v88
	v_mov_b32_e32 v20, v88
	v_mov_b32_e32 v21, v88
	v_mov_b32_e32 v22, v88
	v_mov_b32_e32 v23, v88
	v_mov_b32_e32 v24, v88
	v_mov_b32_e32 v25, v88
	v_mov_b32_e32 v26, v88
	v_mov_b32_e32 v27, v88
	v_mov_b32_e32 v28, v88
	v_mov_b32_e32 v29, v88
	v_mov_b32_e32 v30, v88
	v_mov_b32_e32 v31, v88
	v_mov_b32_e32 v32, v88
	v_mov_b32_e32 v33, v88
	v_mov_b32_e32 v34, v88
	v_mov_b32_e32 v35, v88
	v_mov_b32_e32 v36, v88
	v_mov_b32_e32 v37, v88
	v_mov_b32_e32 v38, v88
	v_mov_b32_e32 v39, v88
	v_mov_b32_e32 v40, v88
	v_mov_b32_e32 v41, v88
	v_mov_b32_e32 v42, v88
	v_mov_b32_e32 v43, v88
	v_mov_b32_e32 v44, v88
	v_mov_b32_e32 v45, v88
	v_mov_b32_e32 v46, v88
	v_mov_b32_e32 v47, v88
	v_mov_b32_e32 v48, v88
	v_mov_b32_e32 v49, v88
	v_mov_b32_e32 v50, v88
	v_mov_b32_e32 v51, v88
	v_mov_b32_e32 v52, v88
	v_mov_b32_e32 v53, v88
	v_mov_b32_e32 v54, v88
	v_mov_b32_e32 v55, v88
	v_mov_b32_e32 v56, v88
	v_mov_b32_e32 v57, v88
	v_mov_b32_e32 v58, v88
	v_mov_b32_e32 v59, v88
	v_mov_b32_e32 v60, v88
	v_mov_b32_e32 v61, v88
	v_mov_b32_e32 v62, v88
	v_mov_b32_e32 v63, v88
	v_mov_b32_e32 v64, v88
	v_mov_b32_e32 v65, v88
	v_mov_b32_e32 v66, v88
	v_mov_b32_e32 v67, v88
	v_mov_b32_e32 v68, v88
	v_mov_b32_e32 v69, v88
	v_mov_b32_e32 v70, v88
	v_mov_b32_e32 v71, v88
	v_mov_b32_e32 v72, v88
	v_mov_b32_e32 v73, v88
	v_mov_b32_e32 v74, v88
	v_mov_b32_e32 v75, v88
	v_mov_b32_e32 v76, v88
	v_mov_b32_e32 v77, v88
	v_mov_b32_e32 v78, v88
	v_mov_b32_e32 v79, v88
	v_mov_b32_e32 v80, v88
	v_mov_b32_e32 v81, v88
	v_mov_b32_e32 v82, v88
	v_mov_b32_e32 v83, v88
	v_mov_b32_e32 v84, v88
	v_mov_b32_e32 v85, v88
	v_mov_b32_e32 v86, v88
	v_mov_b32_e32 v87, v88
	v_mov_b32_e32 v92, v88
	v_mov_b32_e32 v93, v88
	v_mov_b32_e32 v94, v88
	v_mov_b32_e32 v95, v88
	v_mov_b32_e32 v96, v88
	v_mov_b32_e32 v97, v88
	v_mov_b32_e32 v98, v88
	v_mov_b32_e32 v99, v88
	v_mov_b32_e32 v100, v88
	v_mov_b32_e32 v101, v88
	v_mov_b32_e32 v102, v88
	v_mov_b32_e32 v103, v88
	v_mov_b32_e32 v108, v88
	v_mov_b32_e32 v109, v88
	v_mov_b32_e32 v110, v88
	v_mov_b32_e32 v111, v88
	v_mov_b32_e32 v112, v88
	v_mov_b32_e32 v113, v88
	v_mov_b32_e32 v114, v88
	v_mov_b32_e32 v115, v88
	v_mov_b32_e32 v116, v88
	v_mov_b32_e32 v117, v88
	v_mov_b32_e32 v118, v88
	v_mov_b32_e32 v119, v88
	v_mov_b32_e32 v120, v88
	v_mov_b32_e32 v121, v88
	v_mov_b32_e32 v122, v88
	v_mov_b32_e32 v123, v88
	v_mov_b32_e32 v124, v88
	v_mov_b32_e32 v125, v88
	v_mov_b32_e32 v126, v88
	v_mov_b32_e32 v127, v88
	s_waitcnt vmcnt(0) lgkmcnt(0)
	s_barrier
	v_bfe_u32 v250, v178, 3, 3
	v_and_b32_e32 v251, 7, v178
	v_lshrrev_b32_e32 v252, 1, v250
	v_xor_b32_e32 v251, v251, v252
	v_lshlrev_b32_e32 v251, 4, v251
	v_lshl_or_b32 v250, v250, 11, v251
	v_xor_b32_e32 v251, 64, v250
	v_add_u32_e32 v251, 0x4000, v251
	v_add_u32_e32 v252, 0x8000, v250
	v_add_u32_e32 v253, 0x8000, v251
	v_lshl_add_u64 v[242:243], v[140:141], 0, s[38:39]
	s_mov_b64 s[40:41], 0x80
	v_lshl_add_u64 v[242:243], v[242:243], 0, s[40:41]
	v_lshl_add_u64 v[244:245], v[142:143], 0, s[38:39]
	s_mov_b64 s[44:45], 0x12000080
	v_lshl_add_u64 v[244:245], v[244:245], 0, s[44:45]
	v_add_u32_e32 v254, v139, v149
	v_add_u32_e32 v255, v153, v149
	v_readfirstlane_b32 s98, v242
	v_readfirstlane_b32 s99, v243
	v_readfirstlane_b32 s100, v244
	v_readfirstlane_b32 s101, v245
	ds_read_b128 v[162:165], v254
	ds_read_b128 v[166:169], v254 offset:2048
	ds_read_b128 v[154:157], v255 offset:32768
	ds_read_b128 v[158:161], v255 offset:34816
	ds_read_b128 v[170:173], v255 offset:36864
	ds_read_b128 v[174:177], v255 offset:38912
	s_nop 4
	s_lshl_b32 m0, s38, 9
	s_and_b32 m0, m0, 0x10000
	s_xor_b32 m0, m0, 0x10000
	s_add_i32 m0, m0, s10
	s_nop 0
	global_load_lds_dwordx4 v250, s[98:99]
	s_add_i32 m0, m0, 0x8000
	s_nop 0
	global_load_lds_dwordx4 v250, s[100:101]
	s_add_i32 m0, m0, 0xffff8400
	s_nop 0
	global_load_lds_dwordx4 v251, s[98:99]
	s_add_i32 m0, m0, 0x8000
	s_nop 0
	global_load_lds_dwordx4 v251, s[100:101]
.LBB0_792:
	ds_read_b128 v[242:245], v254 offset:4096
	ds_read_b128 v[246:249], v254 offset:6144
	s_lshl_b32 m0, s38, 9
	s_and_b32 m0, m0, 0x10000
	s_xor_b32 m0, m0, 0x10000
	s_add_i32 m0, m0, s10
	s_add_i32 m0, m0, 0x800
	s_waitcnt lgkmcnt(5)
	v_mfma_f32_16x16x32_bf16 v[124:127], v[154:157], v[162:165], v[124:127]
	global_load_lds_dwordx4 v252, s[98:99]
	s_add_i32 m0, m0, 0x8000
	v_mfma_f32_16x16x32_bf16 v[108:111], v[154:157], v[166:169], v[108:111]
	s_waitcnt lgkmcnt(4)
	v_mfma_f32_16x16x32_bf16 v[120:123], v[158:161], v[162:165], v[120:123]
	global_load_lds_dwordx4 v252, s[100:101]
	s_add_i32 m0, m0, 0xffff8400
	v_mfma_f32_16x16x32_bf16 v[100:103], v[158:161], v[166:169], v[100:103]
	s_waitcnt lgkmcnt(3)
	v_mfma_f32_16x16x32_bf16 v[116:119], v[170:173], v[162:165], v[116:119]
	global_load_lds_dwordx4 v253, s[98:99]
	s_add_i32 m0, m0, 0x8000
	v_mfma_f32_16x16x32_bf16 v[96:99], v[170:173], v[166:169], v[96:99]
	s_waitcnt lgkmcnt(2)
	v_mfma_f32_16x16x32_bf16 v[112:115], v[174:177], v[162:165], v[112:115]
	global_load_lds_dwordx4 v253, s[100:101]
	v_mfma_f32_16x16x32_bf16 v[92:95], v[174:177], v[166:169], v[92:95]
	s_add_u32 s98, s98, 0x80
	s_addc_u32 s99, s99, 0
	s_add_u32 s100, s100, 0x80
	s_addc_u32 s101, s101, 0
	ds_read_b128 v[162:165], v254 offset:8192
	ds_read_b128 v[166:169], v254 offset:10240
	s_waitcnt lgkmcnt(2)
	v_mfma_f32_16x16x32_bf16 v[84:87], v[154:157], v[242:245], v[84:87]
	s_add_i32 s42, s40, 0x10000
	v_mfma_f32_16x16x32_bf16 v[68:71], v[154:157], v[246:249], v[68:71]
	s_and_b32 s43, s40, 0x10000
	v_mfma_f32_16x16x32_bf16 v[80:83], v[158:161], v[242:245], v[80:83]
	s_mov_b64 s[40:41], 0x80
	v_mfma_f32_16x16x32_bf16 v[64:67], v[158:161], v[246:249], v[64:67]
	s_and_b32 s46, s42, 0x10000
	v_mfma_f32_16x16x32_bf16 v[76:79], v[170:173], v[242:245], v[76:79]
	s_add_i32 s40, s43, 0
	v_mfma_f32_16x16x32_bf16 v[60:63], v[170:173], v[246:249], v[60:63]
	s_add_i32 s41, s46, 0
	v_mfma_f32_16x16x32_bf16 v[72:75], v[174:177], v[242:245], v[72:75]
	s_add_i32 s40, s41, s10
	v_mfma_f32_16x16x32_bf16 v[56:59], v[174:177], v[246:249], v[56:59]
	s_mov_b64 s[44:45], 0x12000080
	s_add_i32 s43, s41, s51
	s_add_i32 s44, s41, s50
	s_add_i32 s45, s41, s37
	s_add_u32 s38, s38, 0x80
	s_addc_u32 s39, s39, 0
	s_mov_b32 s40, s42
	s_cmpk_eq_i32 s38, 0x780
	ds_read_b128 v[242:245], v254 offset:12288
	ds_read_b128 v[246:249], v254 offset:14336
	s_waitcnt lgkmcnt(2)
	v_mfma_f32_16x16x32_bf16 v[52:55], v[154:157], v[162:165], v[52:55]
	v_mfma_f32_16x16x32_bf16 v[36:39], v[154:157], v[166:169], v[36:39]
	v_mfma_f32_16x16x32_bf16 v[48:51], v[158:161], v[162:165], v[48:51]
	v_mfma_f32_16x16x32_bf16 v[32:35], v[158:161], v[166:169], v[32:35]
	v_mfma_f32_16x16x32_bf16 v[44:47], v[170:173], v[162:165], v[44:47]
	v_mfma_f32_16x16x32_bf16 v[28:31], v[170:173], v[166:169], v[28:31]
	v_mfma_f32_16x16x32_bf16 v[40:43], v[174:177], v[162:165], v[40:43]
	v_mfma_f32_16x16x32_bf16 v[24:27], v[174:177], v[166:169], v[24:27]
	v_xor_b32_e32 v254, 64, v254
	v_xor_b32_e32 v255, 64, v255
	ds_read_b128 v[162:165], v254
	ds_read_b128 v[166:169], v254 offset:2048
	s_waitcnt lgkmcnt(2)
	v_mfma_f32_16x16x32_bf16 v[20:23], v[154:157], v[242:245], v[20:23]
	v_mfma_f32_16x16x32_bf16 v[4:7], v[154:157], v[246:249], v[4:7]
	ds_read_b128 v[154:157], v255 offset:32768
	v_mfma_f32_16x16x32_bf16 v[16:19], v[158:161], v[242:245], v[16:19]
	v_mfma_f32_16x16x32_bf16 v[0:3], v[158:161], v[246:249], v[0:3]
	ds_read_b128 v[158:161], v255 offset:34816
	v_mfma_f32_16x16x32_bf16 v[12:15], v[170:173], v[242:245], v[12:15]
	v_mfma_f32_16x16x32_bf16 v[104:107], v[170:173], v[246:249], v[104:107]
	ds_read_b128 v[170:173], v255 offset:36864
	v_mfma_f32_16x16x32_bf16 v[8:11], v[174:177], v[242:245], v[8:11]
	v_mfma_f32_16x16x32_bf16 v[88:91], v[174:177], v[246:249], v[88:91]
	ds_read_b128 v[174:177], v255 offset:38912
	ds_read_b128 v[242:245], v254 offset:4096
	ds_read_b128 v[246:249], v254 offset:6144
	s_waitcnt lgkmcnt(5)
	v_mfma_f32_16x16x32_bf16 v[124:127], v[154:157], v[162:165], v[124:127]
	v_mfma_f32_16x16x32_bf16 v[108:111], v[154:157], v[166:169], v[108:111]
	s_waitcnt lgkmcnt(4)
	v_mfma_f32_16x16x32_bf16 v[120:123], v[158:161], v[162:165], v[120:123]
	v_mfma_f32_16x16x32_bf16 v[100:103], v[158:161], v[166:169], v[100:103]
	s_waitcnt lgkmcnt(3)
	v_mfma_f32_16x16x32_bf16 v[116:119], v[170:173], v[162:165], v[116:119]
	v_mfma_f32_16x16x32_bf16 v[96:99], v[170:173], v[166:169], v[96:99]
	s_waitcnt lgkmcnt(2)
	v_mfma_f32_16x16x32_bf16 v[112:115], v[174:177], v[162:165], v[112:115]
	v_mfma_f32_16x16x32_bf16 v[92:95], v[174:177], v[166:169], v[92:95]
	ds_read_b128 v[162:165], v254 offset:8192
	ds_read_b128 v[166:169], v254 offset:10240
	s_waitcnt lgkmcnt(2)
	v_mfma_f32_16x16x32_bf16 v[84:87], v[154:157], v[242:245], v[84:87]
	v_mfma_f32_16x16x32_bf16 v[68:71], v[154:157], v[246:249], v[68:71]
	v_mfma_f32_16x16x32_bf16 v[80:83], v[158:161], v[242:245], v[80:83]
	v_mfma_f32_16x16x32_bf16 v[64:67], v[158:161], v[246:249], v[64:67]
	v_mfma_f32_16x16x32_bf16 v[76:79], v[170:173], v[242:245], v[76:79]
	v_mfma_f32_16x16x32_bf16 v[60:63], v[170:173], v[246:249], v[60:63]
	v_mfma_f32_16x16x32_bf16 v[72:75], v[174:177], v[242:245], v[72:75]
	v_mfma_f32_16x16x32_bf16 v[56:59], v[174:177], v[246:249], v[56:59]
	ds_read_b128 v[242:245], v254 offset:12288
	ds_read_b128 v[246:249], v254 offset:14336
	s_waitcnt lgkmcnt(2)
	v_mfma_f32_16x16x32_bf16 v[52:55], v[154:157], v[162:165], v[52:55]
	v_mfma_f32_16x16x32_bf16 v[36:39], v[154:157], v[166:169], v[36:39]
	v_mfma_f32_16x16x32_bf16 v[48:51], v[158:161], v[162:165], v[48:51]
	v_mfma_f32_16x16x32_bf16 v[32:35], v[158:161], v[166:169], v[32:35]
	v_mfma_f32_16x16x32_bf16 v[44:47], v[170:173], v[162:165], v[44:47]
	v_mfma_f32_16x16x32_bf16 v[28:31], v[170:173], v[166:169], v[28:31]
	v_mfma_f32_16x16x32_bf16 v[40:43], v[174:177], v[162:165], v[40:43]
	v_mfma_f32_16x16x32_bf16 v[24:27], v[174:177], v[166:169], v[24:27]
	s_waitcnt vmcnt(0) lgkmcnt(0)
	s_barrier
	s_cmpk_eq_i32 s38, 0x780
	s_cbranch_scc1 .Lgx_792
	v_xor_b32_e32 v254, 0x10040, v254
	v_xor_b32_e32 v255, 0x10040, v255
	ds_read_b128 v[162:165], v254
	ds_read_b128 v[166:169], v254 offset:2048
	s_lshl_b32 m0, s38, 9
	s_and_b32 m0, m0, 0x10000
	s_xor_b32 m0, m0, 0x10000
	s_add_i32 m0, m0, s10
	v_mfma_f32_16x16x32_bf16 v[20:23], v[154:157], v[242:245], v[20:23]
	global_load_lds_dwordx4 v250, s[98:99]
	s_add_i32 m0, m0, 0x8000
	v_mfma_f32_16x16x32_bf16 v[4:7], v[154:157], v[246:249], v[4:7]
	ds_read_b128 v[154:157], v255 offset:32768
	v_mfma_f32_16x16x32_bf16 v[16:19], v[158:161], v[242:245], v[16:19]
	global_load_lds_dwordx4 v250, s[100:101]
	s_add_i32 m0, m0, 0xffff8400
	v_mfma_f32_16x16x32_bf16 v[0:3], v[158:161], v[246:249], v[0:3]
	ds_read_b128 v[158:161], v255 offset:34816
	v_mfma_f32_16x16x32_bf16 v[12:15], v[170:173], v[242:245], v[12:15]
	global_load_lds_dwordx4 v251, s[98:99]
	s_add_i32 m0, m0, 0x8000
	v_mfma_f32_16x16x32_bf16 v[104:107], v[170:173], v[246:249], v[104:107]
	ds_read_b128 v[170:173], v255 offset:36864
	v_mfma_f32_16x16x32_bf16 v[8:11], v[174:177], v[242:245], v[8:11]
	global_load_lds_dwordx4 v251, s[100:101]
	v_mfma_f32_16x16x32_bf16 v[88:91], v[174:177], v[246:249], v[88:91]
	ds_read_b128 v[174:177], v255 offset:38912
	s_branch .LBB0_792
.Lgx_792:
	v_mfma_f32_16x16x32_bf16 v[20:23], v[154:157], v[242:245], v[20:23]
	v_mfma_f32_16x16x32_bf16 v[4:7], v[154:157], v[246:249], v[4:7]
	v_mfma_f32_16x16x32_bf16 v[16:19], v[158:161], v[242:245], v[16:19]
	v_mfma_f32_16x16x32_bf16 v[0:3], v[158:161], v[246:249], v[0:3]
	v_mfma_f32_16x16x32_bf16 v[12:15], v[170:173], v[242:245], v[12:15]
	v_mfma_f32_16x16x32_bf16 v[104:107], v[170:173], v[246:249], v[104:107]
	v_mfma_f32_16x16x32_bf16 v[8:11], v[174:177], v[242:245], v[8:11]
	v_mfma_f32_16x16x32_bf16 v[88:91], v[174:177], v[246:249], v[88:91]
	v_add_u32_e32 v153, s41, v153
	v_add_u32_e32 v166, v153, v149
	v_add_u32_e32 v139, s41, v139
	ds_read_b128 v[140:143], v166 offset:32768
	v_add_u32_e32 v170, v139, v149
	ds_read_b128 v[144:147], v166 offset:34816
	ds_read_b128 v[154:157], v170
	ds_read_b128 v[158:161], v170 offset:2048
	ds_read_b128 v[162:165], v166 offset:36864
	ds_read_b128 v[166:169], v166 offset:38912
	s_waitcnt lgkmcnt(3)
	v_mfma_f32_16x16x32_bf16 v[120:123], v[144:147], v[154:157], v[120:123]
	v_add_u32_e32 v139, v139, v150
	s_and_b64 vcc, exec, s[2:3]
	v_mfma_f32_16x16x32_bf16 v[124:127], v[140:143], v[154:157], v[124:127]
	s_waitcnt lgkmcnt(1)
	v_mfma_f32_16x16x32_bf16 v[116:119], v[162:165], v[154:157], v[116:119]
	s_waitcnt lgkmcnt(0)
	v_mfma_f32_16x16x32_bf16 v[112:115], v[166:169], v[154:157], v[112:115]
	v_mfma_f32_16x16x32_bf16 v[108:111], v[140:143], v[158:161], v[108:111]
	v_mfma_f32_16x16x32_bf16 v[100:103], v[144:147], v[158:161], v[100:103]
	v_mfma_f32_16x16x32_bf16 v[96:99], v[162:165], v[158:161], v[96:99]
	v_mfma_f32_16x16x32_bf16 v[92:95], v[166:169], v[158:161], v[92:95]
	ds_read_b128 v[154:157], v170 offset:4096
	ds_read_b128 v[158:161], v170 offset:6144
	s_waitcnt lgkmcnt(1)
	v_mfma_f32_16x16x32_bf16 v[84:87], v[140:143], v[154:157], v[84:87]
	v_mfma_f32_16x16x32_bf16 v[80:83], v[144:147], v[154:157], v[80:83]
	v_mfma_f32_16x16x32_bf16 v[76:79], v[162:165], v[154:157], v[76:79]
	v_mfma_f32_16x16x32_bf16 v[72:75], v[166:169], v[154:157], v[72:75]
	s_waitcnt lgkmcnt(0)
	v_mfma_f32_16x16x32_bf16 v[68:71], v[140:143], v[158:161], v[68:71]
	v_mfma_f32_16x16x32_bf16 v[64:67], v[144:147], v[158:161], v[64:67]
	v_mfma_f32_16x16x32_bf16 v[60:63], v[162:165], v[158:161], v[60:63]
	v_mfma_f32_16x16x32_bf16 v[56:59], v[166:169], v[158:161], v[56:59]
	ds_read_b128 v[154:157], v170 offset:8192
	ds_read_b128 v[158:161], v170 offset:10240
	s_waitcnt lgkmcnt(1)
	v_mfma_f32_16x16x32_bf16 v[52:55], v[140:143], v[154:157], v[52:55]
	v_mfma_f32_16x16x32_bf16 v[48:51], v[144:147], v[154:157], v[48:51]
	v_mfma_f32_16x16x32_bf16 v[44:47], v[162:165], v[154:157], v[44:47]
	v_mfma_f32_16x16x32_bf16 v[40:43], v[166:169], v[154:157], v[40:43]
	s_waitcnt lgkmcnt(0)
	v_mfma_f32_16x16x32_bf16 v[36:39], v[140:143], v[158:161], v[36:39]
	v_mfma_f32_16x16x32_bf16 v[32:35], v[144:147], v[158:161], v[32:35]
	v_mfma_f32_16x16x32_bf16 v[28:31], v[162:165], v[158:161], v[28:31]
	v_mfma_f32_16x16x32_bf16 v[24:27], v[166:169], v[158:161], v[24:27]
	ds_read_b128 v[154:157], v170 offset:12288
	ds_read_b128 v[158:161], v170 offset:14336
	s_waitcnt lgkmcnt(1)
	v_mfma_f32_16x16x32_bf16 v[20:23], v[140:143], v[154:157], v[20:23]
	s_waitcnt lgkmcnt(0)
	v_mfma_f32_16x16x32_bf16 v[4:7], v[140:143], v[158:161], v[4:7]
	v_mfma_f32_16x16x32_bf16 v[140:143], v[162:165], v[158:161], v[104:107]
	s_nop 2
	v_add_u32_e32 v104, v153, v150
	v_mfma_f32_16x16x32_bf16 v[16:19], v[144:147], v[154:157], v[16:19]
	v_mfma_f32_16x16x32_bf16 v[12:15], v[162:165], v[154:157], v[12:15]
	v_mfma_f32_16x16x32_bf16 v[8:11], v[166:169], v[154:157], v[8:11]
	v_mfma_f32_16x16x32_bf16 v[0:3], v[144:147], v[158:161], v[0:3]
	ds_read_b128 v[144:147], v104 offset:32768
	v_mfma_f32_16x16x32_bf16 v[154:157], v[166:169], v[158:161], v[88:91]
	ds_read_b128 v[158:161], v104 offset:34816
	s_nop 1
	ds_read_b128 v[88:91], v139
	ds_read_b128 v[162:165], v139 offset:2048
	ds_read_b128 v[166:169], v104 offset:36864
	ds_read_b128 v[170:173], v104 offset:38912
	s_waitcnt lgkmcnt(2)
	v_mfma_f32_16x16x32_bf16 v[108:111], v[144:147], v[162:165], v[108:111]
	v_mfma_f32_16x16x32_bf16 v[104:107], v[158:161], v[162:165], v[100:103]
	s_waitcnt lgkmcnt(1)
	v_mfma_f32_16x16x32_bf16 v[100:103], v[166:169], v[162:165], v[96:99]
	s_waitcnt lgkmcnt(0)
	v_mfma_f32_16x16x32_bf16 v[96:99], v[170:173], v[162:165], v[92:95]
	ds_read_b128 v[162:165], v139 offset:4096
	ds_read_b128 v[174:177], v139 offset:6144
	v_mfma_f32_16x16x32_bf16 v[124:127], v[144:147], v[88:91], v[124:127]
	v_mfma_f32_16x16x32_bf16 v[120:123], v[158:161], v[88:91], v[120:123]
	v_mfma_f32_16x16x32_bf16 v[116:119], v[166:169], v[88:91], v[116:119]
	v_mfma_f32_16x16x32_bf16 v[112:115], v[170:173], v[88:91], v[112:115]
	s_waitcnt lgkmcnt(1)
	v_mfma_f32_16x16x32_bf16 v[92:95], v[144:147], v[162:165], v[84:87]
	v_mfma_f32_16x16x32_bf16 v[88:91], v[158:161], v[162:165], v[80:83]
	v_mfma_f32_16x16x32_bf16 v[84:87], v[166:169], v[162:165], v[76:79]
	v_mfma_f32_16x16x32_bf16 v[80:83], v[170:173], v[162:165], v[72:75]
	s_waitcnt lgkmcnt(0)
	v_mfma_f32_16x16x32_bf16 v[76:79], v[144:147], v[174:177], v[68:71]
	v_mfma_f32_16x16x32_bf16 v[72:75], v[158:161], v[174:177], v[64:67]
	v_mfma_f32_16x16x32_bf16 v[68:71], v[166:169], v[174:177], v[60:63]
	v_mfma_f32_16x16x32_bf16 v[64:67], v[170:173], v[174:177], v[56:59]
	ds_read_b128 v[162:165], v139 offset:8192
	ds_read_b128 v[174:177], v139 offset:10240
	s_waitcnt lgkmcnt(1)
	v_mfma_f32_16x16x32_bf16 v[60:63], v[144:147], v[162:165], v[52:55]
	v_mfma_f32_16x16x32_bf16 v[56:59], v[158:161], v[162:165], v[48:51]
	v_mfma_f32_16x16x32_bf16 v[52:55], v[166:169], v[162:165], v[44:47]
	v_mfma_f32_16x16x32_bf16 v[48:51], v[170:173], v[162:165], v[40:43]
	s_waitcnt lgkmcnt(0)
	v_mfma_f32_16x16x32_bf16 v[44:47], v[144:147], v[174:177], v[36:39]
	v_mfma_f32_16x16x32_bf16 v[40:43], v[158:161], v[174:177], v[32:35]
	v_mfma_f32_16x16x32_bf16 v[36:39], v[166:169], v[174:177], v[28:31]
	v_mfma_f32_16x16x32_bf16 v[32:35], v[170:173], v[174:177], v[24:27]
	ds_read_b128 v[162:165], v139 offset:12288
	ds_read_b128 v[174:177], v139 offset:14336
	s_waitcnt vmcnt(0)
	s_waitcnt lgkmcnt(0)
	v_mfma_f32_16x16x32_bf16 v[28:31], v[144:147], v[162:165], v[20:23]
	s_barrier
	v_mfma_f32_16x16x32_bf16 v[24:27], v[158:161], v[162:165], v[16:19]
	v_mfma_f32_16x16x32_bf16 v[20:23], v[166:169], v[162:165], v[12:15]
	v_mfma_f32_16x16x32_bf16 v[16:19], v[170:173], v[162:165], v[8:11]
	v_mfma_f32_16x16x32_bf16 v[12:15], v[144:147], v[174:177], v[4:7]
	v_mfma_f32_16x16x32_bf16 v[8:11], v[158:161], v[174:177], v[0:3]
	v_mfma_f32_16x16x32_bf16 v[4:7], v[166:169], v[174:177], v[140:143]
	v_mfma_f32_16x16x32_bf16 v[0:3], v[170:173], v[174:177], v[154:157]
	s_cbranch_vccz .LBB0_795
	s_add_u32 s6, s56, s6
	s_addc_u32 s7, s57, s7
	s_lshl_b64 s[2:3], s[8:9], 1
	s_add_u32 s4, s4, s2
	s_addc_u32 s5, s5, s3
	s_add_u32 s2, s6, s2
	s_addc_u32 s3, s7, s3
	s_add_i32 s6, s10, 0
	s_mov_b32 m0, s6
	v_mov_b32_e32 v139, v129
	v_lshl_add_u64 v[140:141], s[4:5], 0, v[128:129]
	global_load_lds_dwordx4 v128, s[4:5]
	s_add_i32 m0, s6, 0x8000
	v_lshl_add_u64 v[144:145], s[4:5], 0, v[138:139]
	s_add_i32 s4, s51, 0
	global_load_lds_dwordx4 v128, s[2:3]
	v_lshl_add_u64 v[146:147], v[144:145], 0, s[12:13]
	s_mov_b32 m0, s4
	v_lshl_add_u64 v[142:143], s[2:3], 0, v[128:129]
	global_load_lds_dwordx4 v[146:147], off
	v_lshl_add_u64 v[146:147], s[2:3], 0, v[138:139]
	v_lshl_add_u64 v[154:155], v[146:147], 0, s[12:13]
	s_add_i32 m0, s4, 0x8000
	s_add_i32 s2, s50, 0
	global_load_lds_dwordx4 v[154:155], off
	v_lshl_add_u64 v[140:141], v[140:141], 0, s[14:15]
	s_mov_b32 m0, s2
	s_nop 0
	global_load_lds_dwordx4 v[140:141], off
	v_lshl_add_u64 v[140:141], v[142:143], 0, s[14:15]
	s_add_i32 m0, s2, 0x8000
	s_add_i32 s2, s37, 0
	global_load_lds_dwordx4 v[140:141], off
	v_lshl_add_u64 v[140:141], v[144:145], 0, s[16:17]
	s_mov_b32 m0, s2
	s_nop 0
	global_load_lds_dwordx4 v[140:141], off
	v_lshl_add_u64 v[140:141], v[146:147], 0, s[16:17]
	s_add_i32 m0, s2, 0x8000
	s_nop 0
	global_load_lds_dwordx4 v[140:141], off

.LBB0_1139:
	s_lshr_b32 s48, s47, 1
	s_and_b32 s48, s48, 0x1ffff80
	v_or_b32_e32 v0, s48, v148
	s_and_b32 s47, s47, 0xc0
	v_lshlrev_b32_e32 v139, 7, v0
	v_or_b32_e32 v0, s47, v148
	s_mov_b32 s47, s3
	s_lshl_b64 s[46:47], s[46:47], 16
	s_add_u32 s42, s46, s42
	s_addc_u32 s43, s47, s43
	s_waitcnt vmcnt(0)
	v_lshlrev_b32_e32 v153, 7, v0
	v_lshl_add_u64 v[0:1], s[40:41], 0, v[130:131]
	s_add_u32 s44, s46, s44
	v_lshl_add_u64 v[140:141], v[0:1], 0, s[42:43]
	s_addc_u32 s45, s47, s45
	v_lshl_add_u64 v[0:1], s[40:41], 0, v[134:135]
	v_mov_b32_e32 v88, 0
	v_lshl_add_u64 v[142:143], v[132:133], 0, s[44:45]
	v_lshl_add_u64 v[144:145], v[0:1], 0, s[42:43]
	v_lshl_add_u64 v[146:147], v[136:137], 0, s[44:45]
	s_mov_b64 s[40:41], 0
	s_mov_b32 s42, 0
	v_mov_b32_e32 v89, v88
	v_mov_b32_e32 v90, v88
	v_mov_b32_e32 v91, v88
	v_mov_b32_e32 v104, v88
	v_mov_b32_e32 v105, v88
	v_mov_b32_e32 v106, v88
	v_mov_b32_e32 v107, v88
	v_mov_b32_e32 v0, v88
	v_mov_b32_e32 v1, v88
	v_mov_b32_e32 v2, v88
	v_mov_b32_e32 v3, v88
	v_mov_b32_e32 v4, v88
	v_mov_b32_e32 v5, v88
	v_mov_b32_e32 v6, v88
	v_mov_b32_e32 v7, v88
	v_mov_b32_e32 v8, v88
	v_mov_b32_e32 v9, v88
	v_mov_b32_e32 v10, v88
	v_mov_b32_e32 v11, v88
	v_mov_b32_e32 v12, v88
	v_mov_b32_e32 v13, v88
	v_mov_b32_e32 v14, v88
	v_mov_b32_e32 v15, v88
	v_mov_b32_e32 v16, v88
	v_mov_b32_e32 v17, v88
	v_mov_b32_e32 v18, v88
	v_mov_b32_e32 v19, v88
	v_mov_b32_e32 v20, v88
	v_mov_b32_e32 v21, v88
	v_mov_b32_e32 v22, v88
	v_mov_b32_e32 v23, v88
	v_mov_b32_e32 v24, v88
	v_mov_b32_e32 v25, v88
	v_mov_b32_e32 v26, v88
	v_mov_b32_e32 v27, v88
	v_mov_b32_e32 v28, v88
	v_mov_b32_e32 v29, v88
	v_mov_b32_e32 v30, v88
	v_mov_b32_e32 v31, v88
	v_mov_b32_e32 v32, v88
	v_mov_b32_e32 v33, v88
	v_mov_b32_e32 v34, v88
	v_mov_b32_e32 v35, v88
	v_mov_b32_e32 v36, v88
	v_mov_b32_e32 v37, v88
	v_mov_b32_e32 v38, v88
	v_mov_b32_e32 v39, v88
	v_mov_b32_e32 v40, v88
	v_mov_b32_e32 v41, v88
	v_mov_b32_e32 v42, v88
	v_mov_b32_e32 v43, v88
	v_mov_b32_e32 v44, v88
	v_mov_b32_e32 v45, v88
	v_mov_b32_e32 v46, v88
	v_mov_b32_e32 v47, v88
	v_mov_b32_e32 v48, v88
	v_mov_b32_e32 v49, v88
	v_mov_b32_e32 v50, v88
	v_mov_b32_e32 v51, v88
	v_mov_b32_e32 v52, v88
	v_mov_b32_e32 v53, v88
	v_mov_b32_e32 v54, v88
	v_mov_b32_e32 v55, v88
	v_mov_b32_e32 v56, v88
	v_mov_b32_e32 v57, v88
	v_mov_b32_e32 v58, v88
	v_mov_b32_e32 v59, v88
	v_mov_b32_e32 v60, v88
	v_mov_b32_e32 v61, v88
	v_mov_b32_e32 v62, v88
	v_mov_b32_e32 v63, v88
	v_mov_b32_e32 v64, v88
	v_mov_b32_e32 v65, v88
	v_mov_b32_e32 v66, v88
	v_mov_b32_e32 v67, v88
	v_mov_b32_e32 v68, v88
	v_mov_b32_e32 v69, v88
	v_mov_b32_e32 v70, v88
	v_mov_b32_e32 v71, v88
	v_mov_b32_e32 v72, v88
	v_mov_b32_e32 v73, v88
	v_mov_b32_e32 v74, v88
	v_mov_b32_e32 v75, v88
	v_mov_b32_e32 v76, v88
	v_mov_b32_e32 v77, v88
	v_mov_b32_e32 v78, v88
	v_mov_b32_e32 v79, v88
	v_mov_b32_e32 v80, v88
	v_mov_b32_e32 v81, v88
	v_mov_b32_e32 v82, v88
	v_mov_b32_e32 v83, v88
	v_mov_b32_e32 v84, v88
	v_mov_b32_e32 v85, v88
	v_mov_b32_e32 v86, v88
	v_mov_b32_e32 v87, v88
	v_mov_b32_e32 v92, v88
	v_mov_b32_e32 v93, v88
	v_mov_b32_e32 v94, v88
	v_mov_b32_e32 v95, v88
	v_mov_b32_e32 v96, v88
	v_mov_b32_e32 v97, v88
	v_mov_b32_e32 v98, v88
	v_mov_b32_e32 v99, v88
	v_mov_b32_e32 v100, v88
	v_mov_b32_e32 v101, v88
	v_mov_b32_e32 v102, v88
	v_mov_b32_e32 v103, v88
	v_mov_b32_e32 v108, v88
	v_mov_b32_e32 v109, v88
	v_mov_b32_e32 v110, v88
	v_mov_b32_e32 v111, v88
	v_mov_b32_e32 v112, v88
	v_mov_b32_e32 v113, v88
	v_mov_b32_e32 v114, v88
	v_mov_b32_e32 v115, v88
	v_mov_b32_e32 v116, v88
	v_mov_b32_e32 v117, v88
	v_mov_b32_e32 v118, v88
	v_mov_b32_e32 v119, v88
	v_mov_b32_e32 v120, v88
	v_mov_b32_e32 v121, v88
	v_mov_b32_e32 v122, v88
	v_mov_b32_e32 v123, v88
	v_mov_b32_e32 v124, v88
	v_mov_b32_e32 v125, v88
	v_mov_b32_e32 v126, v88
	v_mov_b32_e32 v127, v88
	s_waitcnt vmcnt(0) lgkmcnt(0)
	s_barrier
	v_bfe_u32 v250, v178, 3, 3
	v_and_b32_e32 v251, 7, v178
	v_lshrrev_b32_e32 v252, 1, v250
	v_xor_b32_e32 v251, v251, v252
	v_lshlrev_b32_e32 v251, 4, v251
	v_lshl_or_b32 v250, v250, 11, v251
	v_xor_b32_e32 v251, 64, v250
	v_add_u32_e32 v251, 0x4000, v251
	v_add_u32_e32 v252, 0x8000, v250
	v_add_u32_e32 v253, 0x8000, v251
	v_lshl_add_u64 v[242:243], v[140:141], 0, s[40:41]
	v_lshl_add_u64 v[242:243], v[242:243], 0, s[10:11]
	v_lshl_add_u64 v[244:245], v[142:143], 0, s[40:41]
	v_lshl_add_u64 v[244:245], v[244:245], 0, s[12:13]
	v_add_u32_e32 v254, v139, v149
	v_add_u32_e32 v255, v153, v149
	v_readfirstlane_b32 s98, v242
	v_readfirstlane_b32 s99, v243
	v_readfirstlane_b32 s100, v244
	v_readfirstlane_b32 s101, v245
	ds_read_b128 v[162:165], v254
	ds_read_b128 v[166:169], v254 offset:2048
	ds_read_b128 v[154:157], v255 offset:32768
	ds_read_b128 v[158:161], v255 offset:34816
	ds_read_b128 v[170:173], v255 offset:36864
	ds_read_b128 v[174:177], v255 offset:38912
	s_nop 4
	s_lshl_b32 m0, s40, 9
	s_and_b32 m0, m0, 0x10000
	s_xor_b32 m0, m0, 0x10000
	s_add_i32 m0, m0, s2
	s_nop 0
	global_load_lds_dwordx4 v250, s[98:99]
	s_add_i32 m0, m0, 0x8000
	s_nop 0
	global_load_lds_dwordx4 v250, s[100:101]
	s_add_i32 m0, m0, 0xffff8400
	s_nop 0
	global_load_lds_dwordx4 v251, s[98:99]
	s_add_i32 m0, m0, 0x8000
	s_nop 0
	global_load_lds_dwordx4 v251, s[100:101]
.LBB0_1140:
	ds_read_b128 v[242:245], v254 offset:4096
	ds_read_b128 v[246:249], v254 offset:6144
	s_lshl_b32 m0, s40, 9
	s_and_b32 m0, m0, 0x10000
	s_xor_b32 m0, m0, 0x10000
	s_add_i32 m0, m0, s2
	s_add_i32 m0, m0, 0x800
	s_waitcnt lgkmcnt(5)
	v_mfma_f32_16x16x32_bf16 v[124:127], v[154:157], v[162:165], v[124:127]
	global_load_lds_dwordx4 v252, s[98:99]
	s_add_i32 m0, m0, 0x8000
	v_mfma_f32_16x16x32_bf16 v[108:111], v[154:157], v[166:169], v[108:111]
	s_waitcnt lgkmcnt(4)
	v_mfma_f32_16x16x32_bf16 v[120:123], v[158:161], v[162:165], v[120:123]
	global_load_lds_dwordx4 v252, s[100:101]
	s_add_i32 m0, m0, 0xffff8400
	v_mfma_f32_16x16x32_bf16 v[100:103], v[158:161], v[166:169], v[100:103]
	s_waitcnt lgkmcnt(3)
	v_mfma_f32_16x16x32_bf16 v[116:119], v[170:173], v[162:165], v[116:119]
	global_load_lds_dwordx4 v253, s[98:99]
	s_add_i32 m0, m0, 0x8000
	v_mfma_f32_16x16x32_bf16 v[96:99], v[170:173], v[166:169], v[96:99]
	s_waitcnt lgkmcnt(2)
	v_mfma_f32_16x16x32_bf16 v[112:115], v[174:177], v[162:165], v[112:115]
	global_load_lds_dwordx4 v253, s[100:101]
	v_mfma_f32_16x16x32_bf16 v[92:95], v[174:177], v[166:169], v[92:95]
	s_add_u32 s98, s98, 0x80
	s_addc_u32 s99, s99, 0
	s_add_u32 s100, s100, 0x80
	s_addc_u32 s101, s101, 0
	ds_read_b128 v[162:165], v254 offset:8192
	ds_read_b128 v[166:169], v254 offset:10240
	s_waitcnt lgkmcnt(2)
	v_mfma_f32_16x16x32_bf16 v[84:87], v[154:157], v[242:245], v[84:87]
	s_add_i32 s44, s42, 0x10000
	v_mfma_f32_16x16x32_bf16 v[68:71], v[154:157], v[246:249], v[68:71]
	s_and_b32 s42, s42, 0x10000
	v_mfma_f32_16x16x32_bf16 v[80:83], v[158:161], v[242:245], v[80:83]
	s_and_b32 s43, s44, 0x10000
	v_mfma_f32_16x16x32_bf16 v[64:67], v[158:161], v[246:249], v[64:67]
	s_add_i32 s42, s42, 0
	v_mfma_f32_16x16x32_bf16 v[76:79], v[170:173], v[242:245], v[76:79]
	s_add_i32 s43, s43, 0
	v_mfma_f32_16x16x32_bf16 v[60:63], v[170:173], v[246:249], v[60:63]
	s_add_i32 s42, s43, s2
	v_mfma_f32_16x16x32_bf16 v[72:75], v[174:177], v[242:245], v[72:75]
	s_add_i32 s45, s43, s53
	v_mfma_f32_16x16x32_bf16 v[56:59], v[174:177], v[246:249], v[56:59]
	s_add_i32 s46, s43, s52
	s_add_i32 s47, s43, s29
	s_add_u32 s40, s40, 0x80
	s_addc_u32 s41, s41, 0
	s_mov_b32 s42, s44
	s_cmpk_eq_i32 s40, 0x780
	ds_read_b128 v[242:245], v254 offset:12288
	ds_read_b128 v[246:249], v254 offset:14336
	s_waitcnt lgkmcnt(2)
	v_mfma_f32_16x16x32_bf16 v[52:55], v[154:157], v[162:165], v[52:55]
	v_mfma_f32_16x16x32_bf16 v[36:39], v[154:157], v[166:169], v[36:39]
	v_mfma_f32_16x16x32_bf16 v[48:51], v[158:161], v[162:165], v[48:51]
	v_mfma_f32_16x16x32_bf16 v[32:35], v[158:161], v[166:169], v[32:35]
	v_mfma_f32_16x16x32_bf16 v[44:47], v[170:173], v[162:165], v[44:47]
	v_mfma_f32_16x16x32_bf16 v[28:31], v[170:173], v[166:169], v[28:31]
	v_mfma_f32_16x16x32_bf16 v[40:43], v[174:177], v[162:165], v[40:43]
	v_mfma_f32_16x16x32_bf16 v[24:27], v[174:177], v[166:169], v[24:27]
	v_xor_b32_e32 v254, 64, v254
	v_xor_b32_e32 v255, 64, v255
	ds_read_b128 v[162:165], v254
	ds_read_b128 v[166:169], v254 offset:2048
	s_waitcnt lgkmcnt(2)
	v_mfma_f32_16x16x32_bf16 v[20:23], v[154:157], v[242:245], v[20:23]
	v_mfma_f32_16x16x32_bf16 v[4:7], v[154:157], v[246:249], v[4:7]
	ds_read_b128 v[154:157], v255 offset:32768
	v_mfma_f32_16x16x32_bf16 v[16:19], v[158:161], v[242:245], v[16:19]
	v_mfma_f32_16x16x32_bf16 v[0:3], v[158:161], v[246:249], v[0:3]
	ds_read_b128 v[158:161], v255 offset:34816
	v_mfma_f32_16x16x32_bf16 v[12:15], v[170:173], v[242:245], v[12:15]
	v_mfma_f32_16x16x32_bf16 v[104:107], v[170:173], v[246:249], v[104:107]
	ds_read_b128 v[170:173], v255 offset:36864
	v_mfma_f32_16x16x32_bf16 v[8:11], v[174:177], v[242:245], v[8:11]
	v_mfma_f32_16x16x32_bf16 v[88:91], v[174:177], v[246:249], v[88:91]
	ds_read_b128 v[174:177], v255 offset:38912
	ds_read_b128 v[242:245], v254 offset:4096
	ds_read_b128 v[246:249], v254 offset:6144
	s_waitcnt lgkmcnt(5)
	v_mfma_f32_16x16x32_bf16 v[124:127], v[154:157], v[162:165], v[124:127]
	v_mfma_f32_16x16x32_bf16 v[108:111], v[154:157], v[166:169], v[108:111]
	s_waitcnt lgkmcnt(4)
	v_mfma_f32_16x16x32_bf16 v[120:123], v[158:161], v[162:165], v[120:123]
	v_mfma_f32_16x16x32_bf16 v[100:103], v[158:161], v[166:169], v[100:103]
	s_waitcnt lgkmcnt(3)
	v_mfma_f32_16x16x32_bf16 v[116:119], v[170:173], v[162:165], v[116:119]
	v_mfma_f32_16x16x32_bf16 v[96:99], v[170:173], v[166:169], v[96:99]
	s_waitcnt lgkmcnt(2)
	v_mfma_f32_16x16x32_bf16 v[112:115], v[174:177], v[162:165], v[112:115]
	v_mfma_f32_16x16x32_bf16 v[92:95], v[174:177], v[166:169], v[92:95]
	ds_read_b128 v[162:165], v254 offset:8192
	ds_read_b128 v[166:169], v254 offset:10240
	s_waitcnt lgkmcnt(2)
	v_mfma_f32_16x16x32_bf16 v[84:87], v[154:157], v[242:245], v[84:87]
	v_mfma_f32_16x16x32_bf16 v[68:71], v[154:157], v[246:249], v[68:71]
	v_mfma_f32_16x16x32_bf16 v[80:83], v[158:161], v[242:245], v[80:83]
	v_mfma_f32_16x16x32_bf16 v[64:67], v[158:161], v[246:249], v[64:67]
	v_mfma_f32_16x16x32_bf16 v[76:79], v[170:173], v[242:245], v[76:79]
	v_mfma_f32_16x16x32_bf16 v[60:63], v[170:173], v[246:249], v[60:63]
	v_mfma_f32_16x16x32_bf16 v[72:75], v[174:177], v[242:245], v[72:75]
	v_mfma_f32_16x16x32_bf16 v[56:59], v[174:177], v[246:249], v[56:59]
	ds_read_b128 v[242:245], v254 offset:12288
	ds_read_b128 v[246:249], v254 offset:14336
	s_waitcnt lgkmcnt(2)
	v_mfma_f32_16x16x32_bf16 v[52:55], v[154:157], v[162:165], v[52:55]
	v_mfma_f32_16x16x32_bf16 v[36:39], v[154:157], v[166:169], v[36:39]
	v_mfma_f32_16x16x32_bf16 v[48:51], v[158:161], v[162:165], v[48:51]
	v_mfma_f32_16x16x32_bf16 v[32:35], v[158:161], v[166:169], v[32:35]
	v_mfma_f32_16x16x32_bf16 v[44:47], v[170:173], v[162:165], v[44:47]
	v_mfma_f32_16x16x32_bf16 v[28:31], v[170:173], v[166:169], v[28:31]
	v_mfma_f32_16x16x32_bf16 v[40:43], v[174:177], v[162:165], v[40:43]
	v_mfma_f32_16x16x32_bf16 v[24:27], v[174:177], v[166:169], v[24:27]
	s_waitcnt vmcnt(0) lgkmcnt(0)
	s_barrier
	s_cmpk_eq_i32 s40, 0x780
	s_cbranch_scc1 .Lgx_1140
	v_xor_b32_e32 v254, 0x10040, v254
	v_xor_b32_e32 v255, 0x10040, v255
	ds_read_b128 v[162:165], v254
	ds_read_b128 v[166:169], v254 offset:2048
	s_lshl_b32 m0, s40, 9
	s_and_b32 m0, m0, 0x10000
	s_xor_b32 m0, m0, 0x10000
	s_add_i32 m0, m0, s2
	v_mfma_f32_16x16x32_bf16 v[20:23], v[154:157], v[242:245], v[20:23]
	global_load_lds_dwordx4 v250, s[98:99]
	s_add_i32 m0, m0, 0x8000
	v_mfma_f32_16x16x32_bf16 v[4:7], v[154:157], v[246:249], v[4:7]
	ds_read_b128 v[154:157], v255 offset:32768
	v_mfma_f32_16x16x32_bf16 v[16:19], v[158:161], v[242:245], v[16:19]
	global_load_lds_dwordx4 v250, s[100:101]
	s_add_i32 m0, m0, 0xffff8400
	v_mfma_f32_16x16x32_bf16 v[0:3], v[158:161], v[246:249], v[0:3]
	ds_read_b128 v[158:161], v255 offset:34816
	v_mfma_f32_16x16x32_bf16 v[12:15], v[170:173], v[242:245], v[12:15]
	global_load_lds_dwordx4 v251, s[98:99]
	s_add_i32 m0, m0, 0x8000
	v_mfma_f32_16x16x32_bf16 v[104:107], v[170:173], v[246:249], v[104:107]
	ds_read_b128 v[170:173], v255 offset:36864
	v_mfma_f32_16x16x32_bf16 v[8:11], v[174:177], v[242:245], v[8:11]
	global_load_lds_dwordx4 v251, s[100:101]
	v_mfma_f32_16x16x32_bf16 v[88:91], v[174:177], v[246:249], v[88:91]
	ds_read_b128 v[174:177], v255 offset:38912
	s_branch .LBB0_1140
.Lgx_1140:
	v_mfma_f32_16x16x32_bf16 v[20:23], v[154:157], v[242:245], v[20:23]
	v_mfma_f32_16x16x32_bf16 v[4:7], v[154:157], v[246:249], v[4:7]
	v_mfma_f32_16x16x32_bf16 v[16:19], v[158:161], v[242:245], v[16:19]
	v_mfma_f32_16x16x32_bf16 v[0:3], v[158:161], v[246:249], v[0:3]
	v_mfma_f32_16x16x32_bf16 v[12:15], v[170:173], v[242:245], v[12:15]
	v_mfma_f32_16x16x32_bf16 v[104:107], v[170:173], v[246:249], v[104:107]
	v_mfma_f32_16x16x32_bf16 v[8:11], v[174:177], v[242:245], v[8:11]
	v_mfma_f32_16x16x32_bf16 v[88:91], v[174:177], v[246:249], v[88:91]
	v_add_u32_e32 v153, s43, v153
	v_add_u32_e32 v166, v153, v149
	v_add_u32_e32 v139, s43, v139
	ds_read_b128 v[140:143], v166 offset:32768
	v_add_u32_e32 v170, v139, v149
	ds_read_b128 v[144:147], v166 offset:34816
	ds_read_b128 v[154:157], v170
	ds_read_b128 v[158:161], v170 offset:2048
	ds_read_b128 v[162:165], v166 offset:36864
	ds_read_b128 v[166:169], v166 offset:38912
	s_waitcnt lgkmcnt(3)
	v_mfma_f32_16x16x32_bf16 v[120:123], v[144:147], v[154:157], v[120:123]
	v_add_u32_e32 v139, v139, v150
	s_and_b64 vcc, exec, s[30:31]
	v_mfma_f32_16x16x32_bf16 v[124:127], v[140:143], v[154:157], v[124:127]
	s_waitcnt lgkmcnt(1)
	v_mfma_f32_16x16x32_bf16 v[116:119], v[162:165], v[154:157], v[116:119]
	s_waitcnt lgkmcnt(0)
	v_mfma_f32_16x16x32_bf16 v[112:115], v[166:169], v[154:157], v[112:115]
	v_mfma_f32_16x16x32_bf16 v[108:111], v[140:143], v[158:161], v[108:111]
	v_mfma_f32_16x16x32_bf16 v[100:103], v[144:147], v[158:161], v[100:103]
	v_mfma_f32_16x16x32_bf16 v[96:99], v[162:165], v[158:161], v[96:99]
	v_mfma_f32_16x16x32_bf16 v[92:95], v[166:169], v[158:161], v[92:95]
	ds_read_b128 v[154:157], v170 offset:4096
	ds_read_b128 v[158:161], v170 offset:6144
	s_waitcnt lgkmcnt(1)
	v_mfma_f32_16x16x32_bf16 v[84:87], v[140:143], v[154:157], v[84:87]
	v_mfma_f32_16x16x32_bf16 v[80:83], v[144:147], v[154:157], v[80:83]
	v_mfma_f32_16x16x32_bf16 v[76:79], v[162:165], v[154:157], v[76:79]
	v_mfma_f32_16x16x32_bf16 v[72:75], v[166:169], v[154:157], v[72:75]
	s_waitcnt lgkmcnt(0)
	v_mfma_f32_16x16x32_bf16 v[68:71], v[140:143], v[158:161], v[68:71]
	v_mfma_f32_16x16x32_bf16 v[64:67], v[144:147], v[158:161], v[64:67]
	v_mfma_f32_16x16x32_bf16 v[60:63], v[162:165], v[158:161], v[60:63]
	v_mfma_f32_16x16x32_bf16 v[56:59], v[166:169], v[158:161], v[56:59]
	ds_read_b128 v[154:157], v170 offset:8192
	ds_read_b128 v[158:161], v170 offset:10240
	s_waitcnt lgkmcnt(1)
	v_mfma_f32_16x16x32_bf16 v[52:55], v[140:143], v[154:157], v[52:55]
	v_mfma_f32_16x16x32_bf16 v[48:51], v[144:147], v[154:157], v[48:51]
	v_mfma_f32_16x16x32_bf16 v[44:47], v[162:165], v[154:157], v[44:47]
	v_mfma_f32_16x16x32_bf16 v[40:43], v[166:169], v[154:157], v[40:43]
	s_waitcnt lgkmcnt(0)
	v_mfma_f32_16x16x32_bf16 v[36:39], v[140:143], v[158:161], v[36:39]
	v_mfma_f32_16x16x32_bf16 v[32:35], v[144:147], v[158:161], v[32:35]
	v_mfma_f32_16x16x32_bf16 v[28:31], v[162:165], v[158:161], v[28:31]
	v_mfma_f32_16x16x32_bf16 v[24:27], v[166:169], v[158:161], v[24:27]
	ds_read_b128 v[154:157], v170 offset:12288
	ds_read_b128 v[158:161], v170 offset:14336
	s_waitcnt lgkmcnt(1)
	v_mfma_f32_16x16x32_bf16 v[20:23], v[140:143], v[154:157], v[20:23]
	s_waitcnt lgkmcnt(0)
	v_mfma_f32_16x16x32_bf16 v[4:7], v[140:143], v[158:161], v[4:7]
	v_mfma_f32_16x16x32_bf16 v[140:143], v[162:165], v[158:161], v[104:107]
	s_nop 2
	v_add_u32_e32 v104, v153, v150
	v_mfma_f32_16x16x32_bf16 v[16:19], v[144:147], v[154:157], v[16:19]
	v_mfma_f32_16x16x32_bf16 v[12:15], v[162:165], v[154:157], v[12:15]
	v_mfma_f32_16x16x32_bf16 v[8:11], v[166:169], v[154:157], v[8:11]
	v_mfma_f32_16x16x32_bf16 v[0:3], v[144:147], v[158:161], v[0:3]
	ds_read_b128 v[144:147], v104 offset:32768
	v_mfma_f32_16x16x32_bf16 v[154:157], v[166:169], v[158:161], v[88:91]
	ds_read_b128 v[158:161], v104 offset:34816
	s_nop 1
	ds_read_b128 v[88:91], v139
	ds_read_b128 v[162:165], v139 offset:2048
	ds_read_b128 v[166:169], v104 offset:36864
	ds_read_b128 v[170:173], v104 offset:38912
	s_waitcnt lgkmcnt(2)
	v_mfma_f32_16x16x32_bf16 v[108:111], v[144:147], v[162:165], v[108:111]
	v_mfma_f32_16x16x32_bf16 v[104:107], v[158:161], v[162:165], v[100:103]
	s_waitcnt lgkmcnt(1)
	v_mfma_f32_16x16x32_bf16 v[100:103], v[166:169], v[162:165], v[96:99]
	s_waitcnt lgkmcnt(0)
	v_mfma_f32_16x16x32_bf16 v[96:99], v[170:173], v[162:165], v[92:95]
	ds_read_b128 v[162:165], v139 offset:4096
	ds_read_b128 v[174:177], v139 offset:6144
	v_mfma_f32_16x16x32_bf16 v[124:127], v[144:147], v[88:91], v[124:127]
	v_mfma_f32_16x16x32_bf16 v[120:123], v[158:161], v[88:91], v[120:123]
	v_mfma_f32_16x16x32_bf16 v[116:119], v[166:169], v[88:91], v[116:119]
	v_mfma_f32_16x16x32_bf16 v[112:115], v[170:173], v[88:91], v[112:115]
	s_waitcnt lgkmcnt(1)
	v_mfma_f32_16x16x32_bf16 v[92:95], v[144:147], v[162:165], v[84:87]
	v_mfma_f32_16x16x32_bf16 v[88:91], v[158:161], v[162:165], v[80:83]
	v_mfma_f32_16x16x32_bf16 v[84:87], v[166:169], v[162:165], v[76:79]
	v_mfma_f32_16x16x32_bf16 v[80:83], v[170:173], v[162:165], v[72:75]
	s_waitcnt lgkmcnt(0)
	v_mfma_f32_16x16x32_bf16 v[76:79], v[144:147], v[174:177], v[68:71]
	v_mfma_f32_16x16x32_bf16 v[72:75], v[158:161], v[174:177], v[64:67]
	v_mfma_f32_16x16x32_bf16 v[68:71], v[166:169], v[174:177], v[60:63]
	v_mfma_f32_16x16x32_bf16 v[64:67], v[170:173], v[174:177], v[56:59]
	ds_read_b128 v[162:165], v139 offset:8192
	ds_read_b128 v[174:177], v139 offset:10240
	s_waitcnt lgkmcnt(1)
	v_mfma_f32_16x16x32_bf16 v[60:63], v[144:147], v[162:165], v[52:55]
	v_mfma_f32_16x16x32_bf16 v[56:59], v[158:161], v[162:165], v[48:51]
	v_mfma_f32_16x16x32_bf16 v[52:55], v[166:169], v[162:165], v[44:47]
	v_mfma_f32_16x16x32_bf16 v[48:51], v[170:173], v[162:165], v[40:43]
	s_waitcnt lgkmcnt(0)
	v_mfma_f32_16x16x32_bf16 v[44:47], v[144:147], v[174:177], v[36:39]
	v_mfma_f32_16x16x32_bf16 v[40:43], v[158:161], v[174:177], v[32:35]
	v_mfma_f32_16x16x32_bf16 v[36:39], v[166:169], v[174:177], v[28:31]
	v_mfma_f32_16x16x32_bf16 v[32:35], v[170:173], v[174:177], v[24:27]
	ds_read_b128 v[162:165], v139 offset:12288
	ds_read_b128 v[174:177], v139 offset:14336
	s_waitcnt vmcnt(0)
	s_waitcnt lgkmcnt(0)
	v_mfma_f32_16x16x32_bf16 v[28:31], v[144:147], v[162:165], v[20:23]
	s_barrier
	v_mfma_f32_16x16x32_bf16 v[24:27], v[158:161], v[162:165], v[16:19]
	v_mfma_f32_16x16x32_bf16 v[20:23], v[166:169], v[162:165], v[12:15]
	v_mfma_f32_16x16x32_bf16 v[16:19], v[170:173], v[162:165], v[8:11]
	v_mfma_f32_16x16x32_bf16 v[12:15], v[144:147], v[174:177], v[4:7]
	v_mfma_f32_16x16x32_bf16 v[8:11], v[158:161], v[174:177], v[0:3]
	v_mfma_f32_16x16x32_bf16 v[4:7], v[166:169], v[174:177], v[140:143]
	v_mfma_f32_16x16x32_bf16 v[0:3], v[170:173], v[174:177], v[154:157]
	s_cbranch_vccz .LBB0_1128
	s_add_u32 s36, s59, s36
	s_addc_u32 s37, s60, s37
	s_lshl_b64 s[30:31], s[38:39], 1
	s_add_u32 s34, s34, s30
	s_addc_u32 s35, s35, s31
	s_add_u32 s30, s36, s30
	s_addc_u32 s31, s37, s31
	s_add_i32 s2, s2, 0
	s_mov_b32 m0, s2
	v_mov_b32_e32 v139, v129
	global_load_lds_dwordx4 v128, s[34:35]
	s_add_i32 m0, s2, 0x8000
	v_lshl_add_u64 v[144:145], s[34:35], 0, v[138:139]
	s_add_i32 s2, s53, 0
	global_load_lds_dwordx4 v128, s[30:31]
	v_lshl_add_u64 v[146:147], v[144:145], 0, s[4:5]
	s_mov_b32 m0, s2
	v_lshl_add_u64 v[140:141], s[34:35], 0, v[128:129]
	global_load_lds_dwordx4 v[146:147], off
	v_lshl_add_u64 v[146:147], s[30:31], 0, v[138:139]
	v_lshl_add_u64 v[154:155], v[146:147], 0, s[4:5]
	s_add_i32 m0, s2, 0x8000
	s_add_i32 s2, s52, 0
	v_lshl_add_u64 v[142:143], s[30:31], 0, v[128:129]
	global_load_lds_dwordx4 v[154:155], off
	v_lshl_add_u64 v[140:141], v[140:141], 0, s[6:7]
	s_mov_b32 m0, s2
	s_nop 0
	global_load_lds_dwordx4 v[140:141], off
	v_lshl_add_u64 v[140:141], v[142:143], 0, s[6:7]
	s_add_i32 m0, s2, 0x8000
	s_add_i32 s2, s29, 0
	global_load_lds_dwordx4 v[140:141], off
	v_lshl_add_u64 v[140:141], v[144:145], 0, s[8:9]
	s_mov_b32 m0, s2
	s_nop 0
	global_load_lds_dwordx4 v[140:141], off
	v_lshl_add_u64 v[140:141], v[146:147], 0, s[8:9]
	s_add_i32 m0, s2, 0x8000
	s_nop 0
	global_load_lds_dwordx4 v[140:141], off
	s_branch .LBB0_1128

.LBB0_1186:
	s_lshr_b32 s50, s49, 1
	s_and_b32 s50, s50, 0x1ffff80
	v_or_b32_e32 v0, s50, v148
	s_and_b32 s49, s49, 0xc0
	v_lshlrev_b32_e32 v139, 7, v0
	v_or_b32_e32 v0, s49, v148
	s_mov_b32 s49, s3
	s_lshl_b64 s[48:49], s[48:49], 17
	s_add_u32 s44, s48, s44
	s_addc_u32 s45, s49, s45
	s_waitcnt vmcnt(0)
	v_lshlrev_b32_e32 v153, 7, v0
	v_lshl_add_u64 v[0:1], s[42:43], 0, v[130:131]
	s_add_u32 s46, s48, s46
	v_lshl_add_u64 v[140:141], v[0:1], 0, s[44:45]
	s_addc_u32 s47, s49, s47
	v_lshl_add_u64 v[0:1], s[42:43], 0, v[134:135]
	v_mov_b32_e32 v88, 0
	v_lshl_add_u64 v[142:143], v[132:133], 0, s[46:47]
	v_lshl_add_u64 v[144:145], v[0:1], 0, s[44:45]
	v_lshl_add_u64 v[146:147], v[136:137], 0, s[46:47]
	s_mov_b64 s[42:43], 0
	s_mov_b32 s44, 0
	v_mov_b32_e32 v89, v88
	v_mov_b32_e32 v90, v88
	v_mov_b32_e32 v91, v88
	v_mov_b32_e32 v104, v88
	v_mov_b32_e32 v105, v88
	v_mov_b32_e32 v106, v88
	v_mov_b32_e32 v107, v88
	v_mov_b32_e32 v0, v88
	v_mov_b32_e32 v1, v88
	v_mov_b32_e32 v2, v88
	v_mov_b32_e32 v3, v88
	v_mov_b32_e32 v4, v88
	v_mov_b32_e32 v5, v88
	v_mov_b32_e32 v6, v88
	v_mov_b32_e32 v7, v88
	v_mov_b32_e32 v8, v88
	v_mov_b32_e32 v9, v88
	v_mov_b32_e32 v10, v88
	v_mov_b32_e32 v11, v88
	v_mov_b32_e32 v12, v88
	v_mov_b32_e32 v13, v88
	v_mov_b32_e32 v14, v88
	v_mov_b32_e32 v15, v88
	v_mov_b32_e32 v16, v88
	v_mov_b32_e32 v17, v88
	v_mov_b32_e32 v18, v88
	v_mov_b32_e32 v19, v88
	v_mov_b32_e32 v20, v88
	v_mov_b32_e32 v21, v88
	v_mov_b32_e32 v22, v88
	v_mov_b32_e32 v23, v88
	v_mov_b32_e32 v24, v88
	v_mov_b32_e32 v25, v88
	v_mov_b32_e32 v26, v88
	v_mov_b32_e32 v27, v88
	v_mov_b32_e32 v28, v88
	v_mov_b32_e32 v29, v88
	v_mov_b32_e32 v30, v88
	v_mov_b32_e32 v31, v88
	v_mov_b32_e32 v32, v88
	v_mov_b32_e32 v33, v88
	v_mov_b32_e32 v34, v88
	v_mov_b32_e32 v35, v88
	v_mov_b32_e32 v36, v88
	v_mov_b32_e32 v37, v88
	v_mov_b32_e32 v38, v88
	v_mov_b32_e32 v39, v88
	v_mov_b32_e32 v40, v88
	v_mov_b32_e32 v41, v88
	v_mov_b32_e32 v42, v88
	v_mov_b32_e32 v43, v88
	v_mov_b32_e32 v44, v88
	v_mov_b32_e32 v45, v88
	v_mov_b32_e32 v46, v88
	v_mov_b32_e32 v47, v88
	v_mov_b32_e32 v48, v88
	v_mov_b32_e32 v49, v88
	v_mov_b32_e32 v50, v88
	v_mov_b32_e32 v51, v88
	v_mov_b32_e32 v52, v88
	v_mov_b32_e32 v53, v88
	v_mov_b32_e32 v54, v88
	v_mov_b32_e32 v55, v88
	v_mov_b32_e32 v56, v88
	v_mov_b32_e32 v57, v88
	v_mov_b32_e32 v58, v88
	v_mov_b32_e32 v59, v88
	v_mov_b32_e32 v60, v88
	v_mov_b32_e32 v61, v88
	v_mov_b32_e32 v62, v88
	v_mov_b32_e32 v63, v88
	v_mov_b32_e32 v64, v88
	v_mov_b32_e32 v65, v88
	v_mov_b32_e32 v66, v88
	v_mov_b32_e32 v67, v88
	v_mov_b32_e32 v68, v88
	v_mov_b32_e32 v69, v88
	v_mov_b32_e32 v70, v88
	v_mov_b32_e32 v71, v88
	v_mov_b32_e32 v72, v88
	v_mov_b32_e32 v73, v88
	v_mov_b32_e32 v74, v88
	v_mov_b32_e32 v75, v88
	v_mov_b32_e32 v76, v88
	v_mov_b32_e32 v77, v88
	v_mov_b32_e32 v78, v88
	v_mov_b32_e32 v79, v88
	v_mov_b32_e32 v80, v88
	v_mov_b32_e32 v81, v88
	v_mov_b32_e32 v82, v88
	v_mov_b32_e32 v83, v88
	v_mov_b32_e32 v84, v88
	v_mov_b32_e32 v85, v88
	v_mov_b32_e32 v86, v88
	v_mov_b32_e32 v87, v88
	v_mov_b32_e32 v92, v88
	v_mov_b32_e32 v93, v88
	v_mov_b32_e32 v94, v88
	v_mov_b32_e32 v95, v88
	v_mov_b32_e32 v96, v88
	v_mov_b32_e32 v97, v88
	v_mov_b32_e32 v98, v88
	v_mov_b32_e32 v99, v88
	v_mov_b32_e32 v100, v88
	v_mov_b32_e32 v101, v88
	v_mov_b32_e32 v102, v88
	v_mov_b32_e32 v103, v88
	v_mov_b32_e32 v108, v88
	v_mov_b32_e32 v109, v88
	v_mov_b32_e32 v110, v88
	v_mov_b32_e32 v111, v88
	v_mov_b32_e32 v112, v88
	v_mov_b32_e32 v113, v88
	v_mov_b32_e32 v114, v88
	v_mov_b32_e32 v115, v88
	v_mov_b32_e32 v116, v88
	v_mov_b32_e32 v117, v88
	v_mov_b32_e32 v118, v88
	v_mov_b32_e32 v119, v88
	v_mov_b32_e32 v120, v88
	v_mov_b32_e32 v121, v88
	v_mov_b32_e32 v122, v88
	v_mov_b32_e32 v123, v88
	v_mov_b32_e32 v124, v88
	v_mov_b32_e32 v125, v88
	v_mov_b32_e32 v126, v88
	v_mov_b32_e32 v127, v88
	s_waitcnt vmcnt(0) lgkmcnt(0)
	s_barrier
	v_bfe_u32 v250, v178, 3, 3
	v_and_b32_e32 v251, 7, v178
	v_lshrrev_b32_e32 v252, 1, v250
	v_xor_b32_e32 v251, v251, v252
	v_lshlrev_b32_e32 v251, 4, v251
	v_lshl_or_b32 v250, v250, 12, v251
	v_xor_b32_e32 v251, 64, v250
	v_add_u32_e32 v251, 0x8000, v251
	v_add_u32_e32 v252, 0x10000, v250
	v_add_u32_e32 v253, 0x10000, v251
	v_lshl_add_u64 v[242:243], v[140:141], 0, s[42:43]
	v_lshl_add_u64 v[242:243], v[242:243], 0, s[12:13]
	v_lshl_add_u64 v[244:245], v[142:143], 0, s[42:43]
	v_lshl_add_u64 v[244:245], v[244:245], 0, s[14:15]
	v_add_u32_e32 v254, v139, v149
	v_add_u32_e32 v255, v153, v149
	v_readfirstlane_b32 s98, v242
	v_readfirstlane_b32 s99, v243
	v_readfirstlane_b32 s100, v244
	v_readfirstlane_b32 s101, v245
	ds_read_b128 v[162:165], v254
	ds_read_b128 v[166:169], v254 offset:2048
	ds_read_b128 v[154:157], v255 offset:32768
	ds_read_b128 v[158:161], v255 offset:34816
	ds_read_b128 v[170:173], v255 offset:36864
	ds_read_b128 v[174:177], v255 offset:38912
	s_nop 4
	s_lshl_b32 m0, s42, 9
	s_and_b32 m0, m0, 0x10000
	s_xor_b32 m0, m0, 0x10000
	s_add_i32 m0, m0, s2
	s_nop 0
	global_load_lds_dwordx4 v250, s[98:99]
	s_add_i32 m0, m0, 0x8000
	s_nop 0
	global_load_lds_dwordx4 v250, s[100:101]
	s_add_i32 m0, m0, 0xffff8400
	s_nop 0
	global_load_lds_dwordx4 v251, s[98:99]
	s_add_i32 m0, m0, 0x8000
	s_nop 0
	global_load_lds_dwordx4 v251, s[100:101]
.LBB0_1187:
	ds_read_b128 v[242:245], v254 offset:4096
	ds_read_b128 v[246:249], v254 offset:6144
	s_lshl_b32 m0, s42, 9
	s_and_b32 m0, m0, 0x10000
	s_xor_b32 m0, m0, 0x10000
	s_add_i32 m0, m0, s2
	s_add_i32 m0, m0, 0x800
	s_waitcnt lgkmcnt(5)
	v_mfma_f32_16x16x32_bf16 v[124:127], v[154:157], v[162:165], v[124:127]
	global_load_lds_dwordx4 v252, s[98:99]
	s_add_i32 m0, m0, 0x8000
	v_mfma_f32_16x16x32_bf16 v[108:111], v[154:157], v[166:169], v[108:111]
	s_waitcnt lgkmcnt(4)
	v_mfma_f32_16x16x32_bf16 v[120:123], v[158:161], v[162:165], v[120:123]
	global_load_lds_dwordx4 v252, s[100:101]
	s_add_i32 m0, m0, 0xffff8400
	v_mfma_f32_16x16x32_bf16 v[100:103], v[158:161], v[166:169], v[100:103]
	s_waitcnt lgkmcnt(3)
	v_mfma_f32_16x16x32_bf16 v[116:119], v[170:173], v[162:165], v[116:119]
	global_load_lds_dwordx4 v253, s[98:99]
	s_add_i32 m0, m0, 0x8000
	v_mfma_f32_16x16x32_bf16 v[96:99], v[170:173], v[166:169], v[96:99]
	s_waitcnt lgkmcnt(2)
	v_mfma_f32_16x16x32_bf16 v[112:115], v[174:177], v[162:165], v[112:115]
	global_load_lds_dwordx4 v253, s[100:101]
	v_mfma_f32_16x16x32_bf16 v[92:95], v[174:177], v[166:169], v[92:95]
	s_add_u32 s98, s98, 0x80
	s_addc_u32 s99, s99, 0
	s_add_u32 s100, s100, 0x80
	s_addc_u32 s101, s101, 0
	ds_read_b128 v[162:165], v254 offset:8192
	ds_read_b128 v[166:169], v254 offset:10240
	s_waitcnt lgkmcnt(2)
	v_mfma_f32_16x16x32_bf16 v[84:87], v[154:157], v[242:245], v[84:87]
	s_add_i32 s46, s44, 0x10000
	v_mfma_f32_16x16x32_bf16 v[68:71], v[154:157], v[246:249], v[68:71]
	s_and_b32 s44, s44, 0x10000
	v_mfma_f32_16x16x32_bf16 v[80:83], v[158:161], v[242:245], v[80:83]
	s_and_b32 s45, s46, 0x10000
	v_mfma_f32_16x16x32_bf16 v[64:67], v[158:161], v[246:249], v[64:67]
	s_add_i32 s44, s44, 0
	v_mfma_f32_16x16x32_bf16 v[76:79], v[170:173], v[242:245], v[76:79]
	s_add_i32 s45, s45, 0
	v_mfma_f32_16x16x32_bf16 v[60:63], v[170:173], v[246:249], v[60:63]
	s_add_i32 s44, s45, s2
	v_mfma_f32_16x16x32_bf16 v[72:75], v[174:177], v[242:245], v[72:75]
	s_add_i32 s47, s45, s65
	v_mfma_f32_16x16x32_bf16 v[56:59], v[174:177], v[246:249], v[56:59]
	s_add_i32 s48, s45, s64
	s_add_i32 s49, s45, s31
	s_add_u32 s42, s42, 0x80
	s_addc_u32 s43, s43, 0
	s_mov_b32 s44, s46
	s_cmpk_eq_i32 s42, 0xf80
	ds_read_b128 v[242:245], v254 offset:12288
	ds_read_b128 v[246:249], v254 offset:14336
	s_waitcnt lgkmcnt(2)
	v_mfma_f32_16x16x32_bf16 v[52:55], v[154:157], v[162:165], v[52:55]
	v_mfma_f32_16x16x32_bf16 v[36:39], v[154:157], v[166:169], v[36:39]
	v_mfma_f32_16x16x32_bf16 v[48:51], v[158:161], v[162:165], v[48:51]
	v_mfma_f32_16x16x32_bf16 v[32:35], v[158:161], v[166:169], v[32:35]
	v_mfma_f32_16x16x32_bf16 v[44:47], v[170:173], v[162:165], v[44:47]
	v_mfma_f32_16x16x32_bf16 v[28:31], v[170:173], v[166:169], v[28:31]
	v_mfma_f32_16x16x32_bf16 v[40:43], v[174:177], v[162:165], v[40:43]
	v_mfma_f32_16x16x32_bf16 v[24:27], v[174:177], v[166:169], v[24:27]
	v_xor_b32_e32 v254, 64, v254
	v_xor_b32_e32 v255, 64, v255
	ds_read_b128 v[162:165], v254
	ds_read_b128 v[166:169], v254 offset:2048
	s_waitcnt lgkmcnt(2)
	v_mfma_f32_16x16x32_bf16 v[20:23], v[154:157], v[242:245], v[20:23]
	v_mfma_f32_16x16x32_bf16 v[4:7], v[154:157], v[246:249], v[4:7]
	ds_read_b128 v[154:157], v255 offset:32768
	v_mfma_f32_16x16x32_bf16 v[16:19], v[158:161], v[242:245], v[16:19]
	v_mfma_f32_16x16x32_bf16 v[0:3], v[158:161], v[246:249], v[0:3]
	ds_read_b128 v[158:161], v255 offset:34816
	v_mfma_f32_16x16x32_bf16 v[12:15], v[170:173], v[242:245], v[12:15]
	v_mfma_f32_16x16x32_bf16 v[104:107], v[170:173], v[246:249], v[104:107]
	ds_read_b128 v[170:173], v255 offset:36864
	v_mfma_f32_16x16x32_bf16 v[8:11], v[174:177], v[242:245], v[8:11]
	v_mfma_f32_16x16x32_bf16 v[88:91], v[174:177], v[246:249], v[88:91]
	ds_read_b128 v[174:177], v255 offset:38912
	ds_read_b128 v[242:245], v254 offset:4096
	ds_read_b128 v[246:249], v254 offset:6144
	s_waitcnt lgkmcnt(5)
	v_mfma_f32_16x16x32_bf16 v[124:127], v[154:157], v[162:165], v[124:127]
	v_mfma_f32_16x16x32_bf16 v[108:111], v[154:157], v[166:169], v[108:111]
	s_waitcnt lgkmcnt(4)
	v_mfma_f32_16x16x32_bf16 v[120:123], v[158:161], v[162:165], v[120:123]
	v_mfma_f32_16x16x32_bf16 v[100:103], v[158:161], v[166:169], v[100:103]
	s_waitcnt lgkmcnt(3)
	v_mfma_f32_16x16x32_bf16 v[116:119], v[170:173], v[162:165], v[116:119]
	v_mfma_f32_16x16x32_bf16 v[96:99], v[170:173], v[166:169], v[96:99]
	s_waitcnt lgkmcnt(2)
	v_mfma_f32_16x16x32_bf16 v[112:115], v[174:177], v[162:165], v[112:115]
	v_mfma_f32_16x16x32_bf16 v[92:95], v[174:177], v[166:169], v[92:95]
	ds_read_b128 v[162:165], v254 offset:8192
	ds_read_b128 v[166:169], v254 offset:10240
	s_waitcnt lgkmcnt(2)
	v_mfma_f32_16x16x32_bf16 v[84:87], v[154:157], v[242:245], v[84:87]
	v_mfma_f32_16x16x32_bf16 v[68:71], v[154:157], v[246:249], v[68:71]
	v_mfma_f32_16x16x32_bf16 v[80:83], v[158:161], v[242:245], v[80:83]
	v_mfma_f32_16x16x32_bf16 v[64:67], v[158:161], v[246:249], v[64:67]
	v_mfma_f32_16x16x32_bf16 v[76:79], v[170:173], v[242:245], v[76:79]
	v_mfma_f32_16x16x32_bf16 v[60:63], v[170:173], v[246:249], v[60:63]
	v_mfma_f32_16x16x32_bf16 v[72:75], v[174:177], v[242:245], v[72:75]
	v_mfma_f32_16x16x32_bf16 v[56:59], v[174:177], v[246:249], v[56:59]
	ds_read_b128 v[242:245], v254 offset:12288
	ds_read_b128 v[246:249], v254 offset:14336
	s_waitcnt lgkmcnt(2)
	v_mfma_f32_16x16x32_bf16 v[52:55], v[154:157], v[162:165], v[52:55]
	v_mfma_f32_16x16x32_bf16 v[36:39], v[154:157], v[166:169], v[36:39]
	v_mfma_f32_16x16x32_bf16 v[48:51], v[158:161], v[162:165], v[48:51]
	v_mfma_f32_16x16x32_bf16 v[32:35], v[158:161], v[166:169], v[32:35]
	v_mfma_f32_16x16x32_bf16 v[44:47], v[170:173], v[162:165], v[44:47]
	v_mfma_f32_16x16x32_bf16 v[28:31], v[170:173], v[166:169], v[28:31]
	v_mfma_f32_16x16x32_bf16 v[40:43], v[174:177], v[162:165], v[40:43]
	v_mfma_f32_16x16x32_bf16 v[24:27], v[174:177], v[166:169], v[24:27]
	s_waitcnt vmcnt(0) lgkmcnt(0)
	s_barrier
	s_cmpk_eq_i32 s42, 0xf80
	s_cbranch_scc1 .Lgx_1187
	v_xor_b32_e32 v254, 0x10040, v254
	v_xor_b32_e32 v255, 0x10040, v255
	ds_read_b128 v[162:165], v254
	ds_read_b128 v[166:169], v254 offset:2048
	s_lshl_b32 m0, s42, 9
	s_and_b32 m0, m0, 0x10000
	s_xor_b32 m0, m0, 0x10000
	s_add_i32 m0, m0, s2
	v_mfma_f32_16x16x32_bf16 v[20:23], v[154:157], v[242:245], v[20:23]
	global_load_lds_dwordx4 v250, s[98:99]
	s_add_i32 m0, m0, 0x8000
	v_mfma_f32_16x16x32_bf16 v[4:7], v[154:157], v[246:249], v[4:7]
	ds_read_b128 v[154:157], v255 offset:32768
	v_mfma_f32_16x16x32_bf16 v[16:19], v[158:161], v[242:245], v[16:19]
	global_load_lds_dwordx4 v250, s[100:101]
	s_add_i32 m0, m0, 0xffff8400
	v_mfma_f32_16x16x32_bf16 v[0:3], v[158:161], v[246:249], v[0:3]
	ds_read_b128 v[158:161], v255 offset:34816
	v_mfma_f32_16x16x32_bf16 v[12:15], v[170:173], v[242:245], v[12:15]
	global_load_lds_dwordx4 v251, s[98:99]
	s_add_i32 m0, m0, 0x8000
	v_mfma_f32_16x16x32_bf16 v[104:107], v[170:173], v[246:249], v[104:107]
	ds_read_b128 v[170:173], v255 offset:36864
	v_mfma_f32_16x16x32_bf16 v[8:11], v[174:177], v[242:245], v[8:11]
	global_load_lds_dwordx4 v251, s[100:101]
	v_mfma_f32_16x16x32_bf16 v[88:91], v[174:177], v[246:249], v[88:91]
	ds_read_b128 v[174:177], v255 offset:38912
	s_branch .LBB0_1187
.Lgx_1187:
	v_mfma_f32_16x16x32_bf16 v[20:23], v[154:157], v[242:245], v[20:23]
	v_mfma_f32_16x16x32_bf16 v[4:7], v[154:157], v[246:249], v[4:7]
	v_mfma_f32_16x16x32_bf16 v[16:19], v[158:161], v[242:245], v[16:19]
	v_mfma_f32_16x16x32_bf16 v[0:3], v[158:161], v[246:249], v[0:3]
	v_mfma_f32_16x16x32_bf16 v[12:15], v[170:173], v[242:245], v[12:15]
	v_mfma_f32_16x16x32_bf16 v[104:107], v[170:173], v[246:249], v[104:107]
	v_mfma_f32_16x16x32_bf16 v[8:11], v[174:177], v[242:245], v[8:11]
	v_mfma_f32_16x16x32_bf16 v[88:91], v[174:177], v[246:249], v[88:91]
	v_add_u32_e32 v153, s45, v153
	v_add_u32_e32 v166, v153, v149
	v_add_u32_e32 v139, s45, v139
	ds_read_b128 v[140:143], v166 offset:32768
	v_add_u32_e32 v170, v139, v149
	ds_read_b128 v[144:147], v166 offset:34816
	ds_read_b128 v[154:157], v170
	ds_read_b128 v[158:161], v170 offset:2048
	ds_read_b128 v[162:165], v166 offset:36864
	ds_read_b128 v[166:169], v166 offset:38912
	s_waitcnt lgkmcnt(3)
	v_mfma_f32_16x16x32_bf16 v[120:123], v[144:147], v[154:157], v[120:123]
	v_add_u32_e32 v139, v139, v150
	s_and_b64 vcc, exec, s[34:35]
	v_mfma_f32_16x16x32_bf16 v[124:127], v[140:143], v[154:157], v[124:127]
	s_waitcnt lgkmcnt(1)
	v_mfma_f32_16x16x32_bf16 v[116:119], v[162:165], v[154:157], v[116:119]
	s_waitcnt lgkmcnt(0)
	v_mfma_f32_16x16x32_bf16 v[112:115], v[166:169], v[154:157], v[112:115]
	v_mfma_f32_16x16x32_bf16 v[108:111], v[140:143], v[158:161], v[108:111]
	v_mfma_f32_16x16x32_bf16 v[100:103], v[144:147], v[158:161], v[100:103]
	v_mfma_f32_16x16x32_bf16 v[96:99], v[162:165], v[158:161], v[96:99]
	v_mfma_f32_16x16x32_bf16 v[92:95], v[166:169], v[158:161], v[92:95]
	ds_read_b128 v[154:157], v170 offset:4096
	ds_read_b128 v[158:161], v170 offset:6144
	s_waitcnt lgkmcnt(1)
	v_mfma_f32_16x16x32_bf16 v[84:87], v[140:143], v[154:157], v[84:87]
	v_mfma_f32_16x16x32_bf16 v[80:83], v[144:147], v[154:157], v[80:83]
	v_mfma_f32_16x16x32_bf16 v[76:79], v[162:165], v[154:157], v[76:79]
	v_mfma_f32_16x16x32_bf16 v[72:75], v[166:169], v[154:157], v[72:75]
	s_waitcnt lgkmcnt(0)
	v_mfma_f32_16x16x32_bf16 v[68:71], v[140:143], v[158:161], v[68:71]
	v_mfma_f32_16x16x32_bf16 v[64:67], v[144:147], v[158:161], v[64:67]
	v_mfma_f32_16x16x32_bf16 v[60:63], v[162:165], v[158:161], v[60:63]
	v_mfma_f32_16x16x32_bf16 v[56:59], v[166:169], v[158:161], v[56:59]
	ds_read_b128 v[154:157], v170 offset:8192
	ds_read_b128 v[158:161], v170 offset:10240
	s_waitcnt lgkmcnt(1)
	v_mfma_f32_16x16x32_bf16 v[52:55], v[140:143], v[154:157], v[52:55]
	v_mfma_f32_16x16x32_bf16 v[48:51], v[144:147], v[154:157], v[48:51]
	v_mfma_f32_16x16x32_bf16 v[44:47], v[162:165], v[154:157], v[44:47]
	v_mfma_f32_16x16x32_bf16 v[40:43], v[166:169], v[154:157], v[40:43]
	s_waitcnt lgkmcnt(0)
	v_mfma_f32_16x16x32_bf16 v[36:39], v[140:143], v[158:161], v[36:39]
	v_mfma_f32_16x16x32_bf16 v[32:35], v[144:147], v[158:161], v[32:35]
	v_mfma_f32_16x16x32_bf16 v[28:31], v[162:165], v[158:161], v[28:31]
	v_mfma_f32_16x16x32_bf16 v[24:27], v[166:169], v[158:161], v[24:27]
	ds_read_b128 v[154:157], v170 offset:12288
	ds_read_b128 v[158:161], v170 offset:14336
	s_waitcnt lgkmcnt(1)
	v_mfma_f32_16x16x32_bf16 v[20:23], v[140:143], v[154:157], v[20:23]
	s_waitcnt lgkmcnt(0)
	v_mfma_f32_16x16x32_bf16 v[4:7], v[140:143], v[158:161], v[4:7]
	v_mfma_f32_16x16x32_bf16 v[140:143], v[162:165], v[158:161], v[104:107]
	s_nop 2
	v_add_u32_e32 v104, v153, v150
	v_mfma_f32_16x16x32_bf16 v[16:19], v[144:147], v[154:157], v[16:19]
	v_mfma_f32_16x16x32_bf16 v[12:15], v[162:165], v[154:157], v[12:15]
	v_mfma_f32_16x16x32_bf16 v[8:11], v[166:169], v[154:157], v[8:11]
	v_mfma_f32_16x16x32_bf16 v[0:3], v[144:147], v[158:161], v[0:3]
	ds_read_b128 v[144:147], v104 offset:32768
	v_mfma_f32_16x16x32_bf16 v[154:157], v[166:169], v[158:161], v[88:91]
	ds_read_b128 v[158:161], v104 offset:34816
	s_nop 1
	ds_read_b128 v[88:91], v139
	ds_read_b128 v[162:165], v139 offset:2048
	ds_read_b128 v[166:169], v104 offset:36864
	ds_read_b128 v[170:173], v104 offset:38912
	s_waitcnt lgkmcnt(2)
	v_mfma_f32_16x16x32_bf16 v[108:111], v[144:147], v[162:165], v[108:111]
	v_mfma_f32_16x16x32_bf16 v[104:107], v[158:161], v[162:165], v[100:103]
	s_waitcnt lgkmcnt(1)
	v_mfma_f32_16x16x32_bf16 v[100:103], v[166:169], v[162:165], v[96:99]
	s_waitcnt lgkmcnt(0)
	v_mfma_f32_16x16x32_bf16 v[96:99], v[170:173], v[162:165], v[92:95]
	ds_read_b128 v[162:165], v139 offset:4096
	ds_read_b128 v[174:177], v139 offset:6144
	v_mfma_f32_16x16x32_bf16 v[124:127], v[144:147], v[88:91], v[124:127]
	v_mfma_f32_16x16x32_bf16 v[120:123], v[158:161], v[88:91], v[120:123]
	v_mfma_f32_16x16x32_bf16 v[116:119], v[166:169], v[88:91], v[116:119]
	v_mfma_f32_16x16x32_bf16 v[112:115], v[170:173], v[88:91], v[112:115]
	s_waitcnt lgkmcnt(1)
	v_mfma_f32_16x16x32_bf16 v[92:95], v[144:147], v[162:165], v[84:87]
	v_mfma_f32_16x16x32_bf16 v[88:91], v[158:161], v[162:165], v[80:83]
	v_mfma_f32_16x16x32_bf16 v[84:87], v[166:169], v[162:165], v[76:79]
	v_mfma_f32_16x16x32_bf16 v[80:83], v[170:173], v[162:165], v[72:75]
	s_waitcnt lgkmcnt(0)
	v_mfma_f32_16x16x32_bf16 v[76:79], v[144:147], v[174:177], v[68:71]
	v_mfma_f32_16x16x32_bf16 v[72:75], v[158:161], v[174:177], v[64:67]
	v_mfma_f32_16x16x32_bf16 v[68:71], v[166:169], v[174:177], v[60:63]
	v_mfma_f32_16x16x32_bf16 v[64:67], v[170:173], v[174:177], v[56:59]
	ds_read_b128 v[162:165], v139 offset:8192
	ds_read_b128 v[174:177], v139 offset:10240
	s_waitcnt lgkmcnt(1)
	v_mfma_f32_16x16x32_bf16 v[60:63], v[144:147], v[162:165], v[52:55]
	v_mfma_f32_16x16x32_bf16 v[56:59], v[158:161], v[162:165], v[48:51]
	v_mfma_f32_16x16x32_bf16 v[52:55], v[166:169], v[162:165], v[44:47]
	v_mfma_f32_16x16x32_bf16 v[48:51], v[170:173], v[162:165], v[40:43]
	s_waitcnt lgkmcnt(0)
	v_mfma_f32_16x16x32_bf16 v[44:47], v[144:147], v[174:177], v[36:39]
	v_mfma_f32_16x16x32_bf16 v[40:43], v[158:161], v[174:177], v[32:35]
	v_mfma_f32_16x16x32_bf16 v[36:39], v[166:169], v[174:177], v[28:31]
	v_mfma_f32_16x16x32_bf16 v[32:35], v[170:173], v[174:177], v[24:27]
	ds_read_b128 v[162:165], v139 offset:12288
	ds_read_b128 v[174:177], v139 offset:14336
	s_waitcnt vmcnt(0)
	s_waitcnt lgkmcnt(0)
	v_mfma_f32_16x16x32_bf16 v[28:31], v[144:147], v[162:165], v[20:23]
	s_barrier
	v_mfma_f32_16x16x32_bf16 v[24:27], v[158:161], v[162:165], v[16:19]
	v_mfma_f32_16x16x32_bf16 v[20:23], v[166:169], v[162:165], v[12:15]
	v_mfma_f32_16x16x32_bf16 v[16:19], v[170:173], v[162:165], v[8:11]
	v_mfma_f32_16x16x32_bf16 v[12:15], v[144:147], v[174:177], v[4:7]
	v_mfma_f32_16x16x32_bf16 v[4:7], v[158:161], v[174:177], v[0:3]
	v_mfma_f32_16x16x32_bf16 v[8:11], v[166:169], v[174:177], v[140:143]
	v_mfma_f32_16x16x32_bf16 v[0:3], v[170:173], v[174:177], v[154:157]
	s_cbranch_vccz .LBB0_1179
	s_add_u32 s38, s56, s38
	s_addc_u32 s39, s57, s39
	s_lshl_b64 s[34:35], s[40:41], 1
	s_add_u32 s36, s36, s34
	s_addc_u32 s37, s37, s35
	s_add_u32 s34, s38, s34
	s_addc_u32 s35, s39, s35
	s_add_i32 s2, s2, 0
	s_mov_b32 m0, s2
	v_mov_b32_e32 v139, v129
	global_load_lds_dwordx4 v128, s[36:37]
	s_add_i32 m0, s2, 0x8000
	v_lshl_add_u64 v[144:145], s[36:37], 0, v[138:139]
	s_add_i32 s2, s65, 0
	global_load_lds_dwordx4 v128, s[34:35]
	v_lshl_add_u64 v[146:147], v[144:145], 0, s[6:7]
	s_mov_b32 m0, s2
	v_lshl_add_u64 v[140:141], s[36:37], 0, v[128:129]
	global_load_lds_dwordx4 v[146:147], off
	v_lshl_add_u64 v[146:147], s[34:35], 0, v[138:139]
	v_lshl_add_u64 v[154:155], v[146:147], 0, s[6:7]
	s_add_i32 m0, s2, 0x8000
	s_add_i32 s2, s64, 0
	v_lshl_add_u64 v[142:143], s[34:35], 0, v[128:129]
	global_load_lds_dwordx4 v[154:155], off
	v_lshl_add_u64 v[140:141], v[140:141], 0, s[8:9]
	s_mov_b32 m0, s2
	s_nop 0
	global_load_lds_dwordx4 v[140:141], off
	v_lshl_add_u64 v[140:141], v[142:143], 0, s[8:9]
	s_add_i32 m0, s2, 0x8000
	s_add_i32 s2, s31, 0
	global_load_lds_dwordx4 v[140:141], off
	v_lshl_add_u64 v[140:141], v[144:145], 0, s[10:11]
	s_mov_b32 m0, s2
	s_nop 0
	global_load_lds_dwordx4 v[140:141], off
	v_lshl_add_u64 v[140:141], v[146:147], 0, s[10:11]
	s_add_i32 m0, s2, 0x8000
	s_nop 0
	global_load_lds_dwordx4 v[140:141], off
	s_branch .LBB0_1179

.LBB0_1242:
	s_lshr_b32 s48, s47, 1
	s_and_b32 s48, s48, 0x1ffff80
	v_or_b32_e32 v0, s48, v150
	s_and_b32 s47, s47, 0xc0
	v_lshlrev_b32_e32 v128, 7, v0
	v_or_b32_e32 v0, s47, v150
	s_mov_b32 s47, s11
	s_lshl_b64 s[46:47], s[46:47], 16
	s_add_u32 s42, s46, s42
	s_addc_u32 s43, s47, s43
	s_waitcnt vmcnt(0)
	v_lshlrev_b32_e32 v139, 7, v0
	v_lshl_add_u64 v[0:1], s[40:41], 0, v[130:131]
	s_add_u32 s44, s46, s44
	v_lshl_add_u64 v[142:143], v[0:1], 0, s[42:43]
	s_addc_u32 s45, s47, s45
	v_lshl_add_u64 v[0:1], s[40:41], 0, v[134:135]
	v_mov_b32_e32 v88, 0
	v_lshl_add_u64 v[144:145], v[132:133], 0, s[44:45]
	v_lshl_add_u64 v[146:147], v[0:1], 0, s[42:43]
	v_lshl_add_u64 v[148:149], v[136:137], 0, s[44:45]
	s_mov_b64 s[40:41], 0
	s_mov_b32 s42, 0
	v_mov_b32_e32 v89, v88
	v_mov_b32_e32 v90, v88
	v_mov_b32_e32 v91, v88
	v_mov_b32_e32 v104, v88
	v_mov_b32_e32 v105, v88
	v_mov_b32_e32 v106, v88
	v_mov_b32_e32 v107, v88
	v_mov_b32_e32 v0, v88
	v_mov_b32_e32 v1, v88
	v_mov_b32_e32 v2, v88
	v_mov_b32_e32 v3, v88
	v_mov_b32_e32 v4, v88
	v_mov_b32_e32 v5, v88
	v_mov_b32_e32 v6, v88
	v_mov_b32_e32 v7, v88
	v_mov_b32_e32 v8, v88
	v_mov_b32_e32 v9, v88
	v_mov_b32_e32 v10, v88
	v_mov_b32_e32 v11, v88
	v_mov_b32_e32 v12, v88
	v_mov_b32_e32 v13, v88
	v_mov_b32_e32 v14, v88
	v_mov_b32_e32 v15, v88
	v_mov_b32_e32 v16, v88
	v_mov_b32_e32 v17, v88
	v_mov_b32_e32 v18, v88
	v_mov_b32_e32 v19, v88
	v_mov_b32_e32 v20, v88
	v_mov_b32_e32 v21, v88
	v_mov_b32_e32 v22, v88
	v_mov_b32_e32 v23, v88
	v_mov_b32_e32 v24, v88
	v_mov_b32_e32 v25, v88
	v_mov_b32_e32 v26, v88
	v_mov_b32_e32 v27, v88
	v_mov_b32_e32 v28, v88
	v_mov_b32_e32 v29, v88
	v_mov_b32_e32 v30, v88
	v_mov_b32_e32 v31, v88
	v_mov_b32_e32 v32, v88
	v_mov_b32_e32 v33, v88
	v_mov_b32_e32 v34, v88
	v_mov_b32_e32 v35, v88
	v_mov_b32_e32 v36, v88
	v_mov_b32_e32 v37, v88
	v_mov_b32_e32 v38, v88
	v_mov_b32_e32 v39, v88
	v_mov_b32_e32 v40, v88
	v_mov_b32_e32 v41, v88
	v_mov_b32_e32 v42, v88
	v_mov_b32_e32 v43, v88
	v_mov_b32_e32 v44, v88
	v_mov_b32_e32 v45, v88
	v_mov_b32_e32 v46, v88
	v_mov_b32_e32 v47, v88
	v_mov_b32_e32 v48, v88
	v_mov_b32_e32 v49, v88
	v_mov_b32_e32 v50, v88
	v_mov_b32_e32 v51, v88
	v_mov_b32_e32 v52, v88
	v_mov_b32_e32 v53, v88
	v_mov_b32_e32 v54, v88
	v_mov_b32_e32 v55, v88
	v_mov_b32_e32 v56, v88
	v_mov_b32_e32 v57, v88
	v_mov_b32_e32 v58, v88
	v_mov_b32_e32 v59, v88
	v_mov_b32_e32 v60, v88
	v_mov_b32_e32 v61, v88
	v_mov_b32_e32 v62, v88
	v_mov_b32_e32 v63, v88
	v_mov_b32_e32 v64, v88
	v_mov_b32_e32 v65, v88
	v_mov_b32_e32 v66, v88
	v_mov_b32_e32 v67, v88
	v_mov_b32_e32 v68, v88
	v_mov_b32_e32 v69, v88
	v_mov_b32_e32 v70, v88
	v_mov_b32_e32 v71, v88
	v_mov_b32_e32 v72, v88
	v_mov_b32_e32 v73, v88
	v_mov_b32_e32 v74, v88
	v_mov_b32_e32 v75, v88
	v_mov_b32_e32 v76, v88
	v_mov_b32_e32 v77, v88
	v_mov_b32_e32 v78, v88
	v_mov_b32_e32 v79, v88
	v_mov_b32_e32 v80, v88
	v_mov_b32_e32 v81, v88
	v_mov_b32_e32 v82, v88
	v_mov_b32_e32 v83, v88
	v_mov_b32_e32 v84, v88
	v_mov_b32_e32 v85, v88
	v_mov_b32_e32 v86, v88
	v_mov_b32_e32 v87, v88
	v_mov_b32_e32 v92, v88
	v_mov_b32_e32 v93, v88
	v_mov_b32_e32 v94, v88
	v_mov_b32_e32 v95, v88
	v_mov_b32_e32 v96, v88
	v_mov_b32_e32 v97, v88
	v_mov_b32_e32 v98, v88
	v_mov_b32_e32 v99, v88
	v_mov_b32_e32 v100, v88
	v_mov_b32_e32 v101, v88
	v_mov_b32_e32 v102, v88
	v_mov_b32_e32 v103, v88
	v_mov_b32_e32 v108, v88
	v_mov_b32_e32 v109, v88
	v_mov_b32_e32 v110, v88
	v_mov_b32_e32 v111, v88
	v_mov_b32_e32 v112, v88
	v_mov_b32_e32 v113, v88
	v_mov_b32_e32 v114, v88
	v_mov_b32_e32 v115, v88
	v_mov_b32_e32 v116, v88
	v_mov_b32_e32 v117, v88
	v_mov_b32_e32 v118, v88
	v_mov_b32_e32 v119, v88
	v_mov_b32_e32 v120, v88
	v_mov_b32_e32 v121, v88
	v_mov_b32_e32 v122, v88
	v_mov_b32_e32 v123, v88
	v_mov_b32_e32 v124, v88
	v_mov_b32_e32 v125, v88
	v_mov_b32_e32 v126, v88
	v_mov_b32_e32 v127, v88
	s_waitcnt vmcnt(0) lgkmcnt(0)
	s_barrier
	v_bfe_u32 v250, v178, 3, 3
	v_and_b32_e32 v251, 7, v178
	v_lshrrev_b32_e32 v252, 1, v250
	v_xor_b32_e32 v251, v251, v252
	v_lshlrev_b32_e32 v251, 4, v251
	v_lshl_or_b32 v250, v250, 11, v251
	v_xor_b32_e32 v251, 64, v250
	v_add_u32_e32 v251, 0x4000, v251
	v_add_u32_e32 v252, 0x8000, v250
	v_add_u32_e32 v253, 0x8000, v251
	v_lshl_add_u64 v[242:243], v[142:143], 0, s[40:41]
	v_lshl_add_u64 v[242:243], v[242:243], 0, s[18:19]
	v_lshl_add_u64 v[244:245], v[144:145], 0, s[40:41]
	v_lshl_add_u64 v[244:245], v[244:245], 0, s[20:21]
	v_add_u32_e32 v254, v128, v151
	v_add_u32_e32 v255, v139, v151
	v_readfirstlane_b32 s98, v242
	v_readfirstlane_b32 s99, v243
	v_readfirstlane_b32 s100, v244
	v_readfirstlane_b32 s101, v245
	ds_read_b128 v[164:167], v254
	ds_read_b128 v[168:171], v254 offset:2048
	ds_read_b128 v[156:159], v255 offset:32768
	ds_read_b128 v[160:163], v255 offset:34816
	ds_read_b128 v[172:175], v255 offset:36864
	ds_read_b128 v[188:191], v255 offset:38912
	s_nop 4
	s_lshl_b32 m0, s40, 9
	s_and_b32 m0, m0, 0x10000
	s_xor_b32 m0, m0, 0x10000
	s_add_i32 m0, m0, s10
	s_nop 0
	global_load_lds_dwordx4 v250, s[98:99]
	s_add_i32 m0, m0, 0x8000
	s_nop 0
	global_load_lds_dwordx4 v250, s[100:101]
	s_add_i32 m0, m0, 0xffff8400
	s_nop 0
	global_load_lds_dwordx4 v251, s[98:99]
	s_add_i32 m0, m0, 0x8000
	s_nop 0
	global_load_lds_dwordx4 v251, s[100:101]
.LBB0_1243:
	ds_read_b128 v[242:245], v254 offset:4096
	ds_read_b128 v[246:249], v254 offset:6144
	s_lshl_b32 m0, s40, 9
	s_and_b32 m0, m0, 0x10000
	s_xor_b32 m0, m0, 0x10000
	s_add_i32 m0, m0, s10
	s_add_i32 m0, m0, 0x800
	s_waitcnt lgkmcnt(5)
	v_mfma_f32_16x16x32_bf16 v[124:127], v[156:159], v[164:167], v[124:127]
	global_load_lds_dwordx4 v252, s[98:99]
	s_add_i32 m0, m0, 0x8000
	v_mfma_f32_16x16x32_bf16 v[108:111], v[156:159], v[168:171], v[108:111]
	s_waitcnt lgkmcnt(4)
	v_mfma_f32_16x16x32_bf16 v[120:123], v[160:163], v[164:167], v[120:123]
	global_load_lds_dwordx4 v252, s[100:101]
	s_add_i32 m0, m0, 0xffff8400
	v_mfma_f32_16x16x32_bf16 v[100:103], v[160:163], v[168:171], v[100:103]
	s_waitcnt lgkmcnt(3)
	v_mfma_f32_16x16x32_bf16 v[116:119], v[172:175], v[164:167], v[116:119]
	global_load_lds_dwordx4 v253, s[98:99]
	s_add_i32 m0, m0, 0x8000
	v_mfma_f32_16x16x32_bf16 v[96:99], v[172:175], v[168:171], v[96:99]
	s_waitcnt lgkmcnt(2)
	v_mfma_f32_16x16x32_bf16 v[112:115], v[188:191], v[164:167], v[112:115]
	global_load_lds_dwordx4 v253, s[100:101]
	v_mfma_f32_16x16x32_bf16 v[92:95], v[188:191], v[168:171], v[92:95]
	s_add_u32 s98, s98, 0x80
	s_addc_u32 s99, s99, 0
	s_add_u32 s100, s100, 0x80
	s_addc_u32 s101, s101, 0
	ds_read_b128 v[164:167], v254 offset:8192
	ds_read_b128 v[168:171], v254 offset:10240
	s_waitcnt lgkmcnt(2)
	v_mfma_f32_16x16x32_bf16 v[84:87], v[156:159], v[242:245], v[84:87]
	s_add_i32 s44, s42, 0x10000
	v_mfma_f32_16x16x32_bf16 v[68:71], v[156:159], v[246:249], v[68:71]
	s_and_b32 s42, s42, 0x10000
	v_mfma_f32_16x16x32_bf16 v[80:83], v[160:163], v[242:245], v[80:83]
	s_and_b32 s43, s44, 0x10000
	v_mfma_f32_16x16x32_bf16 v[64:67], v[160:163], v[246:249], v[64:67]
	s_add_i32 s42, s42, 0
	v_mfma_f32_16x16x32_bf16 v[76:79], v[172:175], v[242:245], v[76:79]
	s_add_i32 s43, s43, 0
	v_mfma_f32_16x16x32_bf16 v[60:63], v[172:175], v[246:249], v[60:63]
	s_add_i32 s42, s43, s10
	v_mfma_f32_16x16x32_bf16 v[72:75], v[188:191], v[242:245], v[72:75]
	s_add_i32 s45, s43, s53
	v_mfma_f32_16x16x32_bf16 v[56:59], v[188:191], v[246:249], v[56:59]
	s_add_i32 s46, s43, s52
	s_add_i32 s47, s43, s39
	s_add_u32 s40, s40, 0x80
	s_addc_u32 s41, s41, 0
	s_mov_b32 s42, s44
	s_cmpk_eq_i32 s40, 0x780
	ds_read_b128 v[242:245], v254 offset:12288
	ds_read_b128 v[246:249], v254 offset:14336
	s_waitcnt lgkmcnt(2)
	v_mfma_f32_16x16x32_bf16 v[52:55], v[156:159], v[164:167], v[52:55]
	v_mfma_f32_16x16x32_bf16 v[36:39], v[156:159], v[168:171], v[36:39]
	v_mfma_f32_16x16x32_bf16 v[48:51], v[160:163], v[164:167], v[48:51]
	v_mfma_f32_16x16x32_bf16 v[32:35], v[160:163], v[168:171], v[32:35]
	v_mfma_f32_16x16x32_bf16 v[44:47], v[172:175], v[164:167], v[44:47]
	v_mfma_f32_16x16x32_bf16 v[28:31], v[172:175], v[168:171], v[28:31]
	v_mfma_f32_16x16x32_bf16 v[40:43], v[188:191], v[164:167], v[40:43]
	v_mfma_f32_16x16x32_bf16 v[24:27], v[188:191], v[168:171], v[24:27]
	v_xor_b32_e32 v254, 64, v254
	v_xor_b32_e32 v255, 64, v255
	ds_read_b128 v[164:167], v254
	ds_read_b128 v[168:171], v254 offset:2048
	s_waitcnt lgkmcnt(2)
	v_mfma_f32_16x16x32_bf16 v[20:23], v[156:159], v[242:245], v[20:23]
	v_mfma_f32_16x16x32_bf16 v[4:7], v[156:159], v[246:249], v[4:7]
	ds_read_b128 v[156:159], v255 offset:32768
	v_mfma_f32_16x16x32_bf16 v[16:19], v[160:163], v[242:245], v[16:19]
	v_mfma_f32_16x16x32_bf16 v[0:3], v[160:163], v[246:249], v[0:3]
	ds_read_b128 v[160:163], v255 offset:34816
	v_mfma_f32_16x16x32_bf16 v[12:15], v[172:175], v[242:245], v[12:15]
	v_mfma_f32_16x16x32_bf16 v[104:107], v[172:175], v[246:249], v[104:107]
	ds_read_b128 v[172:175], v255 offset:36864
	v_mfma_f32_16x16x32_bf16 v[8:11], v[188:191], v[242:245], v[8:11]
	v_mfma_f32_16x16x32_bf16 v[88:91], v[188:191], v[246:249], v[88:91]
	ds_read_b128 v[188:191], v255 offset:38912
	ds_read_b128 v[242:245], v254 offset:4096
	ds_read_b128 v[246:249], v254 offset:6144
	s_waitcnt lgkmcnt(5)
	v_mfma_f32_16x16x32_bf16 v[124:127], v[156:159], v[164:167], v[124:127]
	v_mfma_f32_16x16x32_bf16 v[108:111], v[156:159], v[168:171], v[108:111]
	s_waitcnt lgkmcnt(4)
	v_mfma_f32_16x16x32_bf16 v[120:123], v[160:163], v[164:167], v[120:123]
	v_mfma_f32_16x16x32_bf16 v[100:103], v[160:163], v[168:171], v[100:103]
	s_waitcnt lgkmcnt(3)
	v_mfma_f32_16x16x32_bf16 v[116:119], v[172:175], v[164:167], v[116:119]
	v_mfma_f32_16x16x32_bf16 v[96:99], v[172:175], v[168:171], v[96:99]
	s_waitcnt lgkmcnt(2)
	v_mfma_f32_16x16x32_bf16 v[112:115], v[188:191], v[164:167], v[112:115]
	v_mfma_f32_16x16x32_bf16 v[92:95], v[188:191], v[168:171], v[92:95]
	ds_read_b128 v[164:167], v254 offset:8192
	ds_read_b128 v[168:171], v254 offset:10240
	s_waitcnt lgkmcnt(2)
	v_mfma_f32_16x16x32_bf16 v[84:87], v[156:159], v[242:245], v[84:87]
	v_mfma_f32_16x16x32_bf16 v[68:71], v[156:159], v[246:249], v[68:71]
	v_mfma_f32_16x16x32_bf16 v[80:83], v[160:163], v[242:245], v[80:83]
	v_mfma_f32_16x16x32_bf16 v[64:67], v[160:163], v[246:249], v[64:67]
	v_mfma_f32_16x16x32_bf16 v[76:79], v[172:175], v[242:245], v[76:79]
	v_mfma_f32_16x16x32_bf16 v[60:63], v[172:175], v[246:249], v[60:63]
	v_mfma_f32_16x16x32_bf16 v[72:75], v[188:191], v[242:245], v[72:75]
	v_mfma_f32_16x16x32_bf16 v[56:59], v[188:191], v[246:249], v[56:59]
	ds_read_b128 v[242:245], v254 offset:12288
	ds_read_b128 v[246:249], v254 offset:14336
	s_waitcnt lgkmcnt(2)
	v_mfma_f32_16x16x32_bf16 v[52:55], v[156:159], v[164:167], v[52:55]
	v_mfma_f32_16x16x32_bf16 v[36:39], v[156:159], v[168:171], v[36:39]
	v_mfma_f32_16x16x32_bf16 v[48:51], v[160:163], v[164:167], v[48:51]
	v_mfma_f32_16x16x32_bf16 v[32:35], v[160:163], v[168:171], v[32:35]
	v_mfma_f32_16x16x32_bf16 v[44:47], v[172:175], v[164:167], v[44:47]
	v_mfma_f32_16x16x32_bf16 v[28:31], v[172:175], v[168:171], v[28:31]
	v_mfma_f32_16x16x32_bf16 v[40:43], v[188:191], v[164:167], v[40:43]
	v_mfma_f32_16x16x32_bf16 v[24:27], v[188:191], v[168:171], v[24:27]
	s_waitcnt vmcnt(0) lgkmcnt(0)
	s_barrier
	s_cmpk_eq_i32 s40, 0x780
	s_cbranch_scc1 .Lgx_1243
	v_xor_b32_e32 v254, 0x10040, v254
	v_xor_b32_e32 v255, 0x10040, v255
	ds_read_b128 v[164:167], v254
	ds_read_b128 v[168:171], v254 offset:2048
	s_lshl_b32 m0, s40, 9
	s_and_b32 m0, m0, 0x10000
	s_xor_b32 m0, m0, 0x10000
	s_add_i32 m0, m0, s10
	v_mfma_f32_16x16x32_bf16 v[20:23], v[156:159], v[242:245], v[20:23]
	global_load_lds_dwordx4 v250, s[98:99]
	s_add_i32 m0, m0, 0x8000
	v_mfma_f32_16x16x32_bf16 v[4:7], v[156:159], v[246:249], v[4:7]
	ds_read_b128 v[156:159], v255 offset:32768
	v_mfma_f32_16x16x32_bf16 v[16:19], v[160:163], v[242:245], v[16:19]
	global_load_lds_dwordx4 v250, s[100:101]
	s_add_i32 m0, m0, 0xffff8400
	v_mfma_f32_16x16x32_bf16 v[0:3], v[160:163], v[246:249], v[0:3]
	ds_read_b128 v[160:163], v255 offset:34816
	v_mfma_f32_16x16x32_bf16 v[12:15], v[172:175], v[242:245], v[12:15]
	global_load_lds_dwordx4 v251, s[98:99]
	s_add_i32 m0, m0, 0x8000
	v_mfma_f32_16x16x32_bf16 v[104:107], v[172:175], v[246:249], v[104:107]
	ds_read_b128 v[172:175], v255 offset:36864
	v_mfma_f32_16x16x32_bf16 v[8:11], v[188:191], v[242:245], v[8:11]
	global_load_lds_dwordx4 v251, s[100:101]
	v_mfma_f32_16x16x32_bf16 v[88:91], v[188:191], v[246:249], v[88:91]
	ds_read_b128 v[188:191], v255 offset:38912
	s_branch .LBB0_1243
.Lgx_1243:
	v_mfma_f32_16x16x32_bf16 v[20:23], v[156:159], v[242:245], v[20:23]
	v_mfma_f32_16x16x32_bf16 v[4:7], v[156:159], v[246:249], v[4:7]
	v_mfma_f32_16x16x32_bf16 v[16:19], v[160:163], v[242:245], v[16:19]
	v_mfma_f32_16x16x32_bf16 v[0:3], v[160:163], v[246:249], v[0:3]
	v_mfma_f32_16x16x32_bf16 v[12:15], v[172:175], v[242:245], v[12:15]
	v_mfma_f32_16x16x32_bf16 v[104:107], v[172:175], v[246:249], v[104:107]
	v_mfma_f32_16x16x32_bf16 v[8:11], v[188:191], v[242:245], v[8:11]
	v_mfma_f32_16x16x32_bf16 v[88:91], v[188:191], v[246:249], v[88:91]
	v_add_u32_e32 v139, s43, v139
	v_add_u32_e32 v141, v139, v151
	v_add_u32_e32 v128, s43, v128
	ds_read_b128 v[142:145], v141 offset:32768
	v_add_u32_e32 v155, v128, v151
	ds_read_b128 v[146:149], v141 offset:34816
	ds_read_b128 v[156:159], v155
	ds_read_b128 v[160:163], v155 offset:2048
	ds_read_b128 v[164:167], v141 offset:36864
	ds_read_b128 v[168:171], v141 offset:38912
	s_waitcnt lgkmcnt(3)
	v_mfma_f32_16x16x32_bf16 v[120:123], v[146:149], v[156:159], v[120:123]
	v_add_u32_e32 v128, v128, v152
	s_and_b64 vcc, exec, s[2:3]
	v_mfma_f32_16x16x32_bf16 v[124:127], v[142:145], v[156:159], v[124:127]
	s_waitcnt lgkmcnt(1)
	v_mfma_f32_16x16x32_bf16 v[116:119], v[164:167], v[156:159], v[116:119]
	s_waitcnt lgkmcnt(0)
	v_mfma_f32_16x16x32_bf16 v[112:115], v[168:171], v[156:159], v[112:115]
	v_mfma_f32_16x16x32_bf16 v[108:111], v[142:145], v[160:163], v[108:111]
	v_mfma_f32_16x16x32_bf16 v[100:103], v[146:149], v[160:163], v[100:103]
	v_mfma_f32_16x16x32_bf16 v[96:99], v[164:167], v[160:163], v[96:99]
	v_mfma_f32_16x16x32_bf16 v[92:95], v[168:171], v[160:163], v[92:95]
	ds_read_b128 v[156:159], v155 offset:4096
	ds_read_b128 v[160:163], v155 offset:6144
	s_waitcnt lgkmcnt(1)
	v_mfma_f32_16x16x32_bf16 v[84:87], v[142:145], v[156:159], v[84:87]
	v_mfma_f32_16x16x32_bf16 v[80:83], v[146:149], v[156:159], v[80:83]
	v_mfma_f32_16x16x32_bf16 v[76:79], v[164:167], v[156:159], v[76:79]
	v_mfma_f32_16x16x32_bf16 v[72:75], v[168:171], v[156:159], v[72:75]
	s_waitcnt lgkmcnt(0)
	v_mfma_f32_16x16x32_bf16 v[68:71], v[142:145], v[160:163], v[68:71]
	v_mfma_f32_16x16x32_bf16 v[64:67], v[146:149], v[160:163], v[64:67]
	v_mfma_f32_16x16x32_bf16 v[60:63], v[164:167], v[160:163], v[60:63]
	v_mfma_f32_16x16x32_bf16 v[56:59], v[168:171], v[160:163], v[56:59]
	ds_read_b128 v[156:159], v155 offset:8192
	ds_read_b128 v[160:163], v155 offset:10240
	s_waitcnt lgkmcnt(1)
	v_mfma_f32_16x16x32_bf16 v[52:55], v[142:145], v[156:159], v[52:55]
	v_mfma_f32_16x16x32_bf16 v[48:51], v[146:149], v[156:159], v[48:51]
	v_mfma_f32_16x16x32_bf16 v[44:47], v[164:167], v[156:159], v[44:47]
	v_mfma_f32_16x16x32_bf16 v[40:43], v[168:171], v[156:159], v[40:43]
	s_waitcnt lgkmcnt(0)
	v_mfma_f32_16x16x32_bf16 v[36:39], v[142:145], v[160:163], v[36:39]
	v_mfma_f32_16x16x32_bf16 v[32:35], v[146:149], v[160:163], v[32:35]
	v_mfma_f32_16x16x32_bf16 v[28:31], v[164:167], v[160:163], v[28:31]
	v_mfma_f32_16x16x32_bf16 v[24:27], v[168:171], v[160:163], v[24:27]
	ds_read_b128 v[156:159], v155 offset:12288
	ds_read_b128 v[160:163], v155 offset:14336
	s_waitcnt lgkmcnt(1)
	v_mfma_f32_16x16x32_bf16 v[20:23], v[142:145], v[156:159], v[20:23]
	s_waitcnt lgkmcnt(0)
	v_mfma_f32_16x16x32_bf16 v[4:7], v[142:145], v[160:163], v[4:7]
	v_mfma_f32_16x16x32_bf16 v[142:145], v[164:167], v[160:163], v[104:107]
	s_nop 2
	v_add_u32_e32 v104, v139, v152
	v_mfma_f32_16x16x32_bf16 v[16:19], v[146:149], v[156:159], v[16:19]
	v_mfma_f32_16x16x32_bf16 v[12:15], v[164:167], v[156:159], v[12:15]
	v_mfma_f32_16x16x32_bf16 v[8:11], v[168:171], v[156:159], v[8:11]
	v_mfma_f32_16x16x32_bf16 v[0:3], v[146:149], v[160:163], v[0:3]
	ds_read_b128 v[146:149], v104 offset:32768
	v_mfma_f32_16x16x32_bf16 v[156:159], v[168:171], v[160:163], v[88:91]
	ds_read_b128 v[160:163], v104 offset:34816
	s_nop 1
	ds_read_b128 v[88:91], v128
	ds_read_b128 v[164:167], v128 offset:2048
	ds_read_b128 v[168:171], v104 offset:36864
	ds_read_b128 v[172:175], v104 offset:38912
	s_waitcnt lgkmcnt(2)
	v_mfma_f32_16x16x32_bf16 v[108:111], v[146:149], v[164:167], v[108:111]
	v_mfma_f32_16x16x32_bf16 v[104:107], v[160:163], v[164:167], v[100:103]
	s_waitcnt lgkmcnt(1)
	v_mfma_f32_16x16x32_bf16 v[100:103], v[168:171], v[164:167], v[96:99]
	s_waitcnt lgkmcnt(0)
	v_mfma_f32_16x16x32_bf16 v[96:99], v[172:175], v[164:167], v[92:95]
	ds_read_b128 v[164:167], v128 offset:4096
	ds_read_b128 v[188:191], v128 offset:6144
	v_mfma_f32_16x16x32_bf16 v[124:127], v[146:149], v[88:91], v[124:127]
	v_mfma_f32_16x16x32_bf16 v[120:123], v[160:163], v[88:91], v[120:123]
	v_mfma_f32_16x16x32_bf16 v[116:119], v[168:171], v[88:91], v[116:119]
	v_mfma_f32_16x16x32_bf16 v[112:115], v[172:175], v[88:91], v[112:115]
	s_waitcnt lgkmcnt(1)
	v_mfma_f32_16x16x32_bf16 v[92:95], v[146:149], v[164:167], v[84:87]
	v_mfma_f32_16x16x32_bf16 v[88:91], v[160:163], v[164:167], v[80:83]
	v_mfma_f32_16x16x32_bf16 v[84:87], v[168:171], v[164:167], v[76:79]
	v_mfma_f32_16x16x32_bf16 v[80:83], v[172:175], v[164:167], v[72:75]
	s_waitcnt lgkmcnt(0)
	v_mfma_f32_16x16x32_bf16 v[76:79], v[146:149], v[188:191], v[68:71]
	v_mfma_f32_16x16x32_bf16 v[72:75], v[160:163], v[188:191], v[64:67]
	v_mfma_f32_16x16x32_bf16 v[68:71], v[168:171], v[188:191], v[60:63]
	v_mfma_f32_16x16x32_bf16 v[64:67], v[172:175], v[188:191], v[56:59]
	ds_read_b128 v[164:167], v128 offset:8192
	ds_read_b128 v[188:191], v128 offset:10240
	s_waitcnt lgkmcnt(1)
	v_mfma_f32_16x16x32_bf16 v[60:63], v[146:149], v[164:167], v[52:55]
	v_mfma_f32_16x16x32_bf16 v[56:59], v[160:163], v[164:167], v[48:51]
	v_mfma_f32_16x16x32_bf16 v[52:55], v[168:171], v[164:167], v[44:47]
	v_mfma_f32_16x16x32_bf16 v[48:51], v[172:175], v[164:167], v[40:43]
	s_waitcnt lgkmcnt(0)
	v_mfma_f32_16x16x32_bf16 v[44:47], v[146:149], v[188:191], v[36:39]
	v_mfma_f32_16x16x32_bf16 v[40:43], v[160:163], v[188:191], v[32:35]
	v_mfma_f32_16x16x32_bf16 v[36:39], v[168:171], v[188:191], v[28:31]
	v_mfma_f32_16x16x32_bf16 v[32:35], v[172:175], v[188:191], v[24:27]
	ds_read_b128 v[164:167], v128 offset:12288
	ds_read_b128 v[188:191], v128 offset:14336
	s_waitcnt vmcnt(0)
	s_waitcnt lgkmcnt(0)
	v_mfma_f32_16x16x32_bf16 v[28:31], v[146:149], v[164:167], v[20:23]
	s_barrier
	v_mfma_f32_16x16x32_bf16 v[24:27], v[160:163], v[164:167], v[16:19]
	v_mfma_f32_16x16x32_bf16 v[20:23], v[168:171], v[164:167], v[12:15]
	v_mfma_f32_16x16x32_bf16 v[16:19], v[172:175], v[164:167], v[8:11]
	v_mfma_f32_16x16x32_bf16 v[12:15], v[146:149], v[188:191], v[4:7]
	v_mfma_f32_16x16x32_bf16 v[8:11], v[160:163], v[188:191], v[0:3]
	v_mfma_f32_16x16x32_bf16 v[4:7], v[168:171], v[188:191], v[142:145]
	v_mfma_f32_16x16x32_bf16 v[0:3], v[172:175], v[188:191], v[156:159]
	s_cbranch_vccz .LBB0_1246
	s_add_u32 s6, s60, s6
	s_addc_u32 s7, s61, s7
	s_lshl_b64 s[2:3], s[8:9], 1
	s_add_u32 s4, s4, s2
	s_addc_u32 s5, s5, s3
	s_add_u32 s2, s6, s2
	s_addc_u32 s3, s7, s3
	s_add_i32 s6, s10, 0
	v_mov_b32_e32 v139, v129
	s_mov_b32 m0, s6
	v_mov_b32_e32 v141, v129
	v_lshl_add_u64 v[142:143], s[4:5], 0, v[138:139]
	global_load_lds_dwordx4 v138, s[4:5]
	s_add_i32 m0, s6, 0x8000
	v_lshl_add_u64 v[146:147], s[4:5], 0, v[140:141]
	s_add_i32 s4, s53, 0
	global_load_lds_dwordx4 v138, s[2:3]
	v_lshl_add_u64 v[148:149], v[146:147], 0, s[12:13]
	s_mov_b32 m0, s4
	v_lshl_add_u64 v[144:145], s[2:3], 0, v[138:139]
	global_load_lds_dwordx4 v[148:149], off
	v_lshl_add_u64 v[148:149], s[2:3], 0, v[140:141]
	v_lshl_add_u64 v[156:157], v[148:149], 0, s[12:13]
	s_add_i32 m0, s4, 0x8000
	s_add_i32 s2, s52, 0
	global_load_lds_dwordx4 v[156:157], off
	v_lshl_add_u64 v[142:143], v[142:143], 0, s[14:15]
	s_mov_b32 m0, s2
	s_nop 0
	global_load_lds_dwordx4 v[142:143], off
	v_lshl_add_u64 v[142:143], v[144:145], 0, s[14:15]
	s_add_i32 m0, s2, 0x8000
	s_add_i32 s2, s39, 0
	global_load_lds_dwordx4 v[142:143], off
	v_lshl_add_u64 v[142:143], v[146:147], 0, s[16:17]
	s_mov_b32 m0, s2
	s_nop 0
	global_load_lds_dwordx4 v[142:143], off
	v_lshl_add_u64 v[142:143], v[148:149], 0, s[16:17]
	s_add_i32 m0, s2, 0x8000
	s_nop 0
	global_load_lds_dwordx4 v[142:143], off

.LBB0_1555:
	ds_read_b128 v[242:245], v254 offset:4096
	ds_read_b128 v[246:249], v254 offset:6144
	s_lshl_b32 m0, s40, 9
	s_and_b32 m0, m0, 0x10000
	s_xor_b32 m0, m0, 0x10000
	s_add_i32 m0, m0, s2
	s_add_i32 m0, m0, 0x800
	s_waitcnt lgkmcnt(5)
	v_mfma_f32_16x16x32_bf16 v[124:127], v[154:157], v[162:165], v[124:127]
	global_load_lds_dwordx4 v252, s[98:99]
	s_add_i32 m0, m0, 0x8000
	v_mfma_f32_16x16x32_bf16 v[108:111], v[154:157], v[166:169], v[108:111]
	s_waitcnt lgkmcnt(4)
	v_mfma_f32_16x16x32_bf16 v[120:123], v[158:161], v[162:165], v[120:123]
	global_load_lds_dwordx4 v252, s[100:101]
	s_add_i32 m0, m0, 0xffff8400
	v_mfma_f32_16x16x32_bf16 v[100:103], v[158:161], v[166:169], v[100:103]
	s_waitcnt lgkmcnt(3)
	v_mfma_f32_16x16x32_bf16 v[116:119], v[170:173], v[162:165], v[116:119]
	global_load_lds_dwordx4 v253, s[98:99]
	s_add_i32 m0, m0, 0x8000
	v_mfma_f32_16x16x32_bf16 v[96:99], v[170:173], v[166:169], v[96:99]
	s_waitcnt lgkmcnt(2)
	v_mfma_f32_16x16x32_bf16 v[112:115], v[174:177], v[162:165], v[112:115]
	global_load_lds_dwordx4 v253, s[100:101]
	v_mfma_f32_16x16x32_bf16 v[92:95], v[174:177], v[166:169], v[92:95]
	s_add_u32 s98, s98, 0x80
	s_addc_u32 s99, s99, 0
	s_add_u32 s100, s100, 0x80
	s_addc_u32 s101, s101, 0
	ds_read_b128 v[162:165], v254 offset:8192
	ds_read_b128 v[166:169], v254 offset:10240
	s_waitcnt lgkmcnt(2)
	v_mfma_f32_16x16x32_bf16 v[84:87], v[154:157], v[242:245], v[84:87]
	s_add_i32 s44, s42, 0x10000
	v_mfma_f32_16x16x32_bf16 v[68:71], v[154:157], v[246:249], v[68:71]
	s_and_b32 s42, s42, 0x10000
	v_mfma_f32_16x16x32_bf16 v[80:83], v[158:161], v[242:245], v[80:83]
	s_and_b32 s43, s44, 0x10000
	v_mfma_f32_16x16x32_bf16 v[64:67], v[158:161], v[246:249], v[64:67]
	s_add_i32 s42, s42, 0
	v_mfma_f32_16x16x32_bf16 v[76:79], v[170:173], v[242:245], v[76:79]
	s_add_i32 s43, s43, 0
	v_mfma_f32_16x16x32_bf16 v[60:63], v[170:173], v[246:249], v[60:63]
	s_add_i32 s42, s43, s2
	v_mfma_f32_16x16x32_bf16 v[72:75], v[174:177], v[242:245], v[72:75]
	s_add_i32 s45, s43, s63
	v_mfma_f32_16x16x32_bf16 v[56:59], v[174:177], v[246:249], v[56:59]
	s_add_i32 s46, s43, s62
	s_add_i32 s47, s43, s29
	s_add_u32 s40, s40, 0x80
	s_addc_u32 s41, s41, 0
	s_mov_b32 s42, s44
	s_cmpk_eq_i32 s40, 0x780
	ds_read_b128 v[242:245], v254 offset:12288
	ds_read_b128 v[246:249], v254 offset:14336
	s_waitcnt lgkmcnt(2)
	v_mfma_f32_16x16x32_bf16 v[52:55], v[154:157], v[162:165], v[52:55]
	v_mfma_f32_16x16x32_bf16 v[36:39], v[154:157], v[166:169], v[36:39]
	v_mfma_f32_16x16x32_bf16 v[48:51], v[158:161], v[162:165], v[48:51]
	v_mfma_f32_16x16x32_bf16 v[32:35], v[158:161], v[166:169], v[32:35]
	v_mfma_f32_16x16x32_bf16 v[44:47], v[170:173], v[162:165], v[44:47]
	v_mfma_f32_16x16x32_bf16 v[28:31], v[170:173], v[166:169], v[28:31]
	v_mfma_f32_16x16x32_bf16 v[40:43], v[174:177], v[162:165], v[40:43]
	v_mfma_f32_16x16x32_bf16 v[24:27], v[174:177], v[166:169], v[24:27]
	v_xor_b32_e32 v254, 64, v254
	v_xor_b32_e32 v255, 64, v255
	ds_read_b128 v[162:165], v254
	ds_read_b128 v[166:169], v254 offset:2048
	s_waitcnt lgkmcnt(2)
	v_mfma_f32_16x16x32_bf16 v[20:23], v[154:157], v[242:245], v[20:23]
	v_mfma_f32_16x16x32_bf16 v[4:7], v[154:157], v[246:249], v[4:7]
	ds_read_b128 v[154:157], v255 offset:32768
	v_mfma_f32_16x16x32_bf16 v[16:19], v[158:161], v[242:245], v[16:19]
	v_mfma_f32_16x16x32_bf16 v[0:3], v[158:161], v[246:249], v[0:3]
	ds_read_b128 v[158:161], v255 offset:34816
	v_mfma_f32_16x16x32_bf16 v[12:15], v[170:173], v[242:245], v[12:15]
	v_mfma_f32_16x16x32_bf16 v[104:107], v[170:173], v[246:249], v[104:107]
	ds_read_b128 v[170:173], v255 offset:36864
	v_mfma_f32_16x16x32_bf16 v[8:11], v[174:177], v[242:245], v[8:11]
	v_mfma_f32_16x16x32_bf16 v[88:91], v[174:177], v[246:249], v[88:91]
	ds_read_b128 v[174:177], v255 offset:38912
	ds_read_b128 v[242:245], v254 offset:4096
	ds_read_b128 v[246:249], v254 offset:6144
	s_waitcnt lgkmcnt(5)
	v_mfma_f32_16x16x32_bf16 v[124:127], v[154:157], v[162:165], v[124:127]
	v_mfma_f32_16x16x32_bf16 v[108:111], v[154:157], v[166:169], v[108:111]
	s_waitcnt lgkmcnt(4)
	v_mfma_f32_16x16x32_bf16 v[120:123], v[158:161], v[162:165], v[120:123]
	v_mfma_f32_16x16x32_bf16 v[100:103], v[158:161], v[166:169], v[100:103]
	s_waitcnt lgkmcnt(3)
	v_mfma_f32_16x16x32_bf16 v[116:119], v[170:173], v[162:165], v[116:119]
	v_mfma_f32_16x16x32_bf16 v[96:99], v[170:173], v[166:169], v[96:99]
	s_waitcnt lgkmcnt(2)
	v_mfma_f32_16x16x32_bf16 v[112:115], v[174:177], v[162:165], v[112:115]
	v_mfma_f32_16x16x32_bf16 v[92:95], v[174:177], v[166:169], v[92:95]
	ds_read_b128 v[162:165], v254 offset:8192
	ds_read_b128 v[166:169], v254 offset:10240
	s_waitcnt lgkmcnt(2)
	v_mfma_f32_16x16x32_bf16 v[84:87], v[154:157], v[242:245], v[84:87]
	v_mfma_f32_16x16x32_bf16 v[68:71], v[154:157], v[246:249], v[68:71]
	v_mfma_f32_16x16x32_bf16 v[80:83], v[158:161], v[242:245], v[80:83]
	v_mfma_f32_16x16x32_bf16 v[64:67], v[158:161], v[246:249], v[64:67]
	v_mfma_f32_16x16x32_bf16 v[76:79], v[170:173], v[242:245], v[76:79]
	v_mfma_f32_16x16x32_bf16 v[60:63], v[170:173], v[246:249], v[60:63]
	v_mfma_f32_16x16x32_bf16 v[72:75], v[174:177], v[242:245], v[72:75]
	v_mfma_f32_16x16x32_bf16 v[56:59], v[174:177], v[246:249], v[56:59]
	ds_read_b128 v[242:245], v254 offset:12288
	ds_read_b128 v[246:249], v254 offset:14336
	s_waitcnt lgkmcnt(2)
	v_mfma_f32_16x16x32_bf16 v[52:55], v[154:157], v[162:165], v[52:55]
	v_mfma_f32_16x16x32_bf16 v[36:39], v[154:157], v[166:169], v[36:39]
	v_mfma_f32_16x16x32_bf16 v[48:51], v[158:161], v[162:165], v[48:51]
	v_mfma_f32_16x16x32_bf16 v[32:35], v[158:161], v[166:169], v[32:35]
	v_mfma_f32_16x16x32_bf16 v[44:47], v[170:173], v[162:165], v[44:47]
	v_mfma_f32_16x16x32_bf16 v[28:31], v[170:173], v[166:169], v[28:31]
	v_mfma_f32_16x16x32_bf16 v[40:43], v[174:177], v[162:165], v[40:43]
	v_mfma_f32_16x16x32_bf16 v[24:27], v[174:177], v[166:169], v[24:27]
	s_waitcnt vmcnt(0) lgkmcnt(0)
	s_barrier
	s_cmpk_eq_i32 s40, 0x780
	s_cbranch_scc1 .Lgx_1555
	v_xor_b32_e32 v254, 0x10040, v254
	v_xor_b32_e32 v255, 0x10040, v255
	ds_read_b128 v[162:165], v254
	ds_read_b128 v[166:169], v254 offset:2048
	s_lshl_b32 m0, s40, 9
	s_and_b32 m0, m0, 0x10000
	s_xor_b32 m0, m0, 0x10000
	s_add_i32 m0, m0, s2
	v_mfma_f32_16x16x32_bf16 v[20:23], v[154:157], v[242:245], v[20:23]
	global_load_lds_dwordx4 v250, s[98:99]
	s_add_i32 m0, m0, 0x8000
	v_mfma_f32_16x16x32_bf16 v[4:7], v[154:157], v[246:249], v[4:7]
	ds_read_b128 v[154:157], v255 offset:32768
	v_mfma_f32_16x16x32_bf16 v[16:19], v[158:161], v[242:245], v[16:19]
	global_load_lds_dwordx4 v250, s[100:101]
	s_add_i32 m0, m0, 0xffff8400
	v_mfma_f32_16x16x32_bf16 v[0:3], v[158:161], v[246:249], v[0:3]
	ds_read_b128 v[158:161], v255 offset:34816
	v_mfma_f32_16x16x32_bf16 v[12:15], v[170:173], v[242:245], v[12:15]
	global_load_lds_dwordx4 v251, s[98:99]
	s_add_i32 m0, m0, 0x8000
	v_mfma_f32_16x16x32_bf16 v[104:107], v[170:173], v[246:249], v[104:107]
	ds_read_b128 v[170:173], v255 offset:36864
	v_mfma_f32_16x16x32_bf16 v[8:11], v[174:177], v[242:245], v[8:11]
	global_load_lds_dwordx4 v251, s[100:101]
	v_mfma_f32_16x16x32_bf16 v[88:91], v[174:177], v[246:249], v[88:91]
	ds_read_b128 v[174:177], v255 offset:38912
	s_branch .LBB0_1555
.Lgx_1555:
	v_mfma_f32_16x16x32_bf16 v[20:23], v[154:157], v[242:245], v[20:23]
	v_mfma_f32_16x16x32_bf16 v[4:7], v[154:157], v[246:249], v[4:7]
	v_mfma_f32_16x16x32_bf16 v[16:19], v[158:161], v[242:245], v[16:19]
	v_mfma_f32_16x16x32_bf16 v[0:3], v[158:161], v[246:249], v[0:3]
	v_mfma_f32_16x16x32_bf16 v[12:15], v[170:173], v[242:245], v[12:15]
	v_mfma_f32_16x16x32_bf16 v[104:107], v[170:173], v[246:249], v[104:107]
	v_mfma_f32_16x16x32_bf16 v[8:11], v[174:177], v[242:245], v[8:11]
	v_mfma_f32_16x16x32_bf16 v[88:91], v[174:177], v[246:249], v[88:91]
	v_add_u32_e32 v153, s43, v153
	v_add_u32_e32 v166, v153, v149
	v_add_u32_e32 v139, s43, v139
	ds_read_b128 v[140:143], v166 offset:32768
	v_add_u32_e32 v170, v139, v149
	ds_read_b128 v[144:147], v166 offset:34816
	ds_read_b128 v[154:157], v170
	ds_read_b128 v[158:161], v170 offset:2048
	ds_read_b128 v[162:165], v166 offset:36864
	ds_read_b128 v[166:169], v166 offset:38912
	s_waitcnt lgkmcnt(3)
	v_mfma_f32_16x16x32_bf16 v[120:123], v[144:147], v[154:157], v[120:123]
	v_add_u32_e32 v139, v139, v150
	s_and_b64 vcc, exec, s[30:31]
	v_mfma_f32_16x16x32_bf16 v[124:127], v[140:143], v[154:157], v[124:127]
	s_waitcnt lgkmcnt(1)
	v_mfma_f32_16x16x32_bf16 v[116:119], v[162:165], v[154:157], v[116:119]
	s_waitcnt lgkmcnt(0)
	v_mfma_f32_16x16x32_bf16 v[112:115], v[166:169], v[154:157], v[112:115]
	v_mfma_f32_16x16x32_bf16 v[108:111], v[140:143], v[158:161], v[108:111]
	v_mfma_f32_16x16x32_bf16 v[100:103], v[144:147], v[158:161], v[100:103]
	v_mfma_f32_16x16x32_bf16 v[96:99], v[162:165], v[158:161], v[96:99]
	v_mfma_f32_16x16x32_bf16 v[92:95], v[166:169], v[158:161], v[92:95]
	ds_read_b128 v[154:157], v170 offset:4096
	ds_read_b128 v[158:161], v170 offset:6144
	s_waitcnt lgkmcnt(1)
	v_mfma_f32_16x16x32_bf16 v[84:87], v[140:143], v[154:157], v[84:87]
	v_mfma_f32_16x16x32_bf16 v[80:83], v[144:147], v[154:157], v[80:83]
	v_mfma_f32_16x16x32_bf16 v[76:79], v[162:165], v[154:157], v[76:79]
	v_mfma_f32_16x16x32_bf16 v[72:75], v[166:169], v[154:157], v[72:75]
	s_waitcnt lgkmcnt(0)
	v_mfma_f32_16x16x32_bf16 v[68:71], v[140:143], v[158:161], v[68:71]
	v_mfma_f32_16x16x32_bf16 v[64:67], v[144:147], v[158:161], v[64:67]
	v_mfma_f32_16x16x32_bf16 v[60:63], v[162:165], v[158:161], v[60:63]
	v_mfma_f32_16x16x32_bf16 v[56:59], v[166:169], v[158:161], v[56:59]
	ds_read_b128 v[154:157], v170 offset:8192
	ds_read_b128 v[158:161], v170 offset:10240
	s_waitcnt lgkmcnt(1)
	v_mfma_f32_16x16x32_bf16 v[52:55], v[140:143], v[154:157], v[52:55]
	v_mfma_f32_16x16x32_bf16 v[48:51], v[144:147], v[154:157], v[48:51]
	v_mfma_f32_16x16x32_bf16 v[44:47], v[162:165], v[154:157], v[44:47]
	v_mfma_f32_16x16x32_bf16 v[40:43], v[166:169], v[154:157], v[40:43]
	s_waitcnt lgkmcnt(0)
	v_mfma_f32_16x16x32_bf16 v[36:39], v[140:143], v[158:161], v[36:39]
	v_mfma_f32_16x16x32_bf16 v[32:35], v[144:147], v[158:161], v[32:35]
	v_mfma_f32_16x16x32_bf16 v[28:31], v[162:165], v[158:161], v[28:31]
	v_mfma_f32_16x16x32_bf16 v[24:27], v[166:169], v[158:161], v[24:27]
	ds_read_b128 v[154:157], v170 offset:12288
	ds_read_b128 v[158:161], v170 offset:14336
	s_waitcnt lgkmcnt(1)
	v_mfma_f32_16x16x32_bf16 v[20:23], v[140:143], v[154:157], v[20:23]
	s_waitcnt lgkmcnt(0)
	v_mfma_f32_16x16x32_bf16 v[4:7], v[140:143], v[158:161], v[4:7]
	v_mfma_f32_16x16x32_bf16 v[140:143], v[162:165], v[158:161], v[104:107]
	s_nop 2
	v_add_u32_e32 v104, v153, v150
	v_mfma_f32_16x16x32_bf16 v[16:19], v[144:147], v[154:157], v[16:19]
	v_mfma_f32_16x16x32_bf16 v[12:15], v[162:165], v[154:157], v[12:15]
	v_mfma_f32_16x16x32_bf16 v[8:11], v[166:169], v[154:157], v[8:11]
	v_mfma_f32_16x16x32_bf16 v[0:3], v[144:147], v[158:161], v[0:3]
	ds_read_b128 v[144:147], v104 offset:32768
	v_mfma_f32_16x16x32_bf16 v[154:157], v[166:169], v[158:161], v[88:91]
	ds_read_b128 v[158:161], v104 offset:34816
	s_nop 1
	ds_read_b128 v[88:91], v139
	ds_read_b128 v[162:165], v139 offset:2048
	ds_read_b128 v[166:169], v104 offset:36864
	ds_read_b128 v[170:173], v104 offset:38912
	s_waitcnt lgkmcnt(2)
	v_mfma_f32_16x16x32_bf16 v[108:111], v[144:147], v[162:165], v[108:111]
	v_mfma_f32_16x16x32_bf16 v[104:107], v[158:161], v[162:165], v[100:103]
	s_waitcnt lgkmcnt(1)
	v_mfma_f32_16x16x32_bf16 v[100:103], v[166:169], v[162:165], v[96:99]
	s_waitcnt lgkmcnt(0)
	v_mfma_f32_16x16x32_bf16 v[96:99], v[170:173], v[162:165], v[92:95]
	ds_read_b128 v[162:165], v139 offset:4096
	ds_read_b128 v[174:177], v139 offset:6144
	v_mfma_f32_16x16x32_bf16 v[124:127], v[144:147], v[88:91], v[124:127]
	v_mfma_f32_16x16x32_bf16 v[120:123], v[158:161], v[88:91], v[120:123]
	v_mfma_f32_16x16x32_bf16 v[116:119], v[166:169], v[88:91], v[116:119]
	v_mfma_f32_16x16x32_bf16 v[112:115], v[170:173], v[88:91], v[112:115]
	s_waitcnt lgkmcnt(1)
	v_mfma_f32_16x16x32_bf16 v[92:95], v[144:147], v[162:165], v[84:87]
	v_mfma_f32_16x16x32_bf16 v[88:91], v[158:161], v[162:165], v[80:83]
	v_mfma_f32_16x16x32_bf16 v[84:87], v[166:169], v[162:165], v[76:79]
	v_mfma_f32_16x16x32_bf16 v[80:83], v[170:173], v[162:165], v[72:75]
	s_waitcnt lgkmcnt(0)
	v_mfma_f32_16x16x32_bf16 v[76:79], v[144:147], v[174:177], v[68:71]
	v_mfma_f32_16x16x32_bf16 v[72:75], v[158:161], v[174:177], v[64:67]
	v_mfma_f32_16x16x32_bf16 v[68:71], v[166:169], v[174:177], v[60:63]
	v_mfma_f32_16x16x32_bf16 v[64:67], v[170:173], v[174:177], v[56:59]
	ds_read_b128 v[162:165], v139 offset:8192
	ds_read_b128 v[174:177], v139 offset:10240
	s_waitcnt lgkmcnt(1)
	v_mfma_f32_16x16x32_bf16 v[60:63], v[144:147], v[162:165], v[52:55]
	v_mfma_f32_16x16x32_bf16 v[56:59], v[158:161], v[162:165], v[48:51]
	v_mfma_f32_16x16x32_bf16 v[52:55], v[166:169], v[162:165], v[44:47]
	v_mfma_f32_16x16x32_bf16 v[48:51], v[170:173], v[162:165], v[40:43]
	s_waitcnt lgkmcnt(0)
	v_mfma_f32_16x16x32_bf16 v[44:47], v[144:147], v[174:177], v[36:39]
	v_mfma_f32_16x16x32_bf16 v[40:43], v[158:161], v[174:177], v[32:35]
	v_mfma_f32_16x16x32_bf16 v[36:39], v[166:169], v[174:177], v[28:31]
	v_mfma_f32_16x16x32_bf16 v[32:35], v[170:173], v[174:177], v[24:27]
	ds_read_b128 v[162:165], v139 offset:12288
	ds_read_b128 v[174:177], v139 offset:14336
	s_waitcnt vmcnt(0)
	s_waitcnt lgkmcnt(0)
	v_mfma_f32_16x16x32_bf16 v[28:31], v[144:147], v[162:165], v[20:23]
	s_barrier
	v_mfma_f32_16x16x32_bf16 v[24:27], v[158:161], v[162:165], v[16:19]
	v_mfma_f32_16x16x32_bf16 v[20:23], v[166:169], v[162:165], v[12:15]
	v_mfma_f32_16x16x32_bf16 v[16:19], v[170:173], v[162:165], v[8:11]
	v_mfma_f32_16x16x32_bf16 v[12:15], v[144:147], v[174:177], v[4:7]
	v_mfma_f32_16x16x32_bf16 v[4:7], v[158:161], v[174:177], v[0:3]
	v_mfma_f32_16x16x32_bf16 v[8:11], v[166:169], v[174:177], v[140:143]
	v_mfma_f32_16x16x32_bf16 v[0:3], v[170:173], v[174:177], v[154:157]
	s_cbranch_vccz .LBB0_1547
	s_add_u32 s36, s54, s36
	s_addc_u32 s37, s55, s37
	s_lshl_b64 s[30:31], s[38:39], 1
	s_add_u32 s34, s34, s30
	s_addc_u32 s35, s35, s31
	s_add_u32 s30, s36, s30
	s_addc_u32 s31, s37, s31
	s_add_i32 s2, s2, 0
	s_mov_b32 m0, s2
	v_mov_b32_e32 v139, v129
	global_load_lds_dwordx4 v128, s[34:35]
	s_add_i32 m0, s2, 0x8000
	v_lshl_add_u64 v[144:145], s[34:35], 0, v[138:139]
	s_add_i32 s2, s63, 0
	global_load_lds_dwordx4 v128, s[30:31]
	v_lshl_add_u64 v[146:147], v[144:145], 0, s[4:5]
	s_mov_b32 m0, s2
	v_lshl_add_u64 v[140:141], s[34:35], 0, v[128:129]
	global_load_lds_dwordx4 v[146:147], off
	v_lshl_add_u64 v[146:147], s[30:31], 0, v[138:139]
	v_lshl_add_u64 v[154:155], v[146:147], 0, s[4:5]
	s_add_i32 m0, s2, 0x8000
	s_add_i32 s2, s62, 0
	v_lshl_add_u64 v[142:143], s[30:31], 0, v[128:129]
	global_load_lds_dwordx4 v[154:155], off
	v_lshl_add_u64 v[140:141], v[140:141], 0, s[6:7]
	s_mov_b32 m0, s2
	s_nop 0
	global_load_lds_dwordx4 v[140:141], off
	v_lshl_add_u64 v[140:141], v[142:143], 0, s[6:7]
	s_add_i32 m0, s2, 0x8000
	s_add_i32 s2, s29, 0
	global_load_lds_dwordx4 v[140:141], off
	v_lshl_add_u64 v[140:141], v[144:145], 0, s[8:9]
	s_mov_b32 m0, s2
	s_nop 0
	global_load_lds_dwordx4 v[140:141], off
	v_lshl_add_u64 v[140:141], v[146:147], 0, s[8:9]
	s_add_i32 m0, s2, 0x8000
	s_nop 0
	global_load_lds_dwordx4 v[140:141], off
	s_branch .LBB0_1547

.LBB0_1613:
	s_lshr_b32 s4, s3, 1
	s_and_b32 s4, s4, 0x1ffff80
	v_or_b32_e32 v0, s4, v154
	s_and_b32 s3, s3, 0xc0
	v_lshlrev_b32_e32 v128, 7, v0
	v_or_b32_e32 v0, s3, v154
	s_mov_b32 s3, s15
	s_lshl_b64 s[2:3], s[2:3], 16
	s_add_u32 s4, s2, s74
	v_lshlrev_b32_e32 v139, 7, v0
	v_lshl_add_u64 v[0:1], s[66:67], 0, v[130:131]
	s_addc_u32 s5, s3, s75
	s_waitcnt vmcnt(0)
	v_lshl_add_u64 v[142:143], v[0:1], 0, s[4:5]
	s_add_u32 s2, s2, s76
	v_lshl_add_u64 v[0:1], s[66:67], 0, v[134:135]
	s_addc_u32 s3, s3, s77
	v_lshl_add_u64 v[146:147], v[0:1], 0, s[4:5]
	v_mov_b32_e32 v0, 0
	v_lshl_add_u64 v[144:145], v[132:133], 0, s[2:3]
	v_lshl_add_u64 v[148:149], v[136:137], 0, s[2:3]
	s_mov_b64 s[2:3], 0
	s_mov_b32 s10, 0
	v_mov_b32_e32 v1, v0
	v_mov_b32_e32 v2, v0
	v_mov_b32_e32 v3, v0
	v_mov_b32_e32 v4, v0
	v_mov_b32_e32 v5, v0
	v_mov_b32_e32 v6, v0
	v_mov_b32_e32 v7, v0
	v_mov_b32_e32 v8, v0
	v_mov_b32_e32 v9, v0
	v_mov_b32_e32 v10, v0
	v_mov_b32_e32 v11, v0
	v_mov_b32_e32 v12, v0
	v_mov_b32_e32 v13, v0
	v_mov_b32_e32 v14, v0
	v_mov_b32_e32 v15, v0
	v_mov_b32_e32 v16, v0
	v_mov_b32_e32 v17, v0
	v_mov_b32_e32 v18, v0
	v_mov_b32_e32 v19, v0
	v_mov_b32_e32 v20, v0
	v_mov_b32_e32 v21, v0
	v_mov_b32_e32 v22, v0
	v_mov_b32_e32 v23, v0
	v_mov_b32_e32 v24, v0
	v_mov_b32_e32 v25, v0
	v_mov_b32_e32 v26, v0
	v_mov_b32_e32 v27, v0
	v_mov_b32_e32 v28, v0
	v_mov_b32_e32 v29, v0
	v_mov_b32_e32 v30, v0
	v_mov_b32_e32 v31, v0
	v_mov_b32_e32 v32, v0
	v_mov_b32_e32 v33, v0
	v_mov_b32_e32 v34, v0
	v_mov_b32_e32 v35, v0
	v_mov_b32_e32 v36, v0
	v_mov_b32_e32 v37, v0
	v_mov_b32_e32 v38, v0
	v_mov_b32_e32 v39, v0
	v_mov_b32_e32 v40, v0
	v_mov_b32_e32 v41, v0
	v_mov_b32_e32 v42, v0
	v_mov_b32_e32 v43, v0
	v_mov_b32_e32 v44, v0
	v_mov_b32_e32 v45, v0
	v_mov_b32_e32 v46, v0
	v_mov_b32_e32 v47, v0
	v_mov_b32_e32 v48, v0
	v_mov_b32_e32 v49, v0
	v_mov_b32_e32 v50, v0
	v_mov_b32_e32 v51, v0
	v_mov_b32_e32 v52, v0
	v_mov_b32_e32 v53, v0
	v_mov_b32_e32 v54, v0
	v_mov_b32_e32 v55, v0
	v_mov_b32_e32 v56, v0
	v_mov_b32_e32 v57, v0
	v_mov_b32_e32 v58, v0
	v_mov_b32_e32 v59, v0
	v_mov_b32_e32 v60, v0
	v_mov_b32_e32 v61, v0
	v_mov_b32_e32 v62, v0
	v_mov_b32_e32 v63, v0
	v_mov_b32_e32 v64, v0
	v_mov_b32_e32 v65, v0
	v_mov_b32_e32 v66, v0
	v_mov_b32_e32 v67, v0
	v_mov_b32_e32 v68, v0
	v_mov_b32_e32 v69, v0
	v_mov_b32_e32 v70, v0
	v_mov_b32_e32 v71, v0
	v_mov_b32_e32 v72, v0
	v_mov_b32_e32 v73, v0
	v_mov_b32_e32 v74, v0
	v_mov_b32_e32 v75, v0
	v_mov_b32_e32 v76, v0
	v_mov_b32_e32 v77, v0
	v_mov_b32_e32 v78, v0
	v_mov_b32_e32 v79, v0
	v_mov_b32_e32 v80, v0
	v_mov_b32_e32 v81, v0
	v_mov_b32_e32 v82, v0
	v_mov_b32_e32 v83, v0
	v_mov_b32_e32 v84, v0
	v_mov_b32_e32 v85, v0
	v_mov_b32_e32 v86, v0
	v_mov_b32_e32 v87, v0
	v_mov_b32_e32 v88, v0
	v_mov_b32_e32 v89, v0
	v_mov_b32_e32 v90, v0
	v_mov_b32_e32 v91, v0
	v_mov_b32_e32 v92, v0
	v_mov_b32_e32 v93, v0
	v_mov_b32_e32 v94, v0
	v_mov_b32_e32 v95, v0
	v_mov_b32_e32 v96, v0
	v_mov_b32_e32 v97, v0
	v_mov_b32_e32 v98, v0
	v_mov_b32_e32 v99, v0
	v_mov_b32_e32 v100, v0
	v_mov_b32_e32 v101, v0
	v_mov_b32_e32 v102, v0
	v_mov_b32_e32 v103, v0
	v_mov_b32_e32 v104, v0
	v_mov_b32_e32 v105, v0
	v_mov_b32_e32 v106, v0
	v_mov_b32_e32 v107, v0
	v_mov_b32_e32 v108, v0
	v_mov_b32_e32 v109, v0
	v_mov_b32_e32 v110, v0
	v_mov_b32_e32 v111, v0
	v_mov_b32_e32 v112, v0
	v_mov_b32_e32 v113, v0
	v_mov_b32_e32 v114, v0
	v_mov_b32_e32 v115, v0
	v_mov_b32_e32 v116, v0
	v_mov_b32_e32 v117, v0
	v_mov_b32_e32 v118, v0
	v_mov_b32_e32 v119, v0
	v_mov_b32_e32 v120, v0
	v_mov_b32_e32 v121, v0
	v_mov_b32_e32 v122, v0
	v_mov_b32_e32 v123, v0
	v_mov_b32_e32 v124, v0
	v_mov_b32_e32 v125, v0
	v_mov_b32_e32 v126, v0
	v_mov_b32_e32 v127, v0
	s_waitcnt vmcnt(0) lgkmcnt(0)
	s_barrier
	v_bfe_u32 v250, v178, 3, 3
	v_and_b32_e32 v251, 7, v178
	v_lshrrev_b32_e32 v252, 1, v250
	v_xor_b32_e32 v251, v251, v252
	v_lshlrev_b32_e32 v251, 4, v251
	v_lshl_or_b32 v250, v250, 11, v251
	v_xor_b32_e32 v251, 64, v250
	v_add_u32_e32 v251, 0x4000, v251
	v_add_u32_e32 v252, 0x8000, v250
	v_add_u32_e32 v253, 0x8000, v251
	v_lshl_add_u64 v[242:243], v[142:143], 0, s[2:3]
	v_lshl_add_u64 v[242:243], v[242:243], 0, s[38:39]
	v_lshl_add_u64 v[244:245], v[144:145], 0, s[2:3]
	v_lshl_add_u64 v[244:245], v[244:245], 0, s[40:41]
	v_add_u32_e32 v254, v128, v155
	v_add_u32_e32 v255, v139, v155
	v_readfirstlane_b32 s98, v242
	v_readfirstlane_b32 s99, v243
	v_readfirstlane_b32 s100, v244
	v_readfirstlane_b32 s101, v245
	ds_read_b128 v[208:211], v254
	ds_read_b128 v[212:215], v254 offset:2048
	ds_read_b128 v[150:153], v255 offset:32768
	ds_read_b128 v[196:199], v255 offset:34816
	ds_read_b128 v[200:203], v255 offset:36864
	ds_read_b128 v[204:207], v255 offset:38912
	s_nop 4
	s_lshl_b32 m0, s2, 9
	s_and_b32 m0, m0, 0x10000
	s_xor_b32 m0, m0, 0x10000
	s_add_i32 m0, m0, s6
	s_nop 0
	global_load_lds_dwordx4 v250, s[98:99]
	s_add_i32 m0, m0, 0x8000
	s_nop 0
	global_load_lds_dwordx4 v250, s[100:101]
	s_add_i32 m0, m0, 0xffff8400
	s_nop 0
	global_load_lds_dwordx4 v251, s[98:99]
	s_add_i32 m0, m0, 0x8000
	s_nop 0
	global_load_lds_dwordx4 v251, s[100:101]
.LBB0_1614:
	ds_read_b128 v[242:245], v254 offset:4096
	ds_read_b128 v[246:249], v254 offset:6144
	s_lshl_b32 m0, s2, 9
	s_and_b32 m0, m0, 0x10000
	s_xor_b32 m0, m0, 0x10000
	s_add_i32 m0, m0, s6
	s_add_i32 m0, m0, 0x800
	s_waitcnt lgkmcnt(5)
	v_mfma_f32_16x16x32_bf16 v[124:127], v[150:153], v[208:211], v[124:127]
	global_load_lds_dwordx4 v252, s[98:99]
	s_add_i32 m0, m0, 0x8000
	v_mfma_f32_16x16x32_bf16 v[108:111], v[150:153], v[212:215], v[108:111]
	s_waitcnt lgkmcnt(4)
	v_mfma_f32_16x16x32_bf16 v[120:123], v[196:199], v[208:211], v[120:123]
	global_load_lds_dwordx4 v252, s[100:101]
	s_add_i32 m0, m0, 0xffff8400
	v_mfma_f32_16x16x32_bf16 v[104:107], v[196:199], v[212:215], v[104:107]
	s_waitcnt lgkmcnt(3)
	v_mfma_f32_16x16x32_bf16 v[116:119], v[200:203], v[208:211], v[116:119]
	global_load_lds_dwordx4 v253, s[98:99]
	s_add_i32 m0, m0, 0x8000
	v_mfma_f32_16x16x32_bf16 v[100:103], v[200:203], v[212:215], v[100:103]
	s_waitcnt lgkmcnt(2)
	v_mfma_f32_16x16x32_bf16 v[112:115], v[204:207], v[208:211], v[112:115]
	global_load_lds_dwordx4 v253, s[100:101]
	v_mfma_f32_16x16x32_bf16 v[96:99], v[204:207], v[212:215], v[96:99]
	s_add_u32 s98, s98, 0x80
	s_addc_u32 s99, s99, 0
	s_add_u32 s100, s100, 0x80
	s_addc_u32 s101, s101, 0
	ds_read_b128 v[208:211], v254 offset:8192
	ds_read_b128 v[212:215], v254 offset:10240
	s_waitcnt lgkmcnt(2)
	v_mfma_f32_16x16x32_bf16 v[92:95], v[150:153], v[242:245], v[92:95]
	s_add_i32 s5, s10, 0x10000
	v_mfma_f32_16x16x32_bf16 v[76:79], v[150:153], v[246:249], v[76:79]
	s_and_b32 s4, s5, 0x10000
	v_mfma_f32_16x16x32_bf16 v[88:91], v[196:199], v[242:245], v[88:91]
	s_add_i32 s4, s4, 0
	v_mfma_f32_16x16x32_bf16 v[72:75], v[196:199], v[246:249], v[72:75]
	s_add_i32 s11, s4, s6
	v_mfma_f32_16x16x32_bf16 v[84:87], v[200:203], v[242:245], v[84:87]
	s_add_i32 s11, s4, s9
	v_mfma_f32_16x16x32_bf16 v[68:71], v[200:203], v[246:249], v[68:71]
	s_and_b32 s10, s10, 0x10000
	v_mfma_f32_16x16x32_bf16 v[80:83], v[204:207], v[242:245], v[80:83]
	s_add_i32 s11, s4, s8
	v_mfma_f32_16x16x32_bf16 v[64:67], v[204:207], v[246:249], v[64:67]
	s_add_i32 s10, s10, 0
	s_add_i32 s11, s4, s7
	s_add_u32 s2, s2, 0x80
	s_addc_u32 s3, s3, 0
	s_cmpk_eq_i32 s2, 0x780
	s_mov_b32 s10, s5
	ds_read_b128 v[242:245], v254 offset:12288
	ds_read_b128 v[246:249], v254 offset:14336
	s_waitcnt lgkmcnt(2)
	v_mfma_f32_16x16x32_bf16 v[60:63], v[150:153], v[208:211], v[60:63]
	v_mfma_f32_16x16x32_bf16 v[44:47], v[150:153], v[212:215], v[44:47]
	v_mfma_f32_16x16x32_bf16 v[56:59], v[196:199], v[208:211], v[56:59]
	v_mfma_f32_16x16x32_bf16 v[40:43], v[196:199], v[212:215], v[40:43]
	v_mfma_f32_16x16x32_bf16 v[52:55], v[200:203], v[208:211], v[52:55]
	v_mfma_f32_16x16x32_bf16 v[36:39], v[200:203], v[212:215], v[36:39]
	v_mfma_f32_16x16x32_bf16 v[48:51], v[204:207], v[208:211], v[48:51]
	v_mfma_f32_16x16x32_bf16 v[32:35], v[204:207], v[212:215], v[32:35]
	v_xor_b32_e32 v254, 64, v254
	v_xor_b32_e32 v255, 64, v255
	ds_read_b128 v[208:211], v254
	ds_read_b128 v[212:215], v254 offset:2048
	s_waitcnt lgkmcnt(2)
	v_mfma_f32_16x16x32_bf16 v[28:31], v[150:153], v[242:245], v[28:31]
	v_mfma_f32_16x16x32_bf16 v[12:15], v[150:153], v[246:249], v[12:15]
	ds_read_b128 v[150:153], v255 offset:32768
	v_mfma_f32_16x16x32_bf16 v[24:27], v[196:199], v[242:245], v[24:27]
	v_mfma_f32_16x16x32_bf16 v[8:11], v[196:199], v[246:249], v[8:11]
	ds_read_b128 v[196:199], v255 offset:34816
	v_mfma_f32_16x16x32_bf16 v[20:23], v[200:203], v[242:245], v[20:23]
	v_mfma_f32_16x16x32_bf16 v[4:7], v[200:203], v[246:249], v[4:7]
	ds_read_b128 v[200:203], v255 offset:36864
	v_mfma_f32_16x16x32_bf16 v[16:19], v[204:207], v[242:245], v[16:19]
	v_mfma_f32_16x16x32_bf16 v[0:3], v[204:207], v[246:249], v[0:3]
	ds_read_b128 v[204:207], v255 offset:38912
	ds_read_b128 v[242:245], v254 offset:4096
	ds_read_b128 v[246:249], v254 offset:6144
	s_waitcnt lgkmcnt(5)
	v_mfma_f32_16x16x32_bf16 v[124:127], v[150:153], v[208:211], v[124:127]
	v_mfma_f32_16x16x32_bf16 v[108:111], v[150:153], v[212:215], v[108:111]
	s_waitcnt lgkmcnt(4)
	v_mfma_f32_16x16x32_bf16 v[120:123], v[196:199], v[208:211], v[120:123]
	v_mfma_f32_16x16x32_bf16 v[104:107], v[196:199], v[212:215], v[104:107]
	s_waitcnt lgkmcnt(3)
	v_mfma_f32_16x16x32_bf16 v[116:119], v[200:203], v[208:211], v[116:119]
	v_mfma_f32_16x16x32_bf16 v[100:103], v[200:203], v[212:215], v[100:103]
	s_waitcnt lgkmcnt(2)
	v_mfma_f32_16x16x32_bf16 v[112:115], v[204:207], v[208:211], v[112:115]
	v_mfma_f32_16x16x32_bf16 v[96:99], v[204:207], v[212:215], v[96:99]
	ds_read_b128 v[208:211], v254 offset:8192
	ds_read_b128 v[212:215], v254 offset:10240
	s_waitcnt lgkmcnt(2)
	v_mfma_f32_16x16x32_bf16 v[92:95], v[150:153], v[242:245], v[92:95]
	v_mfma_f32_16x16x32_bf16 v[76:79], v[150:153], v[246:249], v[76:79]
	v_mfma_f32_16x16x32_bf16 v[88:91], v[196:199], v[242:245], v[88:91]
	v_mfma_f32_16x16x32_bf16 v[72:75], v[196:199], v[246:249], v[72:75]
	v_mfma_f32_16x16x32_bf16 v[84:87], v[200:203], v[242:245], v[84:87]
	v_mfma_f32_16x16x32_bf16 v[68:71], v[200:203], v[246:249], v[68:71]
	v_mfma_f32_16x16x32_bf16 v[80:83], v[204:207], v[242:245], v[80:83]
	v_mfma_f32_16x16x32_bf16 v[64:67], v[204:207], v[246:249], v[64:67]
	ds_read_b128 v[242:245], v254 offset:12288
	ds_read_b128 v[246:249], v254 offset:14336
	s_waitcnt lgkmcnt(2)
	v_mfma_f32_16x16x32_bf16 v[60:63], v[150:153], v[208:211], v[60:63]
	v_mfma_f32_16x16x32_bf16 v[44:47], v[150:153], v[212:215], v[44:47]
	v_mfma_f32_16x16x32_bf16 v[56:59], v[196:199], v[208:211], v[56:59]
	v_mfma_f32_16x16x32_bf16 v[40:43], v[196:199], v[212:215], v[40:43]
	v_mfma_f32_16x16x32_bf16 v[52:55], v[200:203], v[208:211], v[52:55]
	v_mfma_f32_16x16x32_bf16 v[36:39], v[200:203], v[212:215], v[36:39]
	v_mfma_f32_16x16x32_bf16 v[48:51], v[204:207], v[208:211], v[48:51]
	v_mfma_f32_16x16x32_bf16 v[32:35], v[204:207], v[212:215], v[32:35]
	s_waitcnt vmcnt(0) lgkmcnt(0)
	s_barrier
	s_cmpk_eq_i32 s2, 0x780
	s_cbranch_scc1 .Lgx_1614
	v_xor_b32_e32 v254, 0x10040, v254
	v_xor_b32_e32 v255, 0x10040, v255
	ds_read_b128 v[208:211], v254
	ds_read_b128 v[212:215], v254 offset:2048
	s_lshl_b32 m0, s2, 9
	s_and_b32 m0, m0, 0x10000
	s_xor_b32 m0, m0, 0x10000
	s_add_i32 m0, m0, s6
	v_mfma_f32_16x16x32_bf16 v[28:31], v[150:153], v[242:245], v[28:31]
	global_load_lds_dwordx4 v250, s[98:99]
	s_add_i32 m0, m0, 0x8000
	v_mfma_f32_16x16x32_bf16 v[12:15], v[150:153], v[246:249], v[12:15]
	ds_read_b128 v[150:153], v255 offset:32768
	v_mfma_f32_16x16x32_bf16 v[24:27], v[196:199], v[242:245], v[24:27]
	global_load_lds_dwordx4 v250, s[100:101]
	s_add_i32 m0, m0, 0xffff8400
	v_mfma_f32_16x16x32_bf16 v[8:11], v[196:199], v[246:249], v[8:11]
	ds_read_b128 v[196:199], v255 offset:34816
	v_mfma_f32_16x16x32_bf16 v[20:23], v[200:203], v[242:245], v[20:23]
	global_load_lds_dwordx4 v251, s[98:99]
	s_add_i32 m0, m0, 0x8000
	v_mfma_f32_16x16x32_bf16 v[4:7], v[200:203], v[246:249], v[4:7]
	ds_read_b128 v[200:203], v255 offset:36864
	v_mfma_f32_16x16x32_bf16 v[16:19], v[204:207], v[242:245], v[16:19]
	global_load_lds_dwordx4 v251, s[100:101]
	v_mfma_f32_16x16x32_bf16 v[0:3], v[204:207], v[246:249], v[0:3]
	ds_read_b128 v[204:207], v255 offset:38912
	s_branch .LBB0_1614
.Lgx_1614:
	v_mfma_f32_16x16x32_bf16 v[28:31], v[150:153], v[242:245], v[28:31]
	v_mfma_f32_16x16x32_bf16 v[12:15], v[150:153], v[246:249], v[12:15]
	v_mfma_f32_16x16x32_bf16 v[24:27], v[196:199], v[242:245], v[24:27]
	v_mfma_f32_16x16x32_bf16 v[8:11], v[196:199], v[246:249], v[8:11]
	v_mfma_f32_16x16x32_bf16 v[20:23], v[200:203], v[242:245], v[20:23]
	v_mfma_f32_16x16x32_bf16 v[4:7], v[200:203], v[246:249], v[4:7]
	v_mfma_f32_16x16x32_bf16 v[16:19], v[204:207], v[242:245], v[16:19]
	v_mfma_f32_16x16x32_bf16 v[0:3], v[204:207], v[246:249], v[0:3]
	v_add_u32_e32 v139, s4, v139
	v_add_u32_e32 v141, v139, v155
	ds_read_b128 v[142:145], v141 offset:32768
	ds_read_b128 v[150:153], v141 offset:34816
	ds_read_b128 v[196:199], v141 offset:36864
	ds_read_b128 v[200:203], v141 offset:38912
	v_add_u32_e32 v128, s4, v128
	v_add_u32_e32 v195, v128, v155
	ds_read_b128 v[146:149], v195
	v_add_u32_e32 v139, v139, v156
	v_add_u32_e32 v128, v128, v156
	s_waitcnt lgkmcnt(0)
	v_mfma_f32_16x16x32_bf16 v[124:127], v[142:145], v[146:149], v[124:127]
	s_and_b64 vcc, exec, s[60:61]
	v_mfma_f32_16x16x32_bf16 v[120:123], v[150:153], v[146:149], v[120:123]
	v_mfma_f32_16x16x32_bf16 v[116:119], v[196:199], v[146:149], v[116:119]
	v_mfma_f32_16x16x32_bf16 v[112:115], v[200:203], v[146:149], v[112:115]
	ds_read_b128 v[146:149], v195 offset:2048
	s_waitcnt lgkmcnt(0)
	v_mfma_f32_16x16x32_bf16 v[108:111], v[142:145], v[146:149], v[108:111]
	v_mfma_f32_16x16x32_bf16 v[104:107], v[150:153], v[146:149], v[104:107]
	v_mfma_f32_16x16x32_bf16 v[100:103], v[196:199], v[146:149], v[100:103]
	v_mfma_f32_16x16x32_bf16 v[96:99], v[200:203], v[146:149], v[96:99]
	ds_read_b128 v[146:149], v195 offset:4096
	s_waitcnt lgkmcnt(0)
	v_mfma_f32_16x16x32_bf16 v[92:95], v[142:145], v[146:149], v[92:95]
	v_mfma_f32_16x16x32_bf16 v[88:91], v[150:153], v[146:149], v[88:91]
	v_mfma_f32_16x16x32_bf16 v[84:87], v[196:199], v[146:149], v[84:87]
	v_mfma_f32_16x16x32_bf16 v[80:83], v[200:203], v[146:149], v[80:83]
	ds_read_b128 v[146:149], v195 offset:6144
	s_waitcnt lgkmcnt(0)
	v_mfma_f32_16x16x32_bf16 v[76:79], v[142:145], v[146:149], v[76:79]
	v_mfma_f32_16x16x32_bf16 v[72:75], v[150:153], v[146:149], v[72:75]
	v_mfma_f32_16x16x32_bf16 v[68:71], v[196:199], v[146:149], v[68:71]
	v_mfma_f32_16x16x32_bf16 v[64:67], v[200:203], v[146:149], v[64:67]
	ds_read_b128 v[146:149], v195 offset:8192
	s_waitcnt lgkmcnt(0)
	v_mfma_f32_16x16x32_bf16 v[60:63], v[142:145], v[146:149], v[60:63]
	v_mfma_f32_16x16x32_bf16 v[56:59], v[150:153], v[146:149], v[56:59]
	v_mfma_f32_16x16x32_bf16 v[52:55], v[196:199], v[146:149], v[52:55]
	v_mfma_f32_16x16x32_bf16 v[48:51], v[200:203], v[146:149], v[48:51]
	ds_read_b128 v[146:149], v195 offset:10240
	s_waitcnt lgkmcnt(0)
	v_mfma_f32_16x16x32_bf16 v[44:47], v[142:145], v[146:149], v[44:47]
	v_mfma_f32_16x16x32_bf16 v[40:43], v[150:153], v[146:149], v[40:43]
	v_mfma_f32_16x16x32_bf16 v[36:39], v[196:199], v[146:149], v[36:39]
	v_mfma_f32_16x16x32_bf16 v[32:35], v[200:203], v[146:149], v[32:35]
	ds_read_b128 v[146:149], v195 offset:12288
	s_waitcnt lgkmcnt(0)
	v_mfma_f32_16x16x32_bf16 v[28:31], v[142:145], v[146:149], v[28:31]
	v_mfma_f32_16x16x32_bf16 v[24:27], v[150:153], v[146:149], v[24:27]
	v_mfma_f32_16x16x32_bf16 v[20:23], v[196:199], v[146:149], v[20:23]
	v_mfma_f32_16x16x32_bf16 v[16:19], v[200:203], v[146:149], v[16:19]
	ds_read_b128 v[146:149], v195 offset:14336
	s_waitcnt lgkmcnt(0)
	v_mfma_f32_16x16x32_bf16 v[12:15], v[142:145], v[146:149], v[12:15]
	ds_read_b128 v[142:145], v139 offset:32768
	v_mfma_f32_16x16x32_bf16 v[8:11], v[150:153], v[146:149], v[8:11]
	ds_read_b128 v[150:153], v139 offset:34816
	v_mfma_f32_16x16x32_bf16 v[4:7], v[196:199], v[146:149], v[4:7]
	ds_read_b128 v[196:199], v139 offset:36864
	v_mfma_f32_16x16x32_bf16 v[0:3], v[200:203], v[146:149], v[0:3]
	ds_read_b128 v[200:203], v139 offset:38912
	ds_read_b128 v[146:149], v128
	s_waitcnt lgkmcnt(0)
	v_mfma_f32_16x16x32_bf16 v[124:127], v[142:145], v[146:149], v[124:127]
	v_mfma_f32_16x16x32_bf16 v[120:123], v[150:153], v[146:149], v[120:123]
	v_mfma_f32_16x16x32_bf16 v[116:119], v[196:199], v[146:149], v[116:119]
	v_mfma_f32_16x16x32_bf16 v[112:115], v[200:203], v[146:149], v[112:115]
	ds_read_b128 v[146:149], v128 offset:2048
	s_waitcnt lgkmcnt(0)
	v_mfma_f32_16x16x32_bf16 v[108:111], v[142:145], v[146:149], v[108:111]
	v_mfma_f32_16x16x32_bf16 v[104:107], v[150:153], v[146:149], v[104:107]
	v_mfma_f32_16x16x32_bf16 v[100:103], v[196:199], v[146:149], v[100:103]
	v_mfma_f32_16x16x32_bf16 v[96:99], v[200:203], v[146:149], v[96:99]
	ds_read_b128 v[146:149], v128 offset:4096
	s_waitcnt lgkmcnt(0)
	v_mfma_f32_16x16x32_bf16 v[92:95], v[142:145], v[146:149], v[92:95]
	v_mfma_f32_16x16x32_bf16 v[88:91], v[150:153], v[146:149], v[88:91]
	v_mfma_f32_16x16x32_bf16 v[84:87], v[196:199], v[146:149], v[84:87]
	v_mfma_f32_16x16x32_bf16 v[80:83], v[200:203], v[146:149], v[80:83]
	ds_read_b128 v[146:149], v128 offset:6144
	s_waitcnt lgkmcnt(0)
	v_mfma_f32_16x16x32_bf16 v[76:79], v[142:145], v[146:149], v[76:79]
	v_mfma_f32_16x16x32_bf16 v[72:75], v[150:153], v[146:149], v[72:75]
	v_mfma_f32_16x16x32_bf16 v[68:71], v[196:199], v[146:149], v[68:71]
	v_mfma_f32_16x16x32_bf16 v[64:67], v[200:203], v[146:149], v[64:67]
	ds_read_b128 v[146:149], v128 offset:8192
	s_waitcnt lgkmcnt(0)
	v_mfma_f32_16x16x32_bf16 v[60:63], v[142:145], v[146:149], v[60:63]
	v_mfma_f32_16x16x32_bf16 v[56:59], v[150:153], v[146:149], v[56:59]
	v_mfma_f32_16x16x32_bf16 v[52:55], v[196:199], v[146:149], v[52:55]
	v_mfma_f32_16x16x32_bf16 v[48:51], v[200:203], v[146:149], v[48:51]
	ds_read_b128 v[146:149], v128 offset:10240
	s_waitcnt lgkmcnt(0)
	v_mfma_f32_16x16x32_bf16 v[44:47], v[142:145], v[146:149], v[44:47]
	v_mfma_f32_16x16x32_bf16 v[40:43], v[150:153], v[146:149], v[40:43]
	v_mfma_f32_16x16x32_bf16 v[36:39], v[196:199], v[146:149], v[36:39]
	v_mfma_f32_16x16x32_bf16 v[32:35], v[200:203], v[146:149], v[32:35]
	ds_read_b128 v[146:149], v128 offset:12288
	s_waitcnt lgkmcnt(0)
	v_mfma_f32_16x16x32_bf16 v[28:31], v[142:145], v[146:149], v[28:31]
	v_mfma_f32_16x16x32_bf16 v[24:27], v[150:153], v[146:149], v[24:27]
	v_mfma_f32_16x16x32_bf16 v[20:23], v[196:199], v[146:149], v[20:23]
	v_mfma_f32_16x16x32_bf16 v[16:19], v[200:203], v[146:149], v[16:19]
	ds_read_b128 v[146:149], v128 offset:14336
	s_waitcnt vmcnt(0)
	s_waitcnt lgkmcnt(0)
	v_mfma_f32_16x16x32_bf16 v[12:15], v[142:145], v[146:149], v[12:15]
	s_barrier
	v_mfma_f32_16x16x32_bf16 v[8:11], v[150:153], v[146:149], v[8:11]
	v_mfma_f32_16x16x32_bf16 v[4:7], v[196:199], v[146:149], v[4:7]
	v_mfma_f32_16x16x32_bf16 v[0:3], v[200:203], v[146:149], v[0:3]
	s_cbranch_vccz .LBB0_1617
	s_lshl_b64 s[0:1], s[0:1], 1
	s_add_u32 s2, s62, s0
	s_addc_u32 s3, s63, s1
	s_add_u32 s0, s64, s0
	s_addc_u32 s1, s65, s1
	s_add_i32 s4, s6, 0
	v_mov_b32_e32 v139, v129
	s_mov_b32 m0, s4
	v_mov_b32_e32 v141, v129
	v_lshl_add_u64 v[142:143], s[2:3], 0, v[138:139]
	global_load_lds_dwordx4 v138, s[2:3]
	s_add_i32 m0, s4, 0x8000
	v_lshl_add_u64 v[146:147], s[2:3], 0, v[140:141]
	s_mov_b64 s[4:5], 0x4000
	s_add_i32 s2, s9, 0
	global_load_lds_dwordx4 v138, s[0:1]
	v_lshl_add_u64 v[148:149], v[146:147], 0, s[4:5]
	s_mov_b32 m0, s2
	v_lshl_add_u64 v[144:145], s[0:1], 0, v[138:139]
	global_load_lds_dwordx4 v[148:149], off
	v_lshl_add_u64 v[148:149], s[0:1], 0, v[140:141]
	v_lshl_add_u64 v[150:151], v[148:149], 0, s[4:5]
	s_add_i32 m0, s2, 0x8000
	s_mov_b64 s[2:3], 0x8000
	s_add_i32 s0, s8, 0
	global_load_lds_dwordx4 v[150:151], off
	v_lshl_add_u64 v[142:143], v[142:143], 0, s[2:3]
	s_mov_b32 m0, s0
	s_nop 0
	global_load_lds_dwordx4 v[142:143], off
	v_lshl_add_u64 v[142:143], v[144:145], 0, s[2:3]
	s_add_i32 m0, s0, 0x8000
	s_mov_b64 s[2:3], 0xc000
	s_add_i32 s0, s7, 0
	global_load_lds_dwordx4 v[142:143], off
	v_lshl_add_u64 v[142:143], v[146:147], 0, s[2:3]
	s_mov_b32 m0, s0
	s_nop 0
	global_load_lds_dwordx4 v[142:143], off
	v_lshl_add_u64 v[142:143], v[148:149], 0, s[2:3]
	s_add_i32 m0, s0, 0x8000
	s_nop 0
	global_load_lds_dwordx4 v[142:143], off

.LBB0_2070:
	s_lshr_b32 s4, s3, 1
	s_and_b32 s4, s4, 0x1ffff80
	v_or_b32_e32 v0, s4, v154
	s_and_b32 s3, s3, 0xc0
	v_lshlrev_b32_e32 v139, 7, v0
	v_or_b32_e32 v0, s3, v154
	s_mov_b32 s3, s15
	s_lshl_b64 s[2:3], s[2:3], 16
	s_add_u32 s4, s2, s74
	s_addc_u32 s5, s3, s75
	s_waitcnt vmcnt(0)
	v_lshlrev_b32_e32 v128, 7, v0
	v_lshl_add_u64 v[0:1], s[66:67], 0, v[130:131]
	s_add_u32 s2, s2, s76
	v_lshl_add_u64 v[142:143], v[0:1], 0, s[4:5]
	s_addc_u32 s3, s3, s77
	v_lshl_add_u64 v[0:1], s[66:67], 0, v[134:135]
	v_mov_b32_e32 v72, 0
	v_lshl_add_u64 v[144:145], v[132:133], 0, s[2:3]
	v_lshl_add_u64 v[146:147], v[0:1], 0, s[4:5]
	v_lshl_add_u64 v[148:149], v[136:137], 0, s[2:3]
	s_mov_b32 s4, 0
	s_mov_b64 s[2:3], 0
	v_mov_b32_e32 v73, v72
	v_mov_b32_e32 v74, v72
	v_mov_b32_e32 v75, v72
	v_mov_b32_e32 v88, v72
	v_mov_b32_e32 v89, v72
	v_mov_b32_e32 v90, v72
	v_mov_b32_e32 v91, v72
	v_mov_b32_e32 v0, v72
	v_mov_b32_e32 v1, v72
	v_mov_b32_e32 v2, v72
	v_mov_b32_e32 v3, v72
	v_mov_b32_e32 v4, v72
	v_mov_b32_e32 v5, v72
	v_mov_b32_e32 v6, v72
	v_mov_b32_e32 v7, v72
	v_mov_b32_e32 v8, v72
	v_mov_b32_e32 v9, v72
	v_mov_b32_e32 v10, v72
	v_mov_b32_e32 v11, v72
	v_mov_b32_e32 v12, v72
	v_mov_b32_e32 v13, v72
	v_mov_b32_e32 v14, v72
	v_mov_b32_e32 v15, v72
	v_mov_b32_e32 v16, v72
	v_mov_b32_e32 v17, v72
	v_mov_b32_e32 v18, v72
	v_mov_b32_e32 v19, v72
	v_mov_b32_e32 v20, v72
	v_mov_b32_e32 v21, v72
	v_mov_b32_e32 v22, v72
	v_mov_b32_e32 v23, v72
	v_mov_b32_e32 v24, v72
	v_mov_b32_e32 v25, v72
	v_mov_b32_e32 v26, v72
	v_mov_b32_e32 v27, v72
	v_mov_b32_e32 v28, v72
	v_mov_b32_e32 v29, v72
	v_mov_b32_e32 v30, v72
	v_mov_b32_e32 v31, v72
	v_mov_b32_e32 v32, v72
	v_mov_b32_e32 v33, v72
	v_mov_b32_e32 v34, v72
	v_mov_b32_e32 v35, v72
	v_mov_b32_e32 v36, v72
	v_mov_b32_e32 v37, v72
	v_mov_b32_e32 v38, v72
	v_mov_b32_e32 v39, v72
	v_mov_b32_e32 v40, v72
	v_mov_b32_e32 v41, v72
	v_mov_b32_e32 v42, v72
	v_mov_b32_e32 v43, v72
	v_mov_b32_e32 v44, v72
	v_mov_b32_e32 v45, v72
	v_mov_b32_e32 v46, v72
	v_mov_b32_e32 v47, v72
	v_mov_b32_e32 v48, v72
	v_mov_b32_e32 v49, v72
	v_mov_b32_e32 v50, v72
	v_mov_b32_e32 v51, v72
	v_mov_b32_e32 v52, v72
	v_mov_b32_e32 v53, v72
	v_mov_b32_e32 v54, v72
	v_mov_b32_e32 v55, v72
	v_mov_b32_e32 v56, v72
	v_mov_b32_e32 v57, v72
	v_mov_b32_e32 v58, v72
	v_mov_b32_e32 v59, v72
	v_mov_b32_e32 v60, v72
	v_mov_b32_e32 v61, v72
	v_mov_b32_e32 v62, v72
	v_mov_b32_e32 v63, v72
	v_mov_b32_e32 v64, v72
	v_mov_b32_e32 v65, v72
	v_mov_b32_e32 v66, v72
	v_mov_b32_e32 v67, v72
	v_mov_b32_e32 v68, v72
	v_mov_b32_e32 v69, v72
	v_mov_b32_e32 v70, v72
	v_mov_b32_e32 v71, v72
	v_mov_b32_e32 v76, v72
	v_mov_b32_e32 v77, v72
	v_mov_b32_e32 v78, v72
	v_mov_b32_e32 v79, v72
	v_mov_b32_e32 v80, v72
	v_mov_b32_e32 v81, v72
	v_mov_b32_e32 v82, v72
	v_mov_b32_e32 v83, v72
	v_mov_b32_e32 v84, v72
	v_mov_b32_e32 v85, v72
	v_mov_b32_e32 v86, v72
	v_mov_b32_e32 v87, v72
	v_mov_b32_e32 v92, v72
	v_mov_b32_e32 v93, v72
	v_mov_b32_e32 v94, v72
	v_mov_b32_e32 v95, v72
	v_mov_b32_e32 v96, v72
	v_mov_b32_e32 v97, v72
	v_mov_b32_e32 v98, v72
	v_mov_b32_e32 v99, v72
	v_mov_b32_e32 v100, v72
	v_mov_b32_e32 v101, v72
	v_mov_b32_e32 v102, v72
	v_mov_b32_e32 v103, v72
	v_mov_b32_e32 v104, v72
	v_mov_b32_e32 v105, v72
	v_mov_b32_e32 v106, v72
	v_mov_b32_e32 v107, v72
	v_mov_b32_e32 v108, v72
	v_mov_b32_e32 v109, v72
	v_mov_b32_e32 v110, v72
	v_mov_b32_e32 v111, v72
	v_mov_b32_e32 v112, v72
	v_mov_b32_e32 v113, v72
	v_mov_b32_e32 v114, v72
	v_mov_b32_e32 v115, v72
	v_mov_b32_e32 v116, v72
	v_mov_b32_e32 v117, v72
	v_mov_b32_e32 v118, v72
	v_mov_b32_e32 v119, v72
	v_mov_b32_e32 v120, v72
	v_mov_b32_e32 v121, v72
	v_mov_b32_e32 v122, v72
	v_mov_b32_e32 v123, v72
	v_mov_b32_e32 v124, v72
	v_mov_b32_e32 v125, v72
	v_mov_b32_e32 v126, v72
	v_mov_b32_e32 v127, v72
	s_waitcnt vmcnt(0) lgkmcnt(0)
	s_barrier
	v_bfe_u32 v250, v178, 3, 3
	v_and_b32_e32 v251, 7, v178
	v_lshrrev_b32_e32 v252, 1, v250
	v_xor_b32_e32 v251, v251, v252
	v_lshlrev_b32_e32 v251, 4, v251
	v_lshl_or_b32 v250, v250, 11, v251
	v_xor_b32_e32 v251, 64, v250
	v_add_u32_e32 v251, 0x4000, v251
	v_add_u32_e32 v252, 0x8000, v250
	v_add_u32_e32 v253, 0x8000, v251
	v_lshl_add_u64 v[242:243], v[142:143], 0, s[2:3]
	v_lshl_add_u64 v[242:243], v[242:243], 0, s[38:39]
	v_lshl_add_u64 v[244:245], v[144:145], 0, s[2:3]
	v_lshl_add_u64 v[244:245], v[244:245], 0, s[40:41]
	v_add_u32_e32 v254, v139, v155
	v_add_u32_e32 v255, v128, v155
	v_readfirstlane_b32 s98, v242
	v_readfirstlane_b32 s99, v243
	v_readfirstlane_b32 s100, v244
	v_readfirstlane_b32 s101, v245
	ds_read_b128 v[150:153], v254
	ds_read_b128 v[204:207], v254 offset:2048
	ds_read_b128 v[196:199], v255 offset:32768
	ds_read_b128 v[200:203], v255 offset:34816
	ds_read_b128 v[208:211], v255 offset:36864
	ds_read_b128 v[212:215], v255 offset:38912
	s_nop 4
	s_lshl_b32 m0, s2, 9
	s_and_b32 m0, m0, 0x10000
	s_xor_b32 m0, m0, 0x10000
	s_add_i32 m0, m0, s6
	s_nop 0
	global_load_lds_dwordx4 v250, s[98:99]
	s_add_i32 m0, m0, 0x8000
	s_nop 0
	global_load_lds_dwordx4 v250, s[100:101]
	s_add_i32 m0, m0, 0xffff8400
	s_nop 0
	global_load_lds_dwordx4 v251, s[98:99]
	s_add_i32 m0, m0, 0x8000
	s_nop 0
	global_load_lds_dwordx4 v251, s[100:101]
.LBB0_2071:
	ds_read_b128 v[242:245], v254 offset:4096
	ds_read_b128 v[246:249], v254 offset:6144
	s_lshl_b32 m0, s2, 9
	s_and_b32 m0, m0, 0x10000
	s_xor_b32 m0, m0, 0x10000
	s_add_i32 m0, m0, s6
	s_add_i32 m0, m0, 0x800
	s_waitcnt lgkmcnt(5)
	v_mfma_f32_16x16x32_bf16 v[124:127], v[150:153], v[196:199], v[124:127]
	global_load_lds_dwordx4 v252, s[98:99]
	s_add_i32 m0, m0, 0x8000
	v_mfma_f32_16x16x32_bf16 v[108:111], v[204:207], v[196:199], v[108:111]
	s_waitcnt lgkmcnt(4)
	v_mfma_f32_16x16x32_bf16 v[120:123], v[150:153], v[200:203], v[120:123]
	global_load_lds_dwordx4 v252, s[100:101]
	s_add_i32 m0, m0, 0xffff8400
	v_mfma_f32_16x16x32_bf16 v[104:107], v[204:207], v[200:203], v[104:107]
	s_waitcnt lgkmcnt(3)
	v_mfma_f32_16x16x32_bf16 v[116:119], v[150:153], v[208:211], v[116:119]
	global_load_lds_dwordx4 v253, s[98:99]
	s_add_i32 m0, m0, 0x8000
	v_mfma_f32_16x16x32_bf16 v[100:103], v[204:207], v[208:211], v[100:103]
	s_waitcnt lgkmcnt(2)
	v_mfma_f32_16x16x32_bf16 v[112:115], v[150:153], v[212:215], v[112:115]
	global_load_lds_dwordx4 v253, s[100:101]
	v_mfma_f32_16x16x32_bf16 v[96:99], v[204:207], v[212:215], v[96:99]
	s_add_u32 s98, s98, 0x80
	s_addc_u32 s99, s99, 0
	s_add_u32 s100, s100, 0x80
	s_addc_u32 s101, s101, 0
	ds_read_b128 v[150:153], v254 offset:8192
	ds_read_b128 v[204:207], v254 offset:10240
	s_waitcnt lgkmcnt(2)
	v_mfma_f32_16x16x32_bf16 v[92:95], v[242:245], v[196:199], v[92:95]
	s_add_i32 s5, s4, 0x10000
	v_mfma_f32_16x16x32_bf16 v[68:71], v[246:249], v[196:199], v[68:71]
	s_and_b32 s4, s4, 0x10000
	v_mfma_f32_16x16x32_bf16 v[84:87], v[242:245], v[200:203], v[84:87]
	s_and_b32 s10, s5, 0x10000
	v_mfma_f32_16x16x32_bf16 v[64:67], v[246:249], v[200:203], v[64:67]
	s_add_i32 s4, s4, 0
	v_mfma_f32_16x16x32_bf16 v[80:83], v[242:245], v[208:211], v[80:83]
	s_add_i32 s10, s10, 0
	v_mfma_f32_16x16x32_bf16 v[60:63], v[246:249], v[208:211], v[60:63]
	s_add_i32 s4, s10, s6
	v_mfma_f32_16x16x32_bf16 v[76:79], v[242:245], v[212:215], v[76:79]
	s_add_i32 s11, s10, s9
	v_mfma_f32_16x16x32_bf16 v[56:59], v[246:249], v[212:215], v[56:59]
	s_add_i32 s14, s10, s8
	s_add_i32 s10, s10, s7
	s_add_u32 s2, s2, 0x80
	s_addc_u32 s3, s3, 0
	s_mov_b32 s4, s5
	s_cmpk_eq_i32 s2, 0x780
	ds_read_b128 v[242:245], v254 offset:12288
	ds_read_b128 v[246:249], v254 offset:14336
	s_waitcnt lgkmcnt(2)
	v_mfma_f32_16x16x32_bf16 v[52:55], v[150:153], v[196:199], v[52:55]
	v_mfma_f32_16x16x32_bf16 v[36:39], v[204:207], v[196:199], v[36:39]
	v_mfma_f32_16x16x32_bf16 v[48:51], v[150:153], v[200:203], v[48:51]
	v_mfma_f32_16x16x32_bf16 v[32:35], v[204:207], v[200:203], v[32:35]
	v_mfma_f32_16x16x32_bf16 v[44:47], v[150:153], v[208:211], v[44:47]
	v_mfma_f32_16x16x32_bf16 v[28:31], v[204:207], v[208:211], v[28:31]
	v_mfma_f32_16x16x32_bf16 v[40:43], v[150:153], v[212:215], v[40:43]
	v_mfma_f32_16x16x32_bf16 v[24:27], v[204:207], v[212:215], v[24:27]
	v_xor_b32_e32 v254, 64, v254
	v_xor_b32_e32 v255, 64, v255
	ds_read_b128 v[150:153], v254
	ds_read_b128 v[204:207], v254 offset:2048
	s_waitcnt lgkmcnt(2)
	v_mfma_f32_16x16x32_bf16 v[20:23], v[242:245], v[196:199], v[20:23]
	v_mfma_f32_16x16x32_bf16 v[4:7], v[246:249], v[196:199], v[4:7]
	ds_read_b128 v[196:199], v255 offset:32768
	v_mfma_f32_16x16x32_bf16 v[16:19], v[242:245], v[200:203], v[16:19]
	v_mfma_f32_16x16x32_bf16 v[0:3], v[246:249], v[200:203], v[0:3]
	ds_read_b128 v[200:203], v255 offset:34816
	v_mfma_f32_16x16x32_bf16 v[12:15], v[242:245], v[208:211], v[12:15]
	v_mfma_f32_16x16x32_bf16 v[88:91], v[246:249], v[208:211], v[88:91]
	ds_read_b128 v[208:211], v255 offset:36864
	v_mfma_f32_16x16x32_bf16 v[8:11], v[242:245], v[212:215], v[8:11]
	v_mfma_f32_16x16x32_bf16 v[72:75], v[246:249], v[212:215], v[72:75]
	ds_read_b128 v[212:215], v255 offset:38912
	ds_read_b128 v[242:245], v254 offset:4096
	ds_read_b128 v[246:249], v254 offset:6144
	s_waitcnt lgkmcnt(5)
	v_mfma_f32_16x16x32_bf16 v[124:127], v[150:153], v[196:199], v[124:127]
	v_mfma_f32_16x16x32_bf16 v[108:111], v[204:207], v[196:199], v[108:111]
	s_waitcnt lgkmcnt(4)
	v_mfma_f32_16x16x32_bf16 v[120:123], v[150:153], v[200:203], v[120:123]
	v_mfma_f32_16x16x32_bf16 v[104:107], v[204:207], v[200:203], v[104:107]
	s_waitcnt lgkmcnt(3)
	v_mfma_f32_16x16x32_bf16 v[116:119], v[150:153], v[208:211], v[116:119]
	v_mfma_f32_16x16x32_bf16 v[100:103], v[204:207], v[208:211], v[100:103]
	s_waitcnt lgkmcnt(2)
	v_mfma_f32_16x16x32_bf16 v[112:115], v[150:153], v[212:215], v[112:115]
	v_mfma_f32_16x16x32_bf16 v[96:99], v[204:207], v[212:215], v[96:99]
	ds_read_b128 v[150:153], v254 offset:8192
	ds_read_b128 v[204:207], v254 offset:10240
	s_waitcnt lgkmcnt(2)
	v_mfma_f32_16x16x32_bf16 v[92:95], v[242:245], v[196:199], v[92:95]
	v_mfma_f32_16x16x32_bf16 v[68:71], v[246:249], v[196:199], v[68:71]
	v_mfma_f32_16x16x32_bf16 v[84:87], v[242:245], v[200:203], v[84:87]
	v_mfma_f32_16x16x32_bf16 v[64:67], v[246:249], v[200:203], v[64:67]
	v_mfma_f32_16x16x32_bf16 v[80:83], v[242:245], v[208:211], v[80:83]
	v_mfma_f32_16x16x32_bf16 v[60:63], v[246:249], v[208:211], v[60:63]
	v_mfma_f32_16x16x32_bf16 v[76:79], v[242:245], v[212:215], v[76:79]
	v_mfma_f32_16x16x32_bf16 v[56:59], v[246:249], v[212:215], v[56:59]
	ds_read_b128 v[242:245], v254 offset:12288
	ds_read_b128 v[246:249], v254 offset:14336
	s_waitcnt lgkmcnt(2)
	v_mfma_f32_16x16x32_bf16 v[52:55], v[150:153], v[196:199], v[52:55]
	v_mfma_f32_16x16x32_bf16 v[36:39], v[204:207], v[196:199], v[36:39]
	v_mfma_f32_16x16x32_bf16 v[48:51], v[150:153], v[200:203], v[48:51]
	v_mfma_f32_16x16x32_bf16 v[32:35], v[204:207], v[200:203], v[32:35]
	v_mfma_f32_16x16x32_bf16 v[44:47], v[150:153], v[208:211], v[44:47]
	v_mfma_f32_16x16x32_bf16 v[28:31], v[204:207], v[208:211], v[28:31]
	v_mfma_f32_16x16x32_bf16 v[40:43], v[150:153], v[212:215], v[40:43]
	v_mfma_f32_16x16x32_bf16 v[24:27], v[204:207], v[212:215], v[24:27]
	s_waitcnt vmcnt(0) lgkmcnt(0)
	s_barrier
	s_cmpk_eq_i32 s2, 0x780
	s_cbranch_scc1 .Lgx_2071
	v_xor_b32_e32 v254, 0x10040, v254
	v_xor_b32_e32 v255, 0x10040, v255
	ds_read_b128 v[150:153], v254
	ds_read_b128 v[204:207], v254 offset:2048
	s_lshl_b32 m0, s2, 9
	s_and_b32 m0, m0, 0x10000
	s_xor_b32 m0, m0, 0x10000
	s_add_i32 m0, m0, s6
	v_mfma_f32_16x16x32_bf16 v[20:23], v[242:245], v[196:199], v[20:23]
	global_load_lds_dwordx4 v250, s[98:99]
	s_add_i32 m0, m0, 0x8000
	v_mfma_f32_16x16x32_bf16 v[4:7], v[246:249], v[196:199], v[4:7]
	ds_read_b128 v[196:199], v255 offset:32768
	v_mfma_f32_16x16x32_bf16 v[16:19], v[242:245], v[200:203], v[16:19]
	global_load_lds_dwordx4 v250, s[100:101]
	s_add_i32 m0, m0, 0xffff8400
	v_mfma_f32_16x16x32_bf16 v[0:3], v[246:249], v[200:203], v[0:3]
	ds_read_b128 v[200:203], v255 offset:34816
	v_mfma_f32_16x16x32_bf16 v[12:15], v[242:245], v[208:211], v[12:15]
	global_load_lds_dwordx4 v251, s[98:99]
	s_add_i32 m0, m0, 0x8000
	v_mfma_f32_16x16x32_bf16 v[88:91], v[246:249], v[208:211], v[88:91]
	ds_read_b128 v[208:211], v255 offset:36864
	v_mfma_f32_16x16x32_bf16 v[8:11], v[242:245], v[212:215], v[8:11]
	global_load_lds_dwordx4 v251, s[100:101]
	v_mfma_f32_16x16x32_bf16 v[72:75], v[246:249], v[212:215], v[72:75]
	ds_read_b128 v[212:215], v255 offset:38912
	s_branch .LBB0_2071
.Lgx_2071:
	v_mfma_f32_16x16x32_bf16 v[20:23], v[242:245], v[196:199], v[20:23]
	v_mfma_f32_16x16x32_bf16 v[4:7], v[246:249], v[196:199], v[4:7]
	v_mfma_f32_16x16x32_bf16 v[16:19], v[242:245], v[200:203], v[16:19]
	v_mfma_f32_16x16x32_bf16 v[0:3], v[246:249], v[200:203], v[0:3]
	v_mfma_f32_16x16x32_bf16 v[12:15], v[242:245], v[208:211], v[12:15]
	v_mfma_f32_16x16x32_bf16 v[88:91], v[246:249], v[208:211], v[88:91]
	v_mfma_f32_16x16x32_bf16 v[8:11], v[242:245], v[212:215], v[8:11]
	v_mfma_f32_16x16x32_bf16 v[72:75], v[246:249], v[212:215], v[72:75]
	s_add_i32 s2, 0, 0x10000
	v_add_u32_e32 v139, s2, v139
	v_add_u32_e32 v141, v139, v155
	ds_read_b128 v[142:145], v141
	v_add_u32_e32 v128, s2, v128
	v_add_u32_e32 v195, v128, v155
	ds_read_b128 v[146:149], v195 offset:32768
	ds_read_b128 v[150:153], v195 offset:34816
	ds_read_b128 v[196:199], v141 offset:2048
	ds_read_b128 v[200:203], v195 offset:36864
	ds_read_b128 v[204:207], v195 offset:38912
	s_waitcnt lgkmcnt(2)
	v_mfma_f32_16x16x32_bf16 v[108:111], v[196:199], v[146:149], v[108:111]
	v_add_u32_e32 v139, v139, v156
	v_add_u32_e32 v128, v128, v156
	s_and_b64 vcc, exec, s[60:61]
	v_mfma_f32_16x16x32_bf16 v[124:127], v[142:145], v[146:149], v[124:127]
	v_mfma_f32_16x16x32_bf16 v[120:123], v[142:145], v[150:153], v[120:123]
	s_waitcnt lgkmcnt(1)
	v_mfma_f32_16x16x32_bf16 v[116:119], v[142:145], v[200:203], v[116:119]
	s_waitcnt lgkmcnt(0)
	v_mfma_f32_16x16x32_bf16 v[112:115], v[142:145], v[204:207], v[112:115]
	v_mfma_f32_16x16x32_bf16 v[104:107], v[196:199], v[150:153], v[104:107]
	v_mfma_f32_16x16x32_bf16 v[100:103], v[196:199], v[200:203], v[100:103]
	v_mfma_f32_16x16x32_bf16 v[96:99], v[196:199], v[204:207], v[96:99]
	ds_read_b128 v[142:145], v141 offset:4096
	ds_read_b128 v[196:199], v141 offset:6144
	s_waitcnt lgkmcnt(1)
	v_mfma_f32_16x16x32_bf16 v[92:95], v[142:145], v[146:149], v[92:95]
	v_mfma_f32_16x16x32_bf16 v[84:87], v[142:145], v[150:153], v[84:87]
	v_mfma_f32_16x16x32_bf16 v[80:83], v[142:145], v[200:203], v[80:83]
	v_mfma_f32_16x16x32_bf16 v[76:79], v[142:145], v[204:207], v[76:79]
	s_waitcnt lgkmcnt(0)
	v_mfma_f32_16x16x32_bf16 v[68:71], v[196:199], v[146:149], v[68:71]
	v_mfma_f32_16x16x32_bf16 v[64:67], v[196:199], v[150:153], v[64:67]
	v_mfma_f32_16x16x32_bf16 v[60:63], v[196:199], v[200:203], v[60:63]
	v_mfma_f32_16x16x32_bf16 v[56:59], v[196:199], v[204:207], v[56:59]
	ds_read_b128 v[142:145], v141 offset:8192
	ds_read_b128 v[196:199], v141 offset:10240
	s_waitcnt lgkmcnt(1)
	v_mfma_f32_16x16x32_bf16 v[52:55], v[142:145], v[146:149], v[52:55]
	v_mfma_f32_16x16x32_bf16 v[48:51], v[142:145], v[150:153], v[48:51]
	v_mfma_f32_16x16x32_bf16 v[44:47], v[142:145], v[200:203], v[44:47]
	v_mfma_f32_16x16x32_bf16 v[40:43], v[142:145], v[204:207], v[40:43]
	s_waitcnt lgkmcnt(0)
	v_mfma_f32_16x16x32_bf16 v[36:39], v[196:199], v[146:149], v[36:39]
	v_mfma_f32_16x16x32_bf16 v[32:35], v[196:199], v[150:153], v[32:35]
	v_mfma_f32_16x16x32_bf16 v[28:31], v[196:199], v[200:203], v[28:31]
	v_mfma_f32_16x16x32_bf16 v[24:27], v[196:199], v[204:207], v[24:27]
	ds_read_b128 v[142:145], v141 offset:12288
	ds_read_b128 v[196:199], v141 offset:14336
	s_waitcnt lgkmcnt(1)
	v_mfma_f32_16x16x32_bf16 v[20:23], v[142:145], v[146:149], v[20:23]
	v_mfma_f32_16x16x32_bf16 v[16:19], v[142:145], v[150:153], v[16:19]
	v_mfma_f32_16x16x32_bf16 v[12:15], v[142:145], v[200:203], v[12:15]
	v_mfma_f32_16x16x32_bf16 v[8:11], v[142:145], v[204:207], v[8:11]
	s_waitcnt lgkmcnt(0)
	v_mfma_f32_16x16x32_bf16 v[4:7], v[196:199], v[146:149], v[4:7]
	v_mfma_f32_16x16x32_bf16 v[0:3], v[196:199], v[150:153], v[0:3]
	v_mfma_f32_16x16x32_bf16 v[142:145], v[196:199], v[200:203], v[88:91]
	s_nop 2
	ds_read_b128 v[88:91], v139
	v_mfma_f32_16x16x32_bf16 v[146:149], v[196:199], v[204:207], v[72:75]
	ds_read_b128 v[150:153], v128 offset:32768
	ds_read_b128 v[196:199], v128 offset:34816
	s_nop 0
	ds_read_b128 v[72:75], v139 offset:2048
	ds_read_b128 v[200:203], v128 offset:36864
	ds_read_b128 v[204:207], v128 offset:38912
	s_waitcnt lgkmcnt(2)
	v_mfma_f32_16x16x32_bf16 v[108:111], v[72:75], v[150:153], v[108:111]
	v_mfma_f32_16x16x32_bf16 v[104:107], v[72:75], v[196:199], v[104:107]
	s_waitcnt lgkmcnt(1)
	v_mfma_f32_16x16x32_bf16 v[100:103], v[72:75], v[200:203], v[100:103]
	s_waitcnt lgkmcnt(0)
	v_mfma_f32_16x16x32_bf16 v[96:99], v[72:75], v[204:207], v[96:99]
	ds_read_b128 v[72:75], v139 offset:4096
	ds_read_b128 v[208:211], v139 offset:6144
	v_mfma_f32_16x16x32_bf16 v[124:127], v[88:91], v[150:153], v[124:127]
	v_mfma_f32_16x16x32_bf16 v[120:123], v[88:91], v[196:199], v[120:123]
	v_mfma_f32_16x16x32_bf16 v[116:119], v[88:91], v[200:203], v[116:119]
	v_mfma_f32_16x16x32_bf16 v[112:115], v[88:91], v[204:207], v[112:115]
	s_waitcnt lgkmcnt(1)
	v_mfma_f32_16x16x32_bf16 v[92:95], v[72:75], v[150:153], v[92:95]
	v_mfma_f32_16x16x32_bf16 v[88:91], v[72:75], v[196:199], v[84:87]
	v_mfma_f32_16x16x32_bf16 v[84:87], v[72:75], v[200:203], v[80:83]
	v_mfma_f32_16x16x32_bf16 v[80:83], v[72:75], v[204:207], v[76:79]
	s_waitcnt lgkmcnt(0)
	v_mfma_f32_16x16x32_bf16 v[76:79], v[208:211], v[150:153], v[68:71]
	v_mfma_f32_16x16x32_bf16 v[72:75], v[208:211], v[196:199], v[64:67]
	v_mfma_f32_16x16x32_bf16 v[68:71], v[208:211], v[200:203], v[60:63]
	v_mfma_f32_16x16x32_bf16 v[64:67], v[208:211], v[204:207], v[56:59]
	ds_read_b128 v[208:211], v139 offset:8192
	ds_read_b128 v[212:215], v139 offset:10240
	s_waitcnt lgkmcnt(1)
	v_mfma_f32_16x16x32_bf16 v[60:63], v[208:211], v[150:153], v[52:55]
	v_mfma_f32_16x16x32_bf16 v[56:59], v[208:211], v[196:199], v[48:51]
	v_mfma_f32_16x16x32_bf16 v[52:55], v[208:211], v[200:203], v[44:47]
	v_mfma_f32_16x16x32_bf16 v[48:51], v[208:211], v[204:207], v[40:43]
	s_waitcnt lgkmcnt(0)
	v_mfma_f32_16x16x32_bf16 v[44:47], v[212:215], v[150:153], v[36:39]
	v_mfma_f32_16x16x32_bf16 v[40:43], v[212:215], v[196:199], v[32:35]
	v_mfma_f32_16x16x32_bf16 v[36:39], v[212:215], v[200:203], v[28:31]
	v_mfma_f32_16x16x32_bf16 v[32:35], v[212:215], v[204:207], v[24:27]
	ds_read_b128 v[208:211], v139 offset:12288
	ds_read_b128 v[212:215], v139 offset:14336
	s_waitcnt vmcnt(0)
	s_waitcnt lgkmcnt(0)
	v_mfma_f32_16x16x32_bf16 v[28:31], v[208:211], v[150:153], v[20:23]
	s_barrier
	v_mfma_f32_16x16x32_bf16 v[24:27], v[208:211], v[196:199], v[16:19]
	v_mfma_f32_16x16x32_bf16 v[20:23], v[208:211], v[200:203], v[12:15]
	v_mfma_f32_16x16x32_bf16 v[16:19], v[208:211], v[204:207], v[8:11]
	v_mfma_f32_16x16x32_bf16 v[12:15], v[212:215], v[150:153], v[4:7]
	v_mfma_f32_16x16x32_bf16 v[8:11], v[212:215], v[196:199], v[0:3]
	v_mfma_f32_16x16x32_bf16 v[4:7], v[212:215], v[200:203], v[142:145]
	v_mfma_f32_16x16x32_bf16 v[0:3], v[212:215], v[204:207], v[146:149]
	s_cbranch_vccz .LBB0_2074
	s_lshl_b64 s[0:1], s[0:1], 1
	s_add_u32 s2, s62, s0
	s_addc_u32 s3, s63, s1
	s_add_u32 s0, s64, s0
	s_addc_u32 s1, s65, s1
	s_add_i32 s4, s6, 0
	v_mov_b32_e32 v139, v129
	s_mov_b32 m0, s4
	v_mov_b32_e32 v141, v129
	v_lshl_add_u64 v[142:143], s[2:3], 0, v[138:139]
	global_load_lds_dwordx4 v138, s[2:3]
	s_add_i32 m0, s4, 0x8000
	v_lshl_add_u64 v[146:147], s[2:3], 0, v[140:141]
	s_mov_b64 s[4:5], 0x4000
	s_add_i32 s2, s9, 0
	global_load_lds_dwordx4 v138, s[0:1]
	v_lshl_add_u64 v[148:149], v[146:147], 0, s[4:5]
	s_mov_b32 m0, s2
	v_lshl_add_u64 v[144:145], s[0:1], 0, v[138:139]
	global_load_lds_dwordx4 v[148:149], off
	v_lshl_add_u64 v[148:149], s[0:1], 0, v[140:141]
	v_lshl_add_u64 v[150:151], v[148:149], 0, s[4:5]
	s_add_i32 m0, s2, 0x8000
	s_mov_b64 s[2:3], 0x8000
	s_add_i32 s0, s8, 0
	global_load_lds_dwordx4 v[150:151], off
	v_lshl_add_u64 v[142:143], v[142:143], 0, s[2:3]
	s_mov_b32 m0, s0
	s_nop 0
	global_load_lds_dwordx4 v[142:143], off
	v_lshl_add_u64 v[142:143], v[144:145], 0, s[2:3]
	s_add_i32 m0, s0, 0x8000
	s_mov_b64 s[2:3], 0xc000
	s_add_i32 s0, s7, 0
	global_load_lds_dwordx4 v[142:143], off
	v_lshl_add_u64 v[142:143], v[146:147], 0, s[2:3]
	s_mov_b32 m0, s0
	s_nop 0
	global_load_lds_dwordx4 v[142:143], off
	v_lshl_add_u64 v[142:143], v[148:149], 0, s[2:3]
	s_add_i32 m0, s0, 0x8000
	s_nop 0
	global_load_lds_dwordx4 v[142:143], off

	.amdhsa_kernel _Z8mega_fwd6Params
		.amdhsa_group_segment_fixed_size 0
		.amdhsa_private_segment_fixed_size 0
		.amdhsa_kernarg_size 464
		.amdhsa_user_sgpr_count 2
		.amdhsa_user_sgpr_dispatch_ptr 0
		.amdhsa_user_sgpr_queue_ptr 0
		.amdhsa_user_sgpr_kernarg_segment_ptr 1
		.amdhsa_user_sgpr_dispatch_id 0
		.amdhsa_user_sgpr_kernarg_preload_length 0
		.amdhsa_user_sgpr_kernarg_preload_offset 0
		.amdhsa_user_sgpr_private_segment_size 0
		.amdhsa_uses_dynamic_stack 0
		.amdhsa_enable_private_segment 0
		.amdhsa_system_sgpr_workgroup_id_x 1
		.amdhsa_system_sgpr_workgroup_id_y 0
		.amdhsa_system_sgpr_workgroup_id_z 0
		.amdhsa_system_sgpr_workgroup_info 0
		.amdhsa_system_vgpr_workitem_id 2
		.amdhsa_next_free_vgpr 256
		.amdhsa_next_free_sgpr 102
		.amdhsa_accum_offset 256
		.amdhsa_reserve_vcc 1
		.amdhsa_float_round_mode_32 0
		.amdhsa_float_round_mode_16_64 0
		.amdhsa_float_denorm_mode_32 3
		.amdhsa_float_denorm_mode_16_64 3
		.amdhsa_dx10_clamp 1
		.amdhsa_ieee_mode 1
		.amdhsa_fp16_overflow 0
		.amdhsa_tg_split 0
		.amdhsa_exception_fp_ieee_invalid_op 0
		.amdhsa_exception_fp_denorm_src 0
		.amdhsa_exception_fp_ieee_div_zero 0
		.amdhsa_exception_fp_ieee_overflow 0
		.amdhsa_exception_fp_ieee_underflow 0
		.amdhsa_exception_fp_ieee_inexact 0
		.amdhsa_exception_int_div_zero 0
	.end_amdhsa_kernel

amdhsa.kernels:
  - .agpr_count:     0
    .args:
      - .offset:         0
        .size:           208
        .value_kind:     by_value
      - .offset:         208
        .size:           4
        .value_kind:     hidden_block_count_x
      - .offset:         212
        .size:           4
        .value_kind:     hidden_block_count_y
      - .offset:         216
        .size:           4
        .value_kind:     hidden_block_count_z
      - .offset:         220
        .size:           2
        .value_kind:     hidden_group_size_x
      - .offset:         222
        .size:           2
        .value_kind:     hidden_group_size_y
      - .offset:         224
        .size:           2
        .value_kind:     hidden_group_size_z
      - .offset:         226
        .size:           2
        .value_kind:     hidden_remainder_x
      - .offset:         228
        .size:           2
        .value_kind:     hidden_remainder_y
      - .offset:         230
        .size:           2
        .value_kind:     hidden_remainder_z
      - .offset:         248
        .size:           8
        .value_kind:     hidden_global_offset_x
      - .offset:         256
        .size:           8
        .value_kind:     hidden_global_offset_y
      - .offset:         264
        .size:           8
        .value_kind:     hidden_global_offset_z
      - .offset:         272
        .size:           2
        .value_kind:     hidden_grid_dims
      - .offset:         296
        .size:           8
        .value_kind:     hidden_multigrid_sync_arg
      - .offset:         328
        .size:           4
        .value_kind:     hidden_dynamic_lds_size
    .group_segment_fixed_size: 0
    .kernarg_segment_align: 8
    .kernarg_segment_size: 464
    .language:       OpenCL C
    .language_version:
      - 2
      - 0
    .max_flat_workgroup_size: 512
    .name:           _Z8mega_fwd6Params
    .private_segment_fixed_size: 0
    .sgpr_count:     108
    .sgpr_spill_count: 72
    .symbol:         _Z8mega_fwd6Params.kd
    .uniform_work_group_size: 1
    .uses_dynamic_stack: false
    .vgpr_count:     256
    .vgpr_spill_count: 0
    .wavefront_size: 64
